# K-loop operand loads (P1 and P5) with sc0 (bypass the per-CU L1: each line is read once per CU)
# speedup vs baseline: 1.0061x; 1.0013x over previous
;     ...
;   const int srow = tid >> 3, skc = tid & 7;
;   const u16* Ag = A + (size_t)(m0 + srow) * K + skc * 8;
;   const u16* Bg[4];
; #pragma unroll
;   for (int i = 0; i < 4; ++i) { int n = n0 + srow + 64 * i; n = n < nmax ? n : nmax - 1; Bg[i] = Bt + (size_t)n * K + skc * 8; }
;   const int nk = nk_override ? nk_override : K / 64;
; #pragma unroll
;   for (int i = 0; i < 4; ++i) { ra[i] = *(const u32x4*)(Ag + (size_t)(64 * i) * K); rb[i] = *(const u32x4*)(Bg[i]); }
; #pragma unroll
;   for (int i = 0; i < 4; ++i) { *(u32x4*)(As0 + (srow + 64 * i) * LD + skc * 8) = ra[i]; *(u32x4*)(Bs0 + (srow + 64 * i) * LD + skc * 8) = rb[i]; }
;   if (nk > 1) {
; #pragma unroll
;     for (int i = 0; i < 4; ++i) { ra[i] = *(const u32x4*)(Ag + (size_t)(64 * i) * K + 64); rb[i] = *(const u32x4*)(Bg[i] + 64); }
;   }
;   for (int kt = 0; kt < nk; ++kt) {
;     __syncthreads();
;     if (kt + 1 < nk) {
;       u16* aw = As0 + ((kt + 1) & 1) * 256 * LD;
;       u16* bw = Bs0 + ((kt + 1) & 1) * 256 * LD;
; #pragma unroll
;       for (int i = 0; i < 4; ++i) { *(u32x4*)(aw + (srow + 64 * i) * LD + skc * 8) = ra[i]; *(u32x4*)(bw + (srow + 64 * i) * LD + skc * 8) = rb[i]; }
;     }
;     if (kt + 2 < nk) {
; #pragma unroll
;       for (int i = 0; i < 4; ++i) { ra[i] = *(const u32x4*)(Ag + (size_t)(64 * i) * K + (kt + 2) * 64); rb[i] = *(const u32x4*)(Bg[i] + (kt + 2) * 64); }
.LBB0_107:
	s_lshl_b32 s34, s34, 1
	s_add_i32 s34, s34, s40
	s_and_b32 s30, s35, 1
	s_or_b32 s30, s34, s30
	s_lshl_b32 s59, s62, 8
	v_ashrrev_i32_e32 v42, 3, v227
	s_lshl_b32 s35, s30, 8
	s_waitcnt vmcnt(3)
	v_add_u32_e32 v10, s59, v42
	s_waitcnt vmcnt(0)
	v_add_u32_e32 v4, s35, v42
	v_lshlrev_b32_e32 v2, 4, v227
	v_min_i32_e32 v8, 0x107f, v10
	v_ashrrev_i32_e32 v5, 31, v4
	v_and_b32_e32 v2, 0x70, v2
	v_ashrrev_i32_e32 v9, 31, v8
	v_lshlrev_b64 v[4:5], 11, v[4:5]
	s_waitcnt lgkmcnt(0)
	v_lshl_add_u64 v[6:7], s[18:19], 0, v[2:3]
	v_lshlrev_b64 v[8:9], 11, v[8:9]
	v_lshl_add_u64 v[228:229], v[6:7], 0, v[8:9]
	v_min_i32_e32 v8, 0x103f, v10
	v_lshl_add_u64 v[4:5], s[16:17], 0, v[4:5]
	v_ashrrev_i32_e32 v9, 31, v8
	v_lshl_add_u64 v[230:231], v[4:5], 0, v[2:3]
	v_lshlrev_b64 v[8:9], 11, v[8:9]
	v_add_co_u32_e32 v232, vcc, s42, v230
	v_lshl_add_u64 v[36:37], v[6:7], 0, v[8:9]
	v_min_i32_e32 v8, 0xfff, v10
	v_addc_co_u32_e32 v233, vcc, 0, v231, vcc
	v_ashrrev_i32_e32 v9, 31, v8
	v_add_co_u32_e32 v16, vcc, s42, v36
	v_lshlrev_b64 v[8:9], 11, v[8:9]
	s_nop 0
	v_addc_co_u32_e32 v17, vcc, 0, v37, vcc
	v_lshl_add_u64 v[38:39], v[6:7], 0, v[8:9]
	v_min_i32_e32 v8, 0xfbf, v10
	v_add_co_u32_e32 v68, vcc, s43, v230
	v_ashrrev_i32_e32 v9, 31, v8
	s_nop 0
	v_addc_co_u32_e32 v69, vcc, 0, v231, vcc
	v_lshlrev_b64 v[8:9], 11, v[8:9]
	v_add_co_u32_e32 v24, vcc, s43, v38
	v_lshl_add_u64 v[40:41], v[6:7], 0, v[8:9]
	global_load_dwordx4 v[4:7], v[230:231], off
	global_load_dwordx4 v[8:11], v[228:229], off
	v_addc_co_u32_e32 v25, vcc, 0, v39, vcc
	global_load_dwordx4 v[16:19], v[16:17], off
	v_add_co_u32_e32 v28, vcc, s44, v40
	global_load_dwordx4 v[24:27], v[24:25], off
	s_nop 0
	v_addc_co_u32_e32 v29, vcc, 0, v41, vcc
	global_load_dwordx4 v[28:31], v[28:29], off
	v_add_co_u32_e32 v70, vcc, s44, v230
	global_load_dwordx4 v[12:15], v[232:233], off
	global_load_dwordx4 v[20:23], v[68:69], off
	v_addc_co_u32_e32 v71, vcc, 0, v231, vcc
	global_load_dwordx4 v[32:35], v[70:71], off
	v_mul_lo_u32 v42, v42, s46
	v_add3_u32 v251, s45, v2, v42
	v_add3_u32 v250, 0, v2, v42
	v_lshl_add_u64 v[238:239], v[36:37], 0, s[24:25]
	v_lshl_add_u64 v[234:235], v[38:39], 0, s[26:27]
	v_lshl_add_u64 v[236:237], v[40:41], 0, s[28:29]
	global_load_dwordx4 v[36:39], v[228:229], off offset:128
	global_load_dwordx4 v[40:43], v[238:239], off offset:128
	global_load_dwordx4 v[44:47], v[234:235], off offset:128
	global_load_dwordx4 v[48:51], v[236:237], off offset:128
	global_load_dwordx4 v[52:55], v[230:231], off offset:128
	global_load_dwordx4 v[56:59], v[232:233], off offset:128
	global_load_dwordx4 v[60:63], v[68:69], off offset:128
	global_load_dwordx4 v[64:67], v[70:71], off offset:128
	s_ashr_i32 s36, s60, 6
	s_bfe_u32 s37, s36, 0x10001
	s_ashr_i32 s38, s60, 8
	s_and_b64 s[30:31], s[6:7], exec
	s_cselect_b32 s37, s37, s38
	s_xor_b64 s[6:7], s[6:7], -1
	s_cmp_lt_i32 s36, 4
	v_and_b32_e32 v225, 31, v227
	s_cselect_b64 s[30:31], -1, 0
	s_lshl_b32 s36, s37, 7
	v_bfe_u32 v247, v227, 5, 1
	v_or_b32_e32 v2, s36, v225
	v_mul_lo_u32 v2, v2, s46
	v_lshlrev_b32_e32 v226, 4, v247
	s_lshl_b32 s61, s20, 6
	v_add3_u32 v248, 0, v2, v226
	v_or_b32_e32 v2, s61, v225
	v_mul_lo_u32 v2, v2, s46
	s_or_b64 s[30:31], s[6:7], s[30:31]
	v_add3_u32 v249, s45, v2, v226
	s_waitcnt vmcnt(14)
	ds_write_b128 v251, v[8:11]
	s_waitcnt vmcnt(13)
	ds_write_b128 v251, v[16:19] offset:9216
	s_waitcnt vmcnt(12)
	ds_write_b128 v251, v[24:27] offset:18432
	s_waitcnt vmcnt(11)
	ds_write_b128 v251, v[28:31] offset:27648
	ds_write_b128 v250, v[4:7]
	s_waitcnt vmcnt(10)
	ds_write_b128 v250, v[12:15] offset:9216
	s_waitcnt vmcnt(9)
	ds_write_b128 v250, v[20:23] offset:18432
	s_waitcnt vmcnt(8)
	ds_write_b128 v250, v[32:35] offset:27648
	s_waitcnt lgkmcnt(0)
	s_barrier
	s_andn2_b64 vcc, exec, s[30:31]
	s_cbranch_vccnz .Lp1_stage_only
	v_lshrrev_b32_e32 v227, 3, v223
	v_lshlrev_b32_e32 v227, 11, v227
	v_lshlrev_b32_e32 v2, 4, v223
	v_and_b32_e32 v2, 0x70, v2
	v_or_b32_e32 v227, v227, v2
	s_lshl_b32 s6, s35, 11
	s_add_u32 s74, s16, s6
	s_addc_u32 s75, s17, 0
	s_add_u32 s76, s74, 0x20000
	s_addc_u32 s77, s75, 0
	s_add_u32 s78, s74, 0x40000
	s_addc_u32 s79, s75, 0
	s_add_u32 s80, s74, 0x60000
	s_addc_u32 s81, s75, 0
	s_lshl_b32 s6, s59, 11
	s_add_u32 s82, s18, s6
	s_addc_u32 s83, s19, 0
	s_add_u32 s84, s82, 0x20000
	s_addc_u32 s85, s83, 0
	s_add_u32 s86, s82, 0x40000
	s_addc_u32 s87, s83, 0
	s_add_u32 s92, s82, 0x60000
	s_addc_u32 s93, s83, 0
	global_load_dwordx4 v[146:149], v227, s[74:75] offset:256 sc0
	global_load_dwordx4 v[178:181], v227, s[82:83] offset:256 sc0
	global_load_dwordx4 v[150:153], v227, s[76:77] offset:256 sc0
	global_load_dwordx4 v[182:185], v227, s[84:85] offset:256 sc0
	global_load_dwordx4 v[154:157], v227, s[78:79] offset:256 sc0
	global_load_dwordx4 v[186:189], v227, s[86:87] offset:256 sc0
	global_load_dwordx4 v[158:161], v227, s[80:81] offset:256 sc0
	global_load_dwordx4 v[190:193], v227, s[92:93] offset:256 sc0
	global_load_dwordx4 v[162:165], v227, s[74:75] offset:384 sc0
	global_load_dwordx4 v[194:197], v227, s[82:83] offset:384 sc0
	global_load_dwordx4 v[166:169], v227, s[76:77] offset:384 sc0
	global_load_dwordx4 v[198:201], v227, s[84:85] offset:384 sc0
	global_load_dwordx4 v[170:173], v227, s[78:79] offset:384 sc0
	global_load_dwordx4 v[202:205], v227, s[86:87] offset:384 sc0
	global_load_dwordx4 v[174:177], v227, s[80:81] offset:384 sc0
	global_load_dwordx4 v[206:209], v227, s[92:93] offset:384 sc0
	s_waitcnt vmcnt(23)
	ds_write_b128 v251, v[36:39] offset:36864
	s_waitcnt vmcnt(22)
	ds_write_b128 v251, v[40:43] offset:46080
	s_waitcnt vmcnt(21)
	ds_write_b128 v251, v[44:47] offset:55296
	s_waitcnt vmcnt(20)
;     ...
;   for (int kt = 0; kt < nk; ++kt) {
;     __syncthreads();
;     if (kt + 1 < nk) {
;       u16* aw = As0 + ((kt + 1) & 1) * 256 * LD;
;       u16* bw = Bs0 + ((kt + 1) & 1) * 256 * LD;
; #pragma unroll
;       for (int i = 0; i < 4; ++i) { *(u32x4*)(aw + (srow + 64 * i) * LD + skc * 8) = ra[i]; *(u32x4*)(bw + (srow + 64 * i) * LD + skc * 8) = rb[i]; }
;     }
;     if (kt + 2 < nk) {
; #pragma unroll
;       for (int i = 0; i < 4; ++i) { ra[i] = *(const u32x4*)(Ag + (size_t)(64 * i) * K + (kt + 2) * 64); rb[i] = *(const u32x4*)(Bg[i] + (kt + 2) * 64); }
;     }
;     __builtin_amdgcn_sched_barrier(0);
;     const u16* as = As0 + (kt & 1) * 256 * LD + (wr * 128 + l31) * LD + h * 8;
;     const u16* bs = Bs0 + (kt & 1) * 256 * LD + (wc * 64 + l31) * LD + h * 8;
;     if (domma)
; #pragma unroll
;     for (int ks = 0; ks < 4; ++ks) {
;       bf16x8 wf[2], xf[4];
; #pragma unroll
;       for (int ct = 0; ct < 2; ++ct) wf[ct] = *(const bf16x8*)(bs + ct * 32 * LD + ks * 16);
; #pragma unroll
;       for (int tt = 0; tt < 4; ++tt) xf[tt] = *(const bf16x8*)(as + tt * 32 * LD + ks * 16);
; #pragma unroll
;       for (int ct = 0; ct < 2; ++ct)
; #pragma unroll
;         for (int tt = 0; tt < 4; ++tt) acc[ct][tt] = __builtin_amdgcn_mfma_f32_32x32x16_bf16(wf[ct], xf[tt], acc[ct][tt], 0, 0, 0);
;     }
	ds_write_b128 v251, v[48:51] offset:64512
	s_waitcnt vmcnt(19)
	ds_write_b128 v250, v[52:55] offset:36864
	s_waitcnt vmcnt(18)
	ds_write_b128 v250, v[56:59] offset:46080
	s_waitcnt vmcnt(17)
	ds_write_b128 v250, v[60:63] offset:55296
	s_waitcnt vmcnt(16)
	ds_write_b128 v250, v[64:67] offset:64512
	ds_read_b128 v[210:213], v249
	ds_read_b128 v[236:239], v248
	ds_read_b128 v[214:217], v249 offset:4608
	ds_read_b128 v[2:5], v248 offset:4608
	ds_read_b128 v[6:9], v248 offset:9216
	ds_read_b128 v[10:13], v248 offset:13824
	s_waitcnt lgkmcnt(4)
	v_mfma_f32_32x32x16_bf16 v[114:129], v[210:213], v[236:239], 0
	ds_read_b128 v[228:231], v249 offset:32
	s_waitcnt lgkmcnt(4)
	v_mfma_f32_32x32x16_bf16 v[130:145], v[214:217], v[236:239], 0
	ds_read_b128 v[14:17], v248 offset:32
	s_waitcnt lgkmcnt(4)
	v_mfma_f32_32x32x16_bf16 v[82:97], v[210:213], v[2:5], 0
	ds_read_b128 v[232:235], v249 offset:4640
	v_mfma_f32_32x32x16_bf16 v[98:113], v[214:217], v[2:5], 0
	ds_read_b128 v[236:239], v248 offset:4640
	s_waitcnt lgkmcnt(5)
	v_mfma_f32_32x32x16_bf16 v[50:65], v[210:213], v[6:9], 0
	ds_read_b128 v[2:5], v248 offset:9248
	v_mfma_f32_32x32x16_bf16 v[66:81], v[214:217], v[6:9], 0
	s_waitcnt lgkmcnt(5)
	v_mfma_f32_32x32x16_bf16 v[18:33], v[210:213], v[10:13], 0
	ds_read_b128 v[6:9], v248 offset:13856
	v_mfma_f32_32x32x16_bf16 v[34:49], v[214:217], v[10:13], 0
	s_waitcnt lgkmcnt(4)
	v_mfma_f32_32x32x16_bf16 v[114:129], v[228:231], v[14:17], v[114:129]
	ds_read_b128 v[210:213], v249 offset:64
	s_waitcnt lgkmcnt(4)
	v_mfma_f32_32x32x16_bf16 v[130:145], v[232:235], v[14:17], v[130:145]
	ds_read_b128 v[10:13], v248 offset:64
	s_waitcnt lgkmcnt(4)
	v_mfma_f32_32x32x16_bf16 v[82:97], v[228:231], v[236:239], v[82:97]
	ds_read_b128 v[214:217], v249 offset:4672
	v_mfma_f32_32x32x16_bf16 v[98:113], v[232:235], v[236:239], v[98:113]
	ds_read_b128 v[14:17], v248 offset:4672
	s_waitcnt lgkmcnt(5)
	v_mfma_f32_32x32x16_bf16 v[50:65], v[228:231], v[2:5], v[50:65]
	ds_read_b128 v[236:239], v248 offset:9280
	v_mfma_f32_32x32x16_bf16 v[66:81], v[232:235], v[2:5], v[66:81]
	s_waitcnt lgkmcnt(5)
	v_mfma_f32_32x32x16_bf16 v[18:33], v[228:231], v[6:9], v[18:33]
	ds_read_b128 v[2:5], v248 offset:13888
	v_mfma_f32_32x32x16_bf16 v[34:49], v[232:235], v[6:9], v[34:49]
	s_waitcnt lgkmcnt(4)
	v_mfma_f32_32x32x16_bf16 v[114:129], v[210:213], v[10:13], v[114:129]
	ds_read_b128 v[228:231], v249 offset:96
	s_waitcnt lgkmcnt(4)
	v_mfma_f32_32x32x16_bf16 v[130:145], v[214:217], v[10:13], v[130:145]
	ds_read_b128 v[6:9], v248 offset:96
	s_waitcnt lgkmcnt(4)
	v_mfma_f32_32x32x16_bf16 v[82:97], v[210:213], v[14:17], v[82:97]
	ds_read_b128 v[232:235], v249 offset:4704
	v_mfma_f32_32x32x16_bf16 v[98:113], v[214:217], v[14:17], v[98:113]
	ds_read_b128 v[10:13], v248 offset:4704
	s_waitcnt lgkmcnt(5)
	v_mfma_f32_32x32x16_bf16 v[50:65], v[210:213], v[236:239], v[50:65]
	ds_read_b128 v[14:17], v248 offset:9312
	v_mfma_f32_32x32x16_bf16 v[66:81], v[214:217], v[236:239], v[66:81]
	s_waitcnt lgkmcnt(5)
	v_mfma_f32_32x32x16_bf16 v[18:33], v[210:213], v[2:5], v[18:33]
	ds_read_b128 v[236:239], v248 offset:13920
	v_mfma_f32_32x32x16_bf16 v[34:49], v[214:217], v[2:5], v[34:49]
	s_waitcnt lgkmcnt(4)
	v_mfma_f32_32x32x16_bf16 v[114:129], v[228:231], v[6:9], v[114:129]
	s_waitcnt lgkmcnt(3)
	v_mfma_f32_32x32x16_bf16 v[130:145], v[232:235], v[6:9], v[130:145]
	s_waitcnt lgkmcnt(2)
	v_mfma_f32_32x32x16_bf16 v[82:97], v[228:231], v[10:13], v[82:97]
	v_mfma_f32_32x32x16_bf16 v[98:113], v[232:235], v[10:13], v[98:113]
	s_waitcnt lgkmcnt(1)
	v_mfma_f32_32x32x16_bf16 v[50:65], v[228:231], v[14:17], v[50:65]
	v_mfma_f32_32x32x16_bf16 v[66:81], v[232:235], v[14:17], v[66:81]
	s_waitcnt lgkmcnt(0)
	v_mfma_f32_32x32x16_bf16 v[18:33], v[228:231], v[236:239], v[18:33]
	v_mfma_f32_32x32x16_bf16 v[34:49], v[232:235], v[236:239], v[34:49]
	s_barrier
	ds_read_b128 v[210:213], v249 offset:36864
	ds_read_b128 v[236:239], v248 offset:36864
	ds_read_b128 v[214:217], v249 offset:41472
	ds_read_b128 v[2:5], v248 offset:41472
	ds_read_b128 v[6:9], v248 offset:46080
	ds_read_b128 v[10:13], v248 offset:50688
	s_waitcnt lgkmcnt(4)
	v_mfma_f32_32x32x16_bf16 v[114:129], v[210:213], v[236:239], v[114:129]
	ds_read_b128 v[228:231], v249 offset:36896
	s_waitcnt lgkmcnt(4)
	v_mfma_f32_32x32x16_bf16 v[130:145], v[214:217], v[236:239], v[130:145]
	ds_read_b128 v[14:17], v248 offset:36896
	s_waitcnt lgkmcnt(4)
	v_mfma_f32_32x32x16_bf16 v[82:97], v[210:213], v[2:5], v[82:97]
	ds_read_b128 v[232:235], v249 offset:41504
	v_mfma_f32_32x32x16_bf16 v[98:113], v[214:217], v[2:5], v[98:113]
	ds_read_b128 v[236:239], v248 offset:41504
	s_waitcnt vmcnt(15)
	ds_write_b128 v250, v[146:149]
	s_waitcnt lgkmcnt(6)
	v_mfma_f32_32x32x16_bf16 v[50:65], v[210:213], v[6:9], v[50:65]
	ds_read_b128 v[2:5], v248 offset:46112
	v_mfma_f32_32x32x16_bf16 v[66:81], v[214:217], v[6:9], v[66:81]
	global_load_dwordx4 v[146:149], v227, s[74:75] offset:512 sc0
	s_waitcnt lgkmcnt(6)
	v_mfma_f32_32x32x16_bf16 v[18:33], v[210:213], v[10:13], v[18:33]
	ds_read_b128 v[6:9], v248 offset:50720
	s_waitcnt vmcnt(15)
	ds_write_b128 v251, v[178:181]
	v_mfma_f32_32x32x16_bf16 v[34:49], v[214:217], v[10:13], v[34:49]
	s_waitcnt lgkmcnt(6)
	v_mfma_f32_32x32x16_bf16 v[114:129], v[228:231], v[14:17], v[114:129]
	ds_read_b128 v[210:213], v249 offset:36928
	global_load_dwordx4 v[178:181], v227, s[82:83] offset:512 sc0
	s_waitcnt lgkmcnt(6)
	v_mfma_f32_32x32x16_bf16 v[130:145], v[232:235], v[14:17], v[130:145]
	ds_read_b128 v[10:13], v248 offset:36928
	s_waitcnt vmcnt(15)
	ds_write_b128 v250, v[150:153] offset:9216
	s_waitcnt lgkmcnt(7)
;     ...
;   for (int kt = 0; kt < nk; ++kt) {
;     __syncthreads();
;     if (kt + 1 < nk) {
;       u16* aw = As0 + ((kt + 1) & 1) * 256 * LD;
;       u16* bw = Bs0 + ((kt + 1) & 1) * 256 * LD;
; #pragma unroll
;       for (int i = 0; i < 4; ++i) { *(u32x4*)(aw + (srow + 64 * i) * LD + skc * 8) = ra[i]; *(u32x4*)(bw + (srow + 64 * i) * LD + skc * 8) = rb[i]; }
;     }
;     if (kt + 2 < nk) {
; #pragma unroll
;       for (int i = 0; i < 4; ++i) { ra[i] = *(const u32x4*)(Ag + (size_t)(64 * i) * K + (kt + 2) * 64); rb[i] = *(const u32x4*)(Bg[i] + (kt + 2) * 64); }
;     }
;     __builtin_amdgcn_sched_barrier(0);
;     const u16* as = As0 + (kt & 1) * 256 * LD + (wr * 128 + l31) * LD + h * 8;
;     const u16* bs = Bs0 + (kt & 1) * 256 * LD + (wc * 64 + l31) * LD + h * 8;
;     if (domma)
; #pragma unroll
;     for (int ks = 0; ks < 4; ++ks) {
;       bf16x8 wf[2], xf[4];
; #pragma unroll
;       for (int ct = 0; ct < 2; ++ct) wf[ct] = *(const bf16x8*)(bs + ct * 32 * LD + ks * 16);
; #pragma unroll
;       for (int tt = 0; tt < 4; ++tt) xf[tt] = *(const bf16x8*)(as + tt * 32 * LD + ks * 16);
; #pragma unroll
;       for (int ct = 0; ct < 2; ++ct)
; #pragma unroll
;         for (int tt = 0; tt < 4; ++tt) acc[ct][tt] = __builtin_amdgcn_mfma_f32_32x32x16_bf16(wf[ct], xf[tt], acc[ct][tt], 0, 0, 0);
;     }
	v_mfma_f32_32x32x16_bf16 v[82:97], v[228:231], v[236:239], v[82:97]
	ds_read_b128 v[214:217], v249 offset:41536
	v_mfma_f32_32x32x16_bf16 v[98:113], v[232:235], v[236:239], v[98:113]
	ds_read_b128 v[14:17], v248 offset:41536
	global_load_dwordx4 v[150:153], v227, s[76:77] offset:512 sc0
	s_waitcnt lgkmcnt(7)
	v_mfma_f32_32x32x16_bf16 v[50:65], v[228:231], v[2:5], v[50:65]
	ds_read_b128 v[236:239], v248 offset:46144
	s_waitcnt vmcnt(15)
	ds_write_b128 v251, v[182:185] offset:9216
	v_mfma_f32_32x32x16_bf16 v[66:81], v[232:235], v[2:5], v[66:81]
	s_waitcnt lgkmcnt(8)
	v_mfma_f32_32x32x16_bf16 v[18:33], v[228:231], v[6:9], v[18:33]
	ds_read_b128 v[2:5], v248 offset:50752
	global_load_dwordx4 v[182:185], v227, s[84:85] offset:512 sc0
	v_mfma_f32_32x32x16_bf16 v[34:49], v[232:235], v[6:9], v[34:49]
	s_waitcnt vmcnt(15)
	ds_write_b128 v250, v[154:157] offset:18432
	s_waitcnt lgkmcnt(7)
	v_mfma_f32_32x32x16_bf16 v[114:129], v[210:213], v[10:13], v[114:129]
	ds_read_b128 v[228:231], v249 offset:36960
	s_waitcnt lgkmcnt(6)
	v_mfma_f32_32x32x16_bf16 v[130:145], v[214:217], v[10:13], v[130:145]
	ds_read_b128 v[6:9], v248 offset:36960
	global_load_dwordx4 v[154:157], v227, s[78:79] offset:512 sc0
	s_waitcnt lgkmcnt(6)
	v_mfma_f32_32x32x16_bf16 v[82:97], v[210:213], v[14:17], v[82:97]
	ds_read_b128 v[232:235], v249 offset:41568
	s_waitcnt vmcnt(15)
	ds_write_b128 v251, v[186:189] offset:18432
	v_mfma_f32_32x32x16_bf16 v[98:113], v[214:217], v[14:17], v[98:113]
	ds_read_b128 v[10:13], v248 offset:41568
	s_waitcnt lgkmcnt(8)
	v_mfma_f32_32x32x16_bf16 v[50:65], v[210:213], v[236:239], v[50:65]
	ds_read_b128 v[14:17], v248 offset:46176
	global_load_dwordx4 v[186:189], v227, s[86:87] offset:512 sc0
	v_mfma_f32_32x32x16_bf16 v[66:81], v[214:217], v[236:239], v[66:81]
	s_waitcnt vmcnt(15)
	ds_write_b128 v250, v[158:161] offset:27648
	s_waitcnt lgkmcnt(8)
	v_mfma_f32_32x32x16_bf16 v[18:33], v[210:213], v[2:5], v[18:33]
	ds_read_b128 v[236:239], v248 offset:50784
	v_mfma_f32_32x32x16_bf16 v[34:49], v[214:217], v[2:5], v[34:49]
	global_load_dwordx4 v[158:161], v227, s[80:81] offset:512 sc0
	s_waitcnt lgkmcnt(6)
	v_mfma_f32_32x32x16_bf16 v[114:129], v[228:231], v[6:9], v[114:129]
	s_waitcnt vmcnt(15)
	ds_write_b128 v251, v[190:193] offset:27648
	s_waitcnt lgkmcnt(6)
	v_mfma_f32_32x32x16_bf16 v[130:145], v[232:235], v[6:9], v[130:145]
	s_waitcnt lgkmcnt(4)
	v_mfma_f32_32x32x16_bf16 v[82:97], v[228:231], v[10:13], v[82:97]
	global_load_dwordx4 v[190:193], v227, s[92:93] offset:512 sc0
	v_mfma_f32_32x32x16_bf16 v[98:113], v[232:235], v[10:13], v[98:113]
	s_waitcnt lgkmcnt(3)
	v_mfma_f32_32x32x16_bf16 v[50:65], v[228:231], v[14:17], v[50:65]
	v_mfma_f32_32x32x16_bf16 v[66:81], v[232:235], v[14:17], v[66:81]
	s_waitcnt lgkmcnt(1)
	v_mfma_f32_32x32x16_bf16 v[18:33], v[228:231], v[236:239], v[18:33]
	v_mfma_f32_32x32x16_bf16 v[34:49], v[232:235], v[236:239], v[34:49]
	s_waitcnt lgkmcnt(0)
	s_barrier
	ds_read_b128 v[210:213], v249
	ds_read_b128 v[236:239], v248
	ds_read_b128 v[214:217], v249 offset:4608
	ds_read_b128 v[2:5], v248 offset:4608
	ds_read_b128 v[6:9], v248 offset:9216
	ds_read_b128 v[10:13], v248 offset:13824
	s_waitcnt lgkmcnt(4)
	v_mfma_f32_32x32x16_bf16 v[114:129], v[210:213], v[236:239], v[114:129]
	ds_read_b128 v[228:231], v249 offset:32
	s_waitcnt lgkmcnt(4)
	v_mfma_f32_32x32x16_bf16 v[130:145], v[214:217], v[236:239], v[130:145]
	ds_read_b128 v[14:17], v248 offset:32
	s_waitcnt lgkmcnt(4)
	v_mfma_f32_32x32x16_bf16 v[82:97], v[210:213], v[2:5], v[82:97]
	ds_read_b128 v[232:235], v249 offset:4640
	v_mfma_f32_32x32x16_bf16 v[98:113], v[214:217], v[2:5], v[98:113]
	ds_read_b128 v[236:239], v248 offset:4640
	s_waitcnt vmcnt(15)
	ds_write_b128 v250, v[162:165] offset:36864
	s_waitcnt lgkmcnt(6)
	v_mfma_f32_32x32x16_bf16 v[50:65], v[210:213], v[6:9], v[50:65]
	ds_read_b128 v[2:5], v248 offset:9248
	v_mfma_f32_32x32x16_bf16 v[66:81], v[214:217], v[6:9], v[66:81]
	global_load_dwordx4 v[162:165], v227, s[74:75] offset:640 sc0
	s_waitcnt lgkmcnt(6)
	v_mfma_f32_32x32x16_bf16 v[18:33], v[210:213], v[10:13], v[18:33]
	ds_read_b128 v[6:9], v248 offset:13856
	s_waitcnt vmcnt(15)
	ds_write_b128 v251, v[194:197] offset:36864
	v_mfma_f32_32x32x16_bf16 v[34:49], v[214:217], v[10:13], v[34:49]
	s_waitcnt lgkmcnt(6)
	v_mfma_f32_32x32x16_bf16 v[114:129], v[228:231], v[14:17], v[114:129]
	ds_read_b128 v[210:213], v249 offset:64
	global_load_dwordx4 v[194:197], v227, s[82:83] offset:640 sc0
	s_waitcnt lgkmcnt(6)
	v_mfma_f32_32x32x16_bf16 v[130:145], v[232:235], v[14:17], v[130:145]
	ds_read_b128 v[10:13], v248 offset:64
	s_waitcnt vmcnt(15)
	ds_write_b128 v250, v[166:169] offset:46080
	s_waitcnt lgkmcnt(7)
	v_mfma_f32_32x32x16_bf16 v[82:97], v[228:231], v[236:239], v[82:97]
	ds_read_b128 v[214:217], v249 offset:4672
	v_mfma_f32_32x32x16_bf16 v[98:113], v[232:235], v[236:239], v[98:113]
	ds_read_b128 v[14:17], v248 offset:4672
	global_load_dwordx4 v[166:169], v227, s[76:77] offset:640 sc0
	s_waitcnt lgkmcnt(7)
	v_mfma_f32_32x32x16_bf16 v[50:65], v[228:231], v[2:5], v[50:65]
	ds_read_b128 v[236:239], v248 offset:9280
	s_waitcnt vmcnt(15)
	ds_write_b128 v251, v[198:201] offset:46080
	v_mfma_f32_32x32x16_bf16 v[66:81], v[232:235], v[2:5], v[66:81]
	s_waitcnt lgkmcnt(8)
	v_mfma_f32_32x32x16_bf16 v[18:33], v[228:231], v[6:9], v[18:33]
	ds_read_b128 v[2:5], v248 offset:13888
	global_load_dwordx4 v[198:201], v227, s[84:85] offset:640 sc0
	v_mfma_f32_32x32x16_bf16 v[34:49], v[232:235], v[6:9], v[34:49]
	s_waitcnt vmcnt(15)
	ds_write_b128 v250, v[170:173] offset:55296
	s_waitcnt lgkmcnt(7)
	v_mfma_f32_32x32x16_bf16 v[114:129], v[210:213], v[10:13], v[114:129]
	ds_read_b128 v[228:231], v249 offset:96
	s_waitcnt lgkmcnt(6)
;     ...
;   for (int kt = 0; kt < nk; ++kt) {
;     __syncthreads();
;     if (kt + 1 < nk) {
;       u16* aw = As0 + ((kt + 1) & 1) * 256 * LD;
;       u16* bw = Bs0 + ((kt + 1) & 1) * 256 * LD;
; #pragma unroll
;       for (int i = 0; i < 4; ++i) { *(u32x4*)(aw + (srow + 64 * i) * LD + skc * 8) = ra[i]; *(u32x4*)(bw + (srow + 64 * i) * LD + skc * 8) = rb[i]; }
;     }
;     if (kt + 2 < nk) {
; #pragma unroll
;       for (int i = 0; i < 4; ++i) { ra[i] = *(const u32x4*)(Ag + (size_t)(64 * i) * K + (kt + 2) * 64); rb[i] = *(const u32x4*)(Bg[i] + (kt + 2) * 64); }
;     }
;     __builtin_amdgcn_sched_barrier(0);
;     const u16* as = As0 + (kt & 1) * 256 * LD + (wr * 128 + l31) * LD + h * 8;
;     const u16* bs = Bs0 + (kt & 1) * 256 * LD + (wc * 64 + l31) * LD + h * 8;
;     if (domma)
; #pragma unroll
;     for (int ks = 0; ks < 4; ++ks) {
;       bf16x8 wf[2], xf[4];
; #pragma unroll
;       for (int ct = 0; ct < 2; ++ct) wf[ct] = *(const bf16x8*)(bs + ct * 32 * LD + ks * 16);
; #pragma unroll
;       for (int tt = 0; tt < 4; ++tt) xf[tt] = *(const bf16x8*)(as + tt * 32 * LD + ks * 16);
; #pragma unroll
;       for (int ct = 0; ct < 2; ++ct)
; #pragma unroll
;         for (int tt = 0; tt < 4; ++tt) acc[ct][tt] = __builtin_amdgcn_mfma_f32_32x32x16_bf16(wf[ct], xf[tt], acc[ct][tt], 0, 0, 0);
;     }
	v_mfma_f32_32x32x16_bf16 v[130:145], v[214:217], v[10:13], v[130:145]
	ds_read_b128 v[6:9], v248 offset:96
	global_load_dwordx4 v[170:173], v227, s[78:79] offset:640 sc0
	s_waitcnt lgkmcnt(6)
	v_mfma_f32_32x32x16_bf16 v[82:97], v[210:213], v[14:17], v[82:97]
	ds_read_b128 v[232:235], v249 offset:4704
	s_waitcnt vmcnt(15)
	ds_write_b128 v251, v[202:205] offset:55296
	v_mfma_f32_32x32x16_bf16 v[98:113], v[214:217], v[14:17], v[98:113]
	ds_read_b128 v[10:13], v248 offset:4704
	s_waitcnt lgkmcnt(8)
	v_mfma_f32_32x32x16_bf16 v[50:65], v[210:213], v[236:239], v[50:65]
	ds_read_b128 v[14:17], v248 offset:9312
	global_load_dwordx4 v[202:205], v227, s[86:87] offset:640 sc0
	v_mfma_f32_32x32x16_bf16 v[66:81], v[214:217], v[236:239], v[66:81]
	s_waitcnt vmcnt(15)
	ds_write_b128 v250, v[174:177] offset:64512
	s_waitcnt lgkmcnt(8)
	v_mfma_f32_32x32x16_bf16 v[18:33], v[210:213], v[2:5], v[18:33]
	ds_read_b128 v[236:239], v248 offset:13920
	v_mfma_f32_32x32x16_bf16 v[34:49], v[214:217], v[2:5], v[34:49]
	global_load_dwordx4 v[174:177], v227, s[80:81] offset:640 sc0
	s_waitcnt lgkmcnt(6)
	v_mfma_f32_32x32x16_bf16 v[114:129], v[228:231], v[6:9], v[114:129]
	s_waitcnt vmcnt(15)
	ds_write_b128 v251, v[206:209] offset:64512
	s_waitcnt lgkmcnt(6)
	v_mfma_f32_32x32x16_bf16 v[130:145], v[232:235], v[6:9], v[130:145]
	s_waitcnt lgkmcnt(4)
	v_mfma_f32_32x32x16_bf16 v[82:97], v[228:231], v[10:13], v[82:97]
	global_load_dwordx4 v[206:209], v227, s[92:93] offset:640 sc0
	v_mfma_f32_32x32x16_bf16 v[98:113], v[232:235], v[10:13], v[98:113]
	s_waitcnt lgkmcnt(3)
	v_mfma_f32_32x32x16_bf16 v[50:65], v[228:231], v[14:17], v[50:65]
	v_mfma_f32_32x32x16_bf16 v[66:81], v[232:235], v[14:17], v[66:81]
	s_waitcnt lgkmcnt(1)
	v_mfma_f32_32x32x16_bf16 v[18:33], v[228:231], v[236:239], v[18:33]
	v_mfma_f32_32x32x16_bf16 v[34:49], v[232:235], v[236:239], v[34:49]
	s_waitcnt lgkmcnt(0)
	s_barrier
	ds_read_b128 v[210:213], v249 offset:36864
	ds_read_b128 v[236:239], v248 offset:36864
	ds_read_b128 v[214:217], v249 offset:41472
	ds_read_b128 v[2:5], v248 offset:41472
	ds_read_b128 v[6:9], v248 offset:46080
	ds_read_b128 v[10:13], v248 offset:50688
	s_waitcnt lgkmcnt(4)
	v_mfma_f32_32x32x16_bf16 v[114:129], v[210:213], v[236:239], v[114:129]
	ds_read_b128 v[228:231], v249 offset:36896
	s_waitcnt lgkmcnt(4)
	v_mfma_f32_32x32x16_bf16 v[130:145], v[214:217], v[236:239], v[130:145]
	ds_read_b128 v[14:17], v248 offset:36896
	s_waitcnt lgkmcnt(4)
	v_mfma_f32_32x32x16_bf16 v[82:97], v[210:213], v[2:5], v[82:97]
	ds_read_b128 v[232:235], v249 offset:41504
	v_mfma_f32_32x32x16_bf16 v[98:113], v[214:217], v[2:5], v[98:113]
	ds_read_b128 v[236:239], v248 offset:41504
	s_waitcnt vmcnt(15)
	ds_write_b128 v250, v[146:149]
	s_waitcnt lgkmcnt(6)
	v_mfma_f32_32x32x16_bf16 v[50:65], v[210:213], v[6:9], v[50:65]
	ds_read_b128 v[2:5], v248 offset:46112
	v_mfma_f32_32x32x16_bf16 v[66:81], v[214:217], v[6:9], v[66:81]
	global_load_dwordx4 v[146:149], v227, s[74:75] offset:768 sc0
	s_waitcnt lgkmcnt(6)
	v_mfma_f32_32x32x16_bf16 v[18:33], v[210:213], v[10:13], v[18:33]
	ds_read_b128 v[6:9], v248 offset:50720
	s_waitcnt vmcnt(15)
	ds_write_b128 v251, v[178:181]
	v_mfma_f32_32x32x16_bf16 v[34:49], v[214:217], v[10:13], v[34:49]
	s_waitcnt lgkmcnt(6)
	v_mfma_f32_32x32x16_bf16 v[114:129], v[228:231], v[14:17], v[114:129]
	ds_read_b128 v[210:213], v249 offset:36928
	global_load_dwordx4 v[178:181], v227, s[82:83] offset:768 sc0
	s_waitcnt lgkmcnt(6)
	v_mfma_f32_32x32x16_bf16 v[130:145], v[232:235], v[14:17], v[130:145]
	ds_read_b128 v[10:13], v248 offset:36928
	s_waitcnt vmcnt(15)
	ds_write_b128 v250, v[150:153] offset:9216
	s_waitcnt lgkmcnt(7)
	v_mfma_f32_32x32x16_bf16 v[82:97], v[228:231], v[236:239], v[82:97]
	ds_read_b128 v[214:217], v249 offset:41536
	v_mfma_f32_32x32x16_bf16 v[98:113], v[232:235], v[236:239], v[98:113]
	ds_read_b128 v[14:17], v248 offset:41536
	global_load_dwordx4 v[150:153], v227, s[76:77] offset:768 sc0
	s_waitcnt lgkmcnt(7)
	v_mfma_f32_32x32x16_bf16 v[50:65], v[228:231], v[2:5], v[50:65]
	ds_read_b128 v[236:239], v248 offset:46144
	s_waitcnt vmcnt(15)
	ds_write_b128 v251, v[182:185] offset:9216
	v_mfma_f32_32x32x16_bf16 v[66:81], v[232:235], v[2:5], v[66:81]
	s_waitcnt lgkmcnt(8)
	v_mfma_f32_32x32x16_bf16 v[18:33], v[228:231], v[6:9], v[18:33]
	ds_read_b128 v[2:5], v248 offset:50752
	global_load_dwordx4 v[182:185], v227, s[84:85] offset:768 sc0
	v_mfma_f32_32x32x16_bf16 v[34:49], v[232:235], v[6:9], v[34:49]
	s_waitcnt vmcnt(15)
	ds_write_b128 v250, v[154:157] offset:18432
	s_waitcnt lgkmcnt(7)
	v_mfma_f32_32x32x16_bf16 v[114:129], v[210:213], v[10:13], v[114:129]
	ds_read_b128 v[228:231], v249 offset:36960
	s_waitcnt lgkmcnt(6)
	v_mfma_f32_32x32x16_bf16 v[130:145], v[214:217], v[10:13], v[130:145]
	ds_read_b128 v[6:9], v248 offset:36960
	global_load_dwordx4 v[154:157], v227, s[78:79] offset:768 sc0
	s_waitcnt lgkmcnt(6)
	v_mfma_f32_32x32x16_bf16 v[82:97], v[210:213], v[14:17], v[82:97]
	ds_read_b128 v[232:235], v249 offset:41568
	s_waitcnt vmcnt(15)
	ds_write_b128 v251, v[186:189] offset:18432
	v_mfma_f32_32x32x16_bf16 v[98:113], v[214:217], v[14:17], v[98:113]
	ds_read_b128 v[10:13], v248 offset:41568
	s_waitcnt lgkmcnt(8)
	v_mfma_f32_32x32x16_bf16 v[50:65], v[210:213], v[236:239], v[50:65]
	ds_read_b128 v[14:17], v248 offset:46176
	global_load_dwordx4 v[186:189], v227, s[86:87] offset:768 sc0
	v_mfma_f32_32x32x16_bf16 v[66:81], v[214:217], v[236:239], v[66:81]
	s_waitcnt vmcnt(15)
	ds_write_b128 v250, v[158:161] offset:27648
	s_waitcnt lgkmcnt(8)
	v_mfma_f32_32x32x16_bf16 v[18:33], v[210:213], v[2:5], v[18:33]
	ds_read_b128 v[236:239], v248 offset:50784
	v_mfma_f32_32x32x16_bf16 v[34:49], v[214:217], v[2:5], v[34:49]
	global_load_dwordx4 v[158:161], v227, s[80:81] offset:768 sc0
	s_waitcnt lgkmcnt(6)
	v_mfma_f32_32x32x16_bf16 v[114:129], v[228:231], v[6:9], v[114:129]
	s_waitcnt vmcnt(15)
	ds_write_b128 v251, v[190:193] offset:27648
	s_waitcnt lgkmcnt(6)
	v_mfma_f32_32x32x16_bf16 v[130:145], v[232:235], v[6:9], v[130:145]
	s_waitcnt lgkmcnt(4)
	v_mfma_f32_32x32x16_bf16 v[82:97], v[228:231], v[10:13], v[82:97]
	global_load_dwordx4 v[190:193], v227, s[92:93] offset:768 sc0
	v_mfma_f32_32x32x16_bf16 v[98:113], v[232:235], v[10:13], v[98:113]
	s_waitcnt lgkmcnt(3)
	v_mfma_f32_32x32x16_bf16 v[50:65], v[228:231], v[14:17], v[50:65]
	v_mfma_f32_32x32x16_bf16 v[66:81], v[232:235], v[14:17], v[66:81]
	s_waitcnt lgkmcnt(1)
	v_mfma_f32_32x32x16_bf16 v[18:33], v[228:231], v[236:239], v[18:33]
	v_mfma_f32_32x32x16_bf16 v[34:49], v[232:235], v[236:239], v[34:49]
	s_waitcnt lgkmcnt(0)
	s_barrier
;     ...
;   for (int kt = 0; kt < nk; ++kt) {
;     __syncthreads();
;     if (kt + 1 < nk) {
;       u16* aw = As0 + ((kt + 1) & 1) * 256 * LD;
;       u16* bw = Bs0 + ((kt + 1) & 1) * 256 * LD;
; #pragma unroll
;       for (int i = 0; i < 4; ++i) { *(u32x4*)(aw + (srow + 64 * i) * LD + skc * 8) = ra[i]; *(u32x4*)(bw + (srow + 64 * i) * LD + skc * 8) = rb[i]; }
;     }
;     if (kt + 2 < nk) {
; #pragma unroll
;       for (int i = 0; i < 4; ++i) { ra[i] = *(const u32x4*)(Ag + (size_t)(64 * i) * K + (kt + 2) * 64); rb[i] = *(const u32x4*)(Bg[i] + (kt + 2) * 64); }
;     }
;     __builtin_amdgcn_sched_barrier(0);
;     const u16* as = As0 + (kt & 1) * 256 * LD + (wr * 128 + l31) * LD + h * 8;
;     const u16* bs = Bs0 + (kt & 1) * 256 * LD + (wc * 64 + l31) * LD + h * 8;
;     if (domma)
; #pragma unroll
;     for (int ks = 0; ks < 4; ++ks) {
;       bf16x8 wf[2], xf[4];
; #pragma unroll
;       for (int ct = 0; ct < 2; ++ct) wf[ct] = *(const bf16x8*)(bs + ct * 32 * LD + ks * 16);
; #pragma unroll
;       for (int tt = 0; tt < 4; ++tt) xf[tt] = *(const bf16x8*)(as + tt * 32 * LD + ks * 16);
; #pragma unroll
;       for (int ct = 0; ct < 2; ++ct)
; #pragma unroll
;         for (int tt = 0; tt < 4; ++tt) acc[ct][tt] = __builtin_amdgcn_mfma_f32_32x32x16_bf16(wf[ct], xf[tt], acc[ct][tt], 0, 0, 0);
;     }
	ds_read_b128 v[210:213], v249
	ds_read_b128 v[236:239], v248
	ds_read_b128 v[214:217], v249 offset:4608
	ds_read_b128 v[2:5], v248 offset:4608
	ds_read_b128 v[6:9], v248 offset:9216
	ds_read_b128 v[10:13], v248 offset:13824
	s_waitcnt lgkmcnt(4)
	v_mfma_f32_32x32x16_bf16 v[114:129], v[210:213], v[236:239], v[114:129]
	ds_read_b128 v[228:231], v249 offset:32
	s_waitcnt lgkmcnt(4)
	v_mfma_f32_32x32x16_bf16 v[130:145], v[214:217], v[236:239], v[130:145]
	ds_read_b128 v[14:17], v248 offset:32
	s_waitcnt lgkmcnt(4)
	v_mfma_f32_32x32x16_bf16 v[82:97], v[210:213], v[2:5], v[82:97]
	ds_read_b128 v[232:235], v249 offset:4640
	v_mfma_f32_32x32x16_bf16 v[98:113], v[214:217], v[2:5], v[98:113]
	ds_read_b128 v[236:239], v248 offset:4640
	s_waitcnt vmcnt(15)
	ds_write_b128 v250, v[162:165] offset:36864
	s_waitcnt lgkmcnt(6)
	v_mfma_f32_32x32x16_bf16 v[50:65], v[210:213], v[6:9], v[50:65]
	ds_read_b128 v[2:5], v248 offset:9248
	v_mfma_f32_32x32x16_bf16 v[66:81], v[214:217], v[6:9], v[66:81]
	global_load_dwordx4 v[162:165], v227, s[74:75] offset:896 sc0
	s_waitcnt lgkmcnt(6)
	v_mfma_f32_32x32x16_bf16 v[18:33], v[210:213], v[10:13], v[18:33]
	ds_read_b128 v[6:9], v248 offset:13856
	s_waitcnt vmcnt(15)
	ds_write_b128 v251, v[194:197] offset:36864
	v_mfma_f32_32x32x16_bf16 v[34:49], v[214:217], v[10:13], v[34:49]
	s_waitcnt lgkmcnt(6)
	v_mfma_f32_32x32x16_bf16 v[114:129], v[228:231], v[14:17], v[114:129]
	ds_read_b128 v[210:213], v249 offset:64
	global_load_dwordx4 v[194:197], v227, s[82:83] offset:896 sc0
	s_waitcnt lgkmcnt(6)
	v_mfma_f32_32x32x16_bf16 v[130:145], v[232:235], v[14:17], v[130:145]
	ds_read_b128 v[10:13], v248 offset:64
	s_waitcnt vmcnt(15)
	ds_write_b128 v250, v[166:169] offset:46080
	s_waitcnt lgkmcnt(7)
	v_mfma_f32_32x32x16_bf16 v[82:97], v[228:231], v[236:239], v[82:97]
	ds_read_b128 v[214:217], v249 offset:4672
	v_mfma_f32_32x32x16_bf16 v[98:113], v[232:235], v[236:239], v[98:113]
	ds_read_b128 v[14:17], v248 offset:4672
	global_load_dwordx4 v[166:169], v227, s[76:77] offset:896 sc0
	s_waitcnt lgkmcnt(7)
	v_mfma_f32_32x32x16_bf16 v[50:65], v[228:231], v[2:5], v[50:65]
	ds_read_b128 v[236:239], v248 offset:9280
	s_waitcnt vmcnt(15)
	ds_write_b128 v251, v[198:201] offset:46080
	v_mfma_f32_32x32x16_bf16 v[66:81], v[232:235], v[2:5], v[66:81]
	s_waitcnt lgkmcnt(8)
	v_mfma_f32_32x32x16_bf16 v[18:33], v[228:231], v[6:9], v[18:33]
	ds_read_b128 v[2:5], v248 offset:13888
	global_load_dwordx4 v[198:201], v227, s[84:85] offset:896 sc0
	v_mfma_f32_32x32x16_bf16 v[34:49], v[232:235], v[6:9], v[34:49]
	s_waitcnt vmcnt(15)
	ds_write_b128 v250, v[170:173] offset:55296
	s_waitcnt lgkmcnt(7)
	v_mfma_f32_32x32x16_bf16 v[114:129], v[210:213], v[10:13], v[114:129]
	ds_read_b128 v[228:231], v249 offset:96
	s_waitcnt lgkmcnt(6)
	v_mfma_f32_32x32x16_bf16 v[130:145], v[214:217], v[10:13], v[130:145]
	ds_read_b128 v[6:9], v248 offset:96
	global_load_dwordx4 v[170:173], v227, s[78:79] offset:896 sc0
	s_waitcnt lgkmcnt(6)
	v_mfma_f32_32x32x16_bf16 v[82:97], v[210:213], v[14:17], v[82:97]
	ds_read_b128 v[232:235], v249 offset:4704
	s_waitcnt vmcnt(15)
	ds_write_b128 v251, v[202:205] offset:55296
	v_mfma_f32_32x32x16_bf16 v[98:113], v[214:217], v[14:17], v[98:113]
	ds_read_b128 v[10:13], v248 offset:4704
	s_waitcnt lgkmcnt(8)
	v_mfma_f32_32x32x16_bf16 v[50:65], v[210:213], v[236:239], v[50:65]
	ds_read_b128 v[14:17], v248 offset:9312
	global_load_dwordx4 v[202:205], v227, s[86:87] offset:896 sc0
	v_mfma_f32_32x32x16_bf16 v[66:81], v[214:217], v[236:239], v[66:81]
	s_waitcnt vmcnt(15)
	ds_write_b128 v250, v[174:177] offset:64512
	s_waitcnt lgkmcnt(8)
	v_mfma_f32_32x32x16_bf16 v[18:33], v[210:213], v[2:5], v[18:33]
	ds_read_b128 v[236:239], v248 offset:13920
	v_mfma_f32_32x32x16_bf16 v[34:49], v[214:217], v[2:5], v[34:49]
	global_load_dwordx4 v[174:177], v227, s[80:81] offset:896 sc0
	s_waitcnt lgkmcnt(6)
	v_mfma_f32_32x32x16_bf16 v[114:129], v[228:231], v[6:9], v[114:129]
	s_waitcnt vmcnt(15)
	ds_write_b128 v251, v[206:209] offset:64512
	s_waitcnt lgkmcnt(6)
	v_mfma_f32_32x32x16_bf16 v[130:145], v[232:235], v[6:9], v[130:145]
	s_waitcnt lgkmcnt(4)
	v_mfma_f32_32x32x16_bf16 v[82:97], v[228:231], v[10:13], v[82:97]
	global_load_dwordx4 v[206:209], v227, s[92:93] offset:896 sc0
	v_mfma_f32_32x32x16_bf16 v[98:113], v[232:235], v[10:13], v[98:113]
	s_waitcnt lgkmcnt(3)
	v_mfma_f32_32x32x16_bf16 v[50:65], v[228:231], v[14:17], v[50:65]
	v_mfma_f32_32x32x16_bf16 v[66:81], v[232:235], v[14:17], v[66:81]
	s_waitcnt lgkmcnt(1)
	v_mfma_f32_32x32x16_bf16 v[18:33], v[228:231], v[236:239], v[18:33]
	v_mfma_f32_32x32x16_bf16 v[34:49], v[232:235], v[236:239], v[34:49]
	s_waitcnt lgkmcnt(0)
	s_barrier
;     ...
;   for (int kt = 0; kt < nk; ++kt) {
;     __syncthreads();
;     if (kt + 1 < nk) {
;       u16* aw = As0 + ((kt + 1) & 1) * 256 * LD;
;       u16* bw = Bs0 + ((kt + 1) & 1) * 256 * LD;
; #pragma unroll
;       for (int i = 0; i < 4; ++i) { *(u32x4*)(aw + (srow + 64 * i) * LD + skc * 8) = ra[i]; *(u32x4*)(bw + (srow + 64 * i) * LD + skc * 8) = rb[i]; }
;     }
;     if (kt + 2 < nk) {
; #pragma unroll
;       for (int i = 0; i < 4; ++i) { ra[i] = *(const u32x4*)(Ag + (size_t)(64 * i) * K + (kt + 2) * 64); rb[i] = *(const u32x4*)(Bg[i] + (kt + 2) * 64); }
;     }
;     __builtin_amdgcn_sched_barrier(0);
;     const u16* as = As0 + (kt & 1) * 256 * LD + (wr * 128 + l31) * LD + h * 8;
;     const u16* bs = Bs0 + (kt & 1) * 256 * LD + (wc * 64 + l31) * LD + h * 8;
;     if (domma)
; #pragma unroll
;     for (int ks = 0; ks < 4; ++ks) {
;       bf16x8 wf[2], xf[4];
; #pragma unroll
;       for (int ct = 0; ct < 2; ++ct) wf[ct] = *(const bf16x8*)(bs + ct * 32 * LD + ks * 16);
; #pragma unroll
;       for (int tt = 0; tt < 4; ++tt) xf[tt] = *(const bf16x8*)(as + tt * 32 * LD + ks * 16);
; #pragma unroll
;       for (int ct = 0; ct < 2; ++ct)
; #pragma unroll
;         for (int tt = 0; tt < 4; ++tt) acc[ct][tt] = __builtin_amdgcn_mfma_f32_32x32x16_bf16(wf[ct], xf[tt], acc[ct][tt], 0, 0, 0);
;     }
	ds_read_b128 v[210:213], v249 offset:36864
	ds_read_b128 v[236:239], v248 offset:36864
	ds_read_b128 v[214:217], v249 offset:41472
	ds_read_b128 v[2:5], v248 offset:41472
	ds_read_b128 v[6:9], v248 offset:46080
	ds_read_b128 v[10:13], v248 offset:50688
	s_waitcnt lgkmcnt(4)
	v_mfma_f32_32x32x16_bf16 v[114:129], v[210:213], v[236:239], v[114:129]
	ds_read_b128 v[228:231], v249 offset:36896
	s_waitcnt lgkmcnt(4)
	v_mfma_f32_32x32x16_bf16 v[130:145], v[214:217], v[236:239], v[130:145]
	ds_read_b128 v[14:17], v248 offset:36896
	s_waitcnt lgkmcnt(4)
	v_mfma_f32_32x32x16_bf16 v[82:97], v[210:213], v[2:5], v[82:97]
	ds_read_b128 v[232:235], v249 offset:41504
	v_mfma_f32_32x32x16_bf16 v[98:113], v[214:217], v[2:5], v[98:113]
	ds_read_b128 v[236:239], v248 offset:41504
	s_waitcnt vmcnt(15)
	ds_write_b128 v250, v[146:149]
	s_waitcnt lgkmcnt(6)
	v_mfma_f32_32x32x16_bf16 v[50:65], v[210:213], v[6:9], v[50:65]
	ds_read_b128 v[2:5], v248 offset:46112
	v_mfma_f32_32x32x16_bf16 v[66:81], v[214:217], v[6:9], v[66:81]
	global_load_dwordx4 v[146:149], v227, s[74:75] offset:1024 sc0
	s_waitcnt lgkmcnt(6)
	v_mfma_f32_32x32x16_bf16 v[18:33], v[210:213], v[10:13], v[18:33]
	ds_read_b128 v[6:9], v248 offset:50720
	s_waitcnt vmcnt(15)
	ds_write_b128 v251, v[178:181]
	v_mfma_f32_32x32x16_bf16 v[34:49], v[214:217], v[10:13], v[34:49]
	s_waitcnt lgkmcnt(6)
	v_mfma_f32_32x32x16_bf16 v[114:129], v[228:231], v[14:17], v[114:129]
	ds_read_b128 v[210:213], v249 offset:36928
	global_load_dwordx4 v[178:181], v227, s[82:83] offset:1024 sc0
	s_waitcnt lgkmcnt(6)
	v_mfma_f32_32x32x16_bf16 v[130:145], v[232:235], v[14:17], v[130:145]
	ds_read_b128 v[10:13], v248 offset:36928
	s_waitcnt vmcnt(15)
	ds_write_b128 v250, v[150:153] offset:9216
	s_waitcnt lgkmcnt(7)
	v_mfma_f32_32x32x16_bf16 v[82:97], v[228:231], v[236:239], v[82:97]
	ds_read_b128 v[214:217], v249 offset:41536
	v_mfma_f32_32x32x16_bf16 v[98:113], v[232:235], v[236:239], v[98:113]
	ds_read_b128 v[14:17], v248 offset:41536
	global_load_dwordx4 v[150:153], v227, s[76:77] offset:1024 sc0
	s_waitcnt lgkmcnt(7)
	v_mfma_f32_32x32x16_bf16 v[50:65], v[228:231], v[2:5], v[50:65]
	ds_read_b128 v[236:239], v248 offset:46144
	s_waitcnt vmcnt(15)
	ds_write_b128 v251, v[182:185] offset:9216
	v_mfma_f32_32x32x16_bf16 v[66:81], v[232:235], v[2:5], v[66:81]
	s_waitcnt lgkmcnt(8)
	v_mfma_f32_32x32x16_bf16 v[18:33], v[228:231], v[6:9], v[18:33]
	ds_read_b128 v[2:5], v248 offset:50752
	global_load_dwordx4 v[182:185], v227, s[84:85] offset:1024 sc0
	v_mfma_f32_32x32x16_bf16 v[34:49], v[232:235], v[6:9], v[34:49]
	s_waitcnt vmcnt(15)
	ds_write_b128 v250, v[154:157] offset:18432
	s_waitcnt lgkmcnt(7)
	v_mfma_f32_32x32x16_bf16 v[114:129], v[210:213], v[10:13], v[114:129]
	ds_read_b128 v[228:231], v249 offset:36960
	s_waitcnt lgkmcnt(6)
	v_mfma_f32_32x32x16_bf16 v[130:145], v[214:217], v[10:13], v[130:145]
	ds_read_b128 v[6:9], v248 offset:36960
	global_load_dwordx4 v[154:157], v227, s[78:79] offset:1024 sc0
	s_waitcnt lgkmcnt(6)
	v_mfma_f32_32x32x16_bf16 v[82:97], v[210:213], v[14:17], v[82:97]
	ds_read_b128 v[232:235], v249 offset:41568
	s_waitcnt vmcnt(15)
	ds_write_b128 v251, v[186:189] offset:18432
	v_mfma_f32_32x32x16_bf16 v[98:113], v[214:217], v[14:17], v[98:113]
	ds_read_b128 v[10:13], v248 offset:41568
	s_waitcnt lgkmcnt(8)
	v_mfma_f32_32x32x16_bf16 v[50:65], v[210:213], v[236:239], v[50:65]
	ds_read_b128 v[14:17], v248 offset:46176
	global_load_dwordx4 v[186:189], v227, s[86:87] offset:1024 sc0
	v_mfma_f32_32x32x16_bf16 v[66:81], v[214:217], v[236:239], v[66:81]
	s_waitcnt vmcnt(15)
	ds_write_b128 v250, v[158:161] offset:27648
	s_waitcnt lgkmcnt(8)
	v_mfma_f32_32x32x16_bf16 v[18:33], v[210:213], v[2:5], v[18:33]
	ds_read_b128 v[236:239], v248 offset:50784
	v_mfma_f32_32x32x16_bf16 v[34:49], v[214:217], v[2:5], v[34:49]
	global_load_dwordx4 v[158:161], v227, s[80:81] offset:1024 sc0
	s_waitcnt lgkmcnt(6)
	v_mfma_f32_32x32x16_bf16 v[114:129], v[228:231], v[6:9], v[114:129]
	s_waitcnt vmcnt(15)
	ds_write_b128 v251, v[190:193] offset:27648
	s_waitcnt lgkmcnt(6)
	v_mfma_f32_32x32x16_bf16 v[130:145], v[232:235], v[6:9], v[130:145]
	s_waitcnt lgkmcnt(4)
	v_mfma_f32_32x32x16_bf16 v[82:97], v[228:231], v[10:13], v[82:97]
	global_load_dwordx4 v[190:193], v227, s[92:93] offset:1024 sc0
	v_mfma_f32_32x32x16_bf16 v[98:113], v[232:235], v[10:13], v[98:113]
	s_waitcnt lgkmcnt(3)
	v_mfma_f32_32x32x16_bf16 v[50:65], v[228:231], v[14:17], v[50:65]
	v_mfma_f32_32x32x16_bf16 v[66:81], v[232:235], v[14:17], v[66:81]
	s_waitcnt lgkmcnt(1)
	v_mfma_f32_32x32x16_bf16 v[18:33], v[228:231], v[236:239], v[18:33]
	v_mfma_f32_32x32x16_bf16 v[34:49], v[232:235], v[236:239], v[34:49]
	s_waitcnt lgkmcnt(0)
	s_barrier
;     ...
;   for (int kt = 0; kt < nk; ++kt) {
;     __syncthreads();
;     if (kt + 1 < nk) {
;       u16* aw = As0 + ((kt + 1) & 1) * 256 * LD;
;       u16* bw = Bs0 + ((kt + 1) & 1) * 256 * LD;
; #pragma unroll
;       for (int i = 0; i < 4; ++i) { *(u32x4*)(aw + (srow + 64 * i) * LD + skc * 8) = ra[i]; *(u32x4*)(bw + (srow + 64 * i) * LD + skc * 8) = rb[i]; }
;     }
;     if (kt + 2 < nk) {
; #pragma unroll
;       for (int i = 0; i < 4; ++i) { ra[i] = *(const u32x4*)(Ag + (size_t)(64 * i) * K + (kt + 2) * 64); rb[i] = *(const u32x4*)(Bg[i] + (kt + 2) * 64); }
;     }
;     __builtin_amdgcn_sched_barrier(0);
;     const u16* as = As0 + (kt & 1) * 256 * LD + (wr * 128 + l31) * LD + h * 8;
;     const u16* bs = Bs0 + (kt & 1) * 256 * LD + (wc * 64 + l31) * LD + h * 8;
;     if (domma)
; #pragma unroll
;     for (int ks = 0; ks < 4; ++ks) {
;       bf16x8 wf[2], xf[4];
; #pragma unroll
;       for (int ct = 0; ct < 2; ++ct) wf[ct] = *(const bf16x8*)(bs + ct * 32 * LD + ks * 16);
; #pragma unroll
;       for (int tt = 0; tt < 4; ++tt) xf[tt] = *(const bf16x8*)(as + tt * 32 * LD + ks * 16);
; #pragma unroll
;       for (int ct = 0; ct < 2; ++ct)
; #pragma unroll
;         for (int tt = 0; tt < 4; ++tt) acc[ct][tt] = __builtin_amdgcn_mfma_f32_32x32x16_bf16(wf[ct], xf[tt], acc[ct][tt], 0, 0, 0);
;     }
	ds_read_b128 v[210:213], v249
	ds_read_b128 v[236:239], v248
	ds_read_b128 v[214:217], v249 offset:4608
	ds_read_b128 v[2:5], v248 offset:4608
	ds_read_b128 v[6:9], v248 offset:9216
	ds_read_b128 v[10:13], v248 offset:13824
	s_waitcnt lgkmcnt(4)
	v_mfma_f32_32x32x16_bf16 v[114:129], v[210:213], v[236:239], v[114:129]
	ds_read_b128 v[228:231], v249 offset:32
	s_waitcnt lgkmcnt(4)
	v_mfma_f32_32x32x16_bf16 v[130:145], v[214:217], v[236:239], v[130:145]
	ds_read_b128 v[14:17], v248 offset:32
	s_waitcnt lgkmcnt(4)
	v_mfma_f32_32x32x16_bf16 v[82:97], v[210:213], v[2:5], v[82:97]
	ds_read_b128 v[232:235], v249 offset:4640
	v_mfma_f32_32x32x16_bf16 v[98:113], v[214:217], v[2:5], v[98:113]
	ds_read_b128 v[236:239], v248 offset:4640
	s_waitcnt vmcnt(15)
	ds_write_b128 v250, v[162:165] offset:36864
	s_waitcnt lgkmcnt(6)
	v_mfma_f32_32x32x16_bf16 v[50:65], v[210:213], v[6:9], v[50:65]
	ds_read_b128 v[2:5], v248 offset:9248
	v_mfma_f32_32x32x16_bf16 v[66:81], v[214:217], v[6:9], v[66:81]
	global_load_dwordx4 v[162:165], v227, s[74:75] offset:1152 sc0
	s_waitcnt lgkmcnt(6)
	v_mfma_f32_32x32x16_bf16 v[18:33], v[210:213], v[10:13], v[18:33]
	ds_read_b128 v[6:9], v248 offset:13856
	s_waitcnt vmcnt(15)
	ds_write_b128 v251, v[194:197] offset:36864
	v_mfma_f32_32x32x16_bf16 v[34:49], v[214:217], v[10:13], v[34:49]
	s_waitcnt lgkmcnt(6)
	v_mfma_f32_32x32x16_bf16 v[114:129], v[228:231], v[14:17], v[114:129]
	ds_read_b128 v[210:213], v249 offset:64
	global_load_dwordx4 v[194:197], v227, s[82:83] offset:1152 sc0
	s_waitcnt lgkmcnt(6)
	v_mfma_f32_32x32x16_bf16 v[130:145], v[232:235], v[14:17], v[130:145]
	ds_read_b128 v[10:13], v248 offset:64
	s_waitcnt vmcnt(15)
	ds_write_b128 v250, v[166:169] offset:46080
	s_waitcnt lgkmcnt(7)
	v_mfma_f32_32x32x16_bf16 v[82:97], v[228:231], v[236:239], v[82:97]
	ds_read_b128 v[214:217], v249 offset:4672
	v_mfma_f32_32x32x16_bf16 v[98:113], v[232:235], v[236:239], v[98:113]
	ds_read_b128 v[14:17], v248 offset:4672
	global_load_dwordx4 v[166:169], v227, s[76:77] offset:1152 sc0
	s_waitcnt lgkmcnt(7)
	v_mfma_f32_32x32x16_bf16 v[50:65], v[228:231], v[2:5], v[50:65]
	ds_read_b128 v[236:239], v248 offset:9280
	s_waitcnt vmcnt(15)
	ds_write_b128 v251, v[198:201] offset:46080
	v_mfma_f32_32x32x16_bf16 v[66:81], v[232:235], v[2:5], v[66:81]
	s_waitcnt lgkmcnt(8)
	v_mfma_f32_32x32x16_bf16 v[18:33], v[228:231], v[6:9], v[18:33]
	ds_read_b128 v[2:5], v248 offset:13888
	global_load_dwordx4 v[198:201], v227, s[84:85] offset:1152 sc0
	v_mfma_f32_32x32x16_bf16 v[34:49], v[232:235], v[6:9], v[34:49]
	s_waitcnt vmcnt(15)
	ds_write_b128 v250, v[170:173] offset:55296
	s_waitcnt lgkmcnt(7)
	v_mfma_f32_32x32x16_bf16 v[114:129], v[210:213], v[10:13], v[114:129]
	ds_read_b128 v[228:231], v249 offset:96
	s_waitcnt lgkmcnt(6)
	v_mfma_f32_32x32x16_bf16 v[130:145], v[214:217], v[10:13], v[130:145]
	ds_read_b128 v[6:9], v248 offset:96
	global_load_dwordx4 v[170:173], v227, s[78:79] offset:1152 sc0
	s_waitcnt lgkmcnt(6)
	v_mfma_f32_32x32x16_bf16 v[82:97], v[210:213], v[14:17], v[82:97]
	ds_read_b128 v[232:235], v249 offset:4704
	s_waitcnt vmcnt(15)
	ds_write_b128 v251, v[202:205] offset:55296
	v_mfma_f32_32x32x16_bf16 v[98:113], v[214:217], v[14:17], v[98:113]
	ds_read_b128 v[10:13], v248 offset:4704
	s_waitcnt lgkmcnt(8)
	v_mfma_f32_32x32x16_bf16 v[50:65], v[210:213], v[236:239], v[50:65]
	ds_read_b128 v[14:17], v248 offset:9312
	global_load_dwordx4 v[202:205], v227, s[86:87] offset:1152 sc0
	v_mfma_f32_32x32x16_bf16 v[66:81], v[214:217], v[236:239], v[66:81]
	s_waitcnt vmcnt(15)
	ds_write_b128 v250, v[174:177] offset:64512
	s_waitcnt lgkmcnt(8)
	v_mfma_f32_32x32x16_bf16 v[18:33], v[210:213], v[2:5], v[18:33]
	ds_read_b128 v[236:239], v248 offset:13920
	v_mfma_f32_32x32x16_bf16 v[34:49], v[214:217], v[2:5], v[34:49]
	global_load_dwordx4 v[174:177], v227, s[80:81] offset:1152 sc0
	s_waitcnt lgkmcnt(6)
	v_mfma_f32_32x32x16_bf16 v[114:129], v[228:231], v[6:9], v[114:129]
	s_waitcnt vmcnt(15)
	ds_write_b128 v251, v[206:209] offset:64512
	s_waitcnt lgkmcnt(6)
	v_mfma_f32_32x32x16_bf16 v[130:145], v[232:235], v[6:9], v[130:145]
	s_waitcnt lgkmcnt(4)
	v_mfma_f32_32x32x16_bf16 v[82:97], v[228:231], v[10:13], v[82:97]
	global_load_dwordx4 v[206:209], v227, s[92:93] offset:1152 sc0
	v_mfma_f32_32x32x16_bf16 v[98:113], v[232:235], v[10:13], v[98:113]
	s_waitcnt lgkmcnt(3)
	v_mfma_f32_32x32x16_bf16 v[50:65], v[228:231], v[14:17], v[50:65]
	v_mfma_f32_32x32x16_bf16 v[66:81], v[232:235], v[14:17], v[66:81]
	s_waitcnt lgkmcnt(1)
	v_mfma_f32_32x32x16_bf16 v[18:33], v[228:231], v[236:239], v[18:33]
	v_mfma_f32_32x32x16_bf16 v[34:49], v[232:235], v[236:239], v[34:49]
	s_waitcnt lgkmcnt(0)
	s_barrier
;     ...
;   for (int kt = 0; kt < nk; ++kt) {
;     __syncthreads();
;     if (kt + 1 < nk) {
;       u16* aw = As0 + ((kt + 1) & 1) * 256 * LD;
;       u16* bw = Bs0 + ((kt + 1) & 1) * 256 * LD;
; #pragma unroll
;       for (int i = 0; i < 4; ++i) { *(u32x4*)(aw + (srow + 64 * i) * LD + skc * 8) = ra[i]; *(u32x4*)(bw + (srow + 64 * i) * LD + skc * 8) = rb[i]; }
;     }
;     if (kt + 2 < nk) {
; #pragma unroll
;       for (int i = 0; i < 4; ++i) { ra[i] = *(const u32x4*)(Ag + (size_t)(64 * i) * K + (kt + 2) * 64); rb[i] = *(const u32x4*)(Bg[i] + (kt + 2) * 64); }
;     }
;     __builtin_amdgcn_sched_barrier(0);
;     const u16* as = As0 + (kt & 1) * 256 * LD + (wr * 128 + l31) * LD + h * 8;
;     const u16* bs = Bs0 + (kt & 1) * 256 * LD + (wc * 64 + l31) * LD + h * 8;
;     if (domma)
; #pragma unroll
;     for (int ks = 0; ks < 4; ++ks) {
;       bf16x8 wf[2], xf[4];
; #pragma unroll
;       for (int ct = 0; ct < 2; ++ct) wf[ct] = *(const bf16x8*)(bs + ct * 32 * LD + ks * 16);
; #pragma unroll
;       for (int tt = 0; tt < 4; ++tt) xf[tt] = *(const bf16x8*)(as + tt * 32 * LD + ks * 16);
; #pragma unroll
;       for (int ct = 0; ct < 2; ++ct)
; #pragma unroll
;         for (int tt = 0; tt < 4; ++tt) acc[ct][tt] = __builtin_amdgcn_mfma_f32_32x32x16_bf16(wf[ct], xf[tt], acc[ct][tt], 0, 0, 0);
;     }
	ds_read_b128 v[210:213], v249 offset:36864
	ds_read_b128 v[236:239], v248 offset:36864
	ds_read_b128 v[214:217], v249 offset:41472
	ds_read_b128 v[2:5], v248 offset:41472
	ds_read_b128 v[6:9], v248 offset:46080
	ds_read_b128 v[10:13], v248 offset:50688
	s_waitcnt lgkmcnt(4)
	v_mfma_f32_32x32x16_bf16 v[114:129], v[210:213], v[236:239], v[114:129]
	ds_read_b128 v[228:231], v249 offset:36896
	s_waitcnt lgkmcnt(4)
	v_mfma_f32_32x32x16_bf16 v[130:145], v[214:217], v[236:239], v[130:145]
	ds_read_b128 v[14:17], v248 offset:36896
	s_waitcnt lgkmcnt(4)
	v_mfma_f32_32x32x16_bf16 v[82:97], v[210:213], v[2:5], v[82:97]
	ds_read_b128 v[232:235], v249 offset:41504
	v_mfma_f32_32x32x16_bf16 v[98:113], v[214:217], v[2:5], v[98:113]
	ds_read_b128 v[236:239], v248 offset:41504
	s_waitcnt vmcnt(15)
	ds_write_b128 v250, v[146:149]
	s_waitcnt lgkmcnt(6)
	v_mfma_f32_32x32x16_bf16 v[50:65], v[210:213], v[6:9], v[50:65]
	ds_read_b128 v[2:5], v248 offset:46112
	v_mfma_f32_32x32x16_bf16 v[66:81], v[214:217], v[6:9], v[66:81]
	global_load_dwordx4 v[146:149], v227, s[74:75] offset:1280 sc0
	s_waitcnt lgkmcnt(6)
	v_mfma_f32_32x32x16_bf16 v[18:33], v[210:213], v[10:13], v[18:33]
	ds_read_b128 v[6:9], v248 offset:50720
	s_waitcnt vmcnt(15)
	ds_write_b128 v251, v[178:181]
	v_mfma_f32_32x32x16_bf16 v[34:49], v[214:217], v[10:13], v[34:49]
	s_waitcnt lgkmcnt(6)
	v_mfma_f32_32x32x16_bf16 v[114:129], v[228:231], v[14:17], v[114:129]
	ds_read_b128 v[210:213], v249 offset:36928
	global_load_dwordx4 v[178:181], v227, s[82:83] offset:1280 sc0
	s_waitcnt lgkmcnt(6)
	v_mfma_f32_32x32x16_bf16 v[130:145], v[232:235], v[14:17], v[130:145]
	ds_read_b128 v[10:13], v248 offset:36928
	s_waitcnt vmcnt(15)
	ds_write_b128 v250, v[150:153] offset:9216
	s_waitcnt lgkmcnt(7)
	v_mfma_f32_32x32x16_bf16 v[82:97], v[228:231], v[236:239], v[82:97]
	ds_read_b128 v[214:217], v249 offset:41536
	v_mfma_f32_32x32x16_bf16 v[98:113], v[232:235], v[236:239], v[98:113]
	ds_read_b128 v[14:17], v248 offset:41536
	global_load_dwordx4 v[150:153], v227, s[76:77] offset:1280 sc0
	s_waitcnt lgkmcnt(7)
	v_mfma_f32_32x32x16_bf16 v[50:65], v[228:231], v[2:5], v[50:65]
	ds_read_b128 v[236:239], v248 offset:46144
	s_waitcnt vmcnt(15)
	ds_write_b128 v251, v[182:185] offset:9216
	v_mfma_f32_32x32x16_bf16 v[66:81], v[232:235], v[2:5], v[66:81]
	s_waitcnt lgkmcnt(8)
	v_mfma_f32_32x32x16_bf16 v[18:33], v[228:231], v[6:9], v[18:33]
	ds_read_b128 v[2:5], v248 offset:50752
	global_load_dwordx4 v[182:185], v227, s[84:85] offset:1280 sc0
	v_mfma_f32_32x32x16_bf16 v[34:49], v[232:235], v[6:9], v[34:49]
	s_waitcnt vmcnt(15)
	ds_write_b128 v250, v[154:157] offset:18432
	s_waitcnt lgkmcnt(7)
	v_mfma_f32_32x32x16_bf16 v[114:129], v[210:213], v[10:13], v[114:129]
	ds_read_b128 v[228:231], v249 offset:36960
	s_waitcnt lgkmcnt(6)
	v_mfma_f32_32x32x16_bf16 v[130:145], v[214:217], v[10:13], v[130:145]
	ds_read_b128 v[6:9], v248 offset:36960
	global_load_dwordx4 v[154:157], v227, s[78:79] offset:1280 sc0
	s_waitcnt lgkmcnt(6)
	v_mfma_f32_32x32x16_bf16 v[82:97], v[210:213], v[14:17], v[82:97]
	ds_read_b128 v[232:235], v249 offset:41568
	s_waitcnt vmcnt(15)
	ds_write_b128 v251, v[186:189] offset:18432
	v_mfma_f32_32x32x16_bf16 v[98:113], v[214:217], v[14:17], v[98:113]
	ds_read_b128 v[10:13], v248 offset:41568
	s_waitcnt lgkmcnt(8)
	v_mfma_f32_32x32x16_bf16 v[50:65], v[210:213], v[236:239], v[50:65]
	ds_read_b128 v[14:17], v248 offset:46176
	global_load_dwordx4 v[186:189], v227, s[86:87] offset:1280 sc0
	v_mfma_f32_32x32x16_bf16 v[66:81], v[214:217], v[236:239], v[66:81]
	s_waitcnt vmcnt(15)
	ds_write_b128 v250, v[158:161] offset:27648
	s_waitcnt lgkmcnt(8)
	v_mfma_f32_32x32x16_bf16 v[18:33], v[210:213], v[2:5], v[18:33]
	ds_read_b128 v[236:239], v248 offset:50784
	v_mfma_f32_32x32x16_bf16 v[34:49], v[214:217], v[2:5], v[34:49]
	global_load_dwordx4 v[158:161], v227, s[80:81] offset:1280 sc0
	s_waitcnt lgkmcnt(6)
	v_mfma_f32_32x32x16_bf16 v[114:129], v[228:231], v[6:9], v[114:129]
	s_waitcnt vmcnt(15)
	ds_write_b128 v251, v[190:193] offset:27648
	s_waitcnt lgkmcnt(6)
	v_mfma_f32_32x32x16_bf16 v[130:145], v[232:235], v[6:9], v[130:145]
	s_waitcnt lgkmcnt(4)
	v_mfma_f32_32x32x16_bf16 v[82:97], v[228:231], v[10:13], v[82:97]
	global_load_dwordx4 v[190:193], v227, s[92:93] offset:1280 sc0
	v_mfma_f32_32x32x16_bf16 v[98:113], v[232:235], v[10:13], v[98:113]
	s_waitcnt lgkmcnt(3)
	v_mfma_f32_32x32x16_bf16 v[50:65], v[228:231], v[14:17], v[50:65]
	v_mfma_f32_32x32x16_bf16 v[66:81], v[232:235], v[14:17], v[66:81]
	s_waitcnt lgkmcnt(1)
	v_mfma_f32_32x32x16_bf16 v[18:33], v[228:231], v[236:239], v[18:33]
	v_mfma_f32_32x32x16_bf16 v[34:49], v[232:235], v[236:239], v[34:49]
	s_waitcnt lgkmcnt(0)
	s_barrier
;     ...
;   for (int kt = 0; kt < nk; ++kt) {
;     __syncthreads();
;     if (kt + 1 < nk) {
;       u16* aw = As0 + ((kt + 1) & 1) * 256 * LD;
;       u16* bw = Bs0 + ((kt + 1) & 1) * 256 * LD;
; #pragma unroll
;       for (int i = 0; i < 4; ++i) { *(u32x4*)(aw + (srow + 64 * i) * LD + skc * 8) = ra[i]; *(u32x4*)(bw + (srow + 64 * i) * LD + skc * 8) = rb[i]; }
;     }
;     if (kt + 2 < nk) {
; #pragma unroll
;       for (int i = 0; i < 4; ++i) { ra[i] = *(const u32x4*)(Ag + (size_t)(64 * i) * K + (kt + 2) * 64); rb[i] = *(const u32x4*)(Bg[i] + (kt + 2) * 64); }
;     }
;     __builtin_amdgcn_sched_barrier(0);
;     const u16* as = As0 + (kt & 1) * 256 * LD + (wr * 128 + l31) * LD + h * 8;
;     const u16* bs = Bs0 + (kt & 1) * 256 * LD + (wc * 64 + l31) * LD + h * 8;
;     if (domma)
; #pragma unroll
;     for (int ks = 0; ks < 4; ++ks) {
;       bf16x8 wf[2], xf[4];
; #pragma unroll
;       for (int ct = 0; ct < 2; ++ct) wf[ct] = *(const bf16x8*)(bs + ct * 32 * LD + ks * 16);
; #pragma unroll
;       for (int tt = 0; tt < 4; ++tt) xf[tt] = *(const bf16x8*)(as + tt * 32 * LD + ks * 16);
; #pragma unroll
;       for (int ct = 0; ct < 2; ++ct)
; #pragma unroll
;         for (int tt = 0; tt < 4; ++tt) acc[ct][tt] = __builtin_amdgcn_mfma_f32_32x32x16_bf16(wf[ct], xf[tt], acc[ct][tt], 0, 0, 0);
;     }
	ds_read_b128 v[210:213], v249
	ds_read_b128 v[236:239], v248
	ds_read_b128 v[214:217], v249 offset:4608
	ds_read_b128 v[2:5], v248 offset:4608
	ds_read_b128 v[6:9], v248 offset:9216
	ds_read_b128 v[10:13], v248 offset:13824
	s_waitcnt lgkmcnt(4)
	v_mfma_f32_32x32x16_bf16 v[114:129], v[210:213], v[236:239], v[114:129]
	ds_read_b128 v[228:231], v249 offset:32
	s_waitcnt lgkmcnt(4)
	v_mfma_f32_32x32x16_bf16 v[130:145], v[214:217], v[236:239], v[130:145]
	ds_read_b128 v[14:17], v248 offset:32
	s_waitcnt lgkmcnt(4)
	v_mfma_f32_32x32x16_bf16 v[82:97], v[210:213], v[2:5], v[82:97]
	ds_read_b128 v[232:235], v249 offset:4640
	v_mfma_f32_32x32x16_bf16 v[98:113], v[214:217], v[2:5], v[98:113]
	ds_read_b128 v[236:239], v248 offset:4640
	s_waitcnt vmcnt(15)
	ds_write_b128 v250, v[162:165] offset:36864
	s_waitcnt lgkmcnt(6)
	v_mfma_f32_32x32x16_bf16 v[50:65], v[210:213], v[6:9], v[50:65]
	ds_read_b128 v[2:5], v248 offset:9248
	v_mfma_f32_32x32x16_bf16 v[66:81], v[214:217], v[6:9], v[66:81]
	global_load_dwordx4 v[162:165], v227, s[74:75] offset:1408 sc0
	s_waitcnt lgkmcnt(6)
	v_mfma_f32_32x32x16_bf16 v[18:33], v[210:213], v[10:13], v[18:33]
	ds_read_b128 v[6:9], v248 offset:13856
	s_waitcnt vmcnt(15)
	ds_write_b128 v251, v[194:197] offset:36864
	v_mfma_f32_32x32x16_bf16 v[34:49], v[214:217], v[10:13], v[34:49]
	s_waitcnt lgkmcnt(6)
	v_mfma_f32_32x32x16_bf16 v[114:129], v[228:231], v[14:17], v[114:129]
	ds_read_b128 v[210:213], v249 offset:64
	global_load_dwordx4 v[194:197], v227, s[82:83] offset:1408 sc0
	s_waitcnt lgkmcnt(6)
	v_mfma_f32_32x32x16_bf16 v[130:145], v[232:235], v[14:17], v[130:145]
	ds_read_b128 v[10:13], v248 offset:64
	s_waitcnt vmcnt(15)
	ds_write_b128 v250, v[166:169] offset:46080
	s_waitcnt lgkmcnt(7)
	v_mfma_f32_32x32x16_bf16 v[82:97], v[228:231], v[236:239], v[82:97]
	ds_read_b128 v[214:217], v249 offset:4672
	v_mfma_f32_32x32x16_bf16 v[98:113], v[232:235], v[236:239], v[98:113]
	ds_read_b128 v[14:17], v248 offset:4672
	global_load_dwordx4 v[166:169], v227, s[76:77] offset:1408 sc0
	s_waitcnt lgkmcnt(7)
	v_mfma_f32_32x32x16_bf16 v[50:65], v[228:231], v[2:5], v[50:65]
	ds_read_b128 v[236:239], v248 offset:9280
	s_waitcnt vmcnt(15)
	ds_write_b128 v251, v[198:201] offset:46080
	v_mfma_f32_32x32x16_bf16 v[66:81], v[232:235], v[2:5], v[66:81]
	s_waitcnt lgkmcnt(8)
	v_mfma_f32_32x32x16_bf16 v[18:33], v[228:231], v[6:9], v[18:33]
	ds_read_b128 v[2:5], v248 offset:13888
	global_load_dwordx4 v[198:201], v227, s[84:85] offset:1408 sc0
	v_mfma_f32_32x32x16_bf16 v[34:49], v[232:235], v[6:9], v[34:49]
	s_waitcnt vmcnt(15)
	ds_write_b128 v250, v[170:173] offset:55296
	s_waitcnt lgkmcnt(7)
	v_mfma_f32_32x32x16_bf16 v[114:129], v[210:213], v[10:13], v[114:129]
	ds_read_b128 v[228:231], v249 offset:96
	s_waitcnt lgkmcnt(6)
	v_mfma_f32_32x32x16_bf16 v[130:145], v[214:217], v[10:13], v[130:145]
	ds_read_b128 v[6:9], v248 offset:96
	global_load_dwordx4 v[170:173], v227, s[78:79] offset:1408 sc0
	s_waitcnt lgkmcnt(6)
	v_mfma_f32_32x32x16_bf16 v[82:97], v[210:213], v[14:17], v[82:97]
	ds_read_b128 v[232:235], v249 offset:4704
	s_waitcnt vmcnt(15)
	ds_write_b128 v251, v[202:205] offset:55296
	v_mfma_f32_32x32x16_bf16 v[98:113], v[214:217], v[14:17], v[98:113]
	ds_read_b128 v[10:13], v248 offset:4704
	s_waitcnt lgkmcnt(8)
	v_mfma_f32_32x32x16_bf16 v[50:65], v[210:213], v[236:239], v[50:65]
	ds_read_b128 v[14:17], v248 offset:9312
	global_load_dwordx4 v[202:205], v227, s[86:87] offset:1408 sc0
	v_mfma_f32_32x32x16_bf16 v[66:81], v[214:217], v[236:239], v[66:81]
	s_waitcnt vmcnt(15)
	ds_write_b128 v250, v[174:177] offset:64512
	s_waitcnt lgkmcnt(8)
	v_mfma_f32_32x32x16_bf16 v[18:33], v[210:213], v[2:5], v[18:33]
	ds_read_b128 v[236:239], v248 offset:13920
	v_mfma_f32_32x32x16_bf16 v[34:49], v[214:217], v[2:5], v[34:49]
	global_load_dwordx4 v[174:177], v227, s[80:81] offset:1408 sc0
	s_waitcnt lgkmcnt(6)
	v_mfma_f32_32x32x16_bf16 v[114:129], v[228:231], v[6:9], v[114:129]
	s_waitcnt vmcnt(15)
	ds_write_b128 v251, v[206:209] offset:64512
	s_waitcnt lgkmcnt(6)
	v_mfma_f32_32x32x16_bf16 v[130:145], v[232:235], v[6:9], v[130:145]
	s_waitcnt lgkmcnt(4)
	v_mfma_f32_32x32x16_bf16 v[82:97], v[228:231], v[10:13], v[82:97]
	global_load_dwordx4 v[206:209], v227, s[92:93] offset:1408 sc0
	v_mfma_f32_32x32x16_bf16 v[98:113], v[232:235], v[10:13], v[98:113]
	s_waitcnt lgkmcnt(3)
	v_mfma_f32_32x32x16_bf16 v[50:65], v[228:231], v[14:17], v[50:65]
	v_mfma_f32_32x32x16_bf16 v[66:81], v[232:235], v[14:17], v[66:81]
	s_waitcnt lgkmcnt(1)
	v_mfma_f32_32x32x16_bf16 v[18:33], v[228:231], v[236:239], v[18:33]
	v_mfma_f32_32x32x16_bf16 v[34:49], v[232:235], v[236:239], v[34:49]
	s_waitcnt lgkmcnt(0)
	s_barrier
;     ...
;   for (int kt = 0; kt < nk; ++kt) {
;     __syncthreads();
;     if (kt + 1 < nk) {
;       u16* aw = As0 + ((kt + 1) & 1) * 256 * LD;
;       u16* bw = Bs0 + ((kt + 1) & 1) * 256 * LD;
; #pragma unroll
;       for (int i = 0; i < 4; ++i) { *(u32x4*)(aw + (srow + 64 * i) * LD + skc * 8) = ra[i]; *(u32x4*)(bw + (srow + 64 * i) * LD + skc * 8) = rb[i]; }
;     }
;     if (kt + 2 < nk) {
; #pragma unroll
;       for (int i = 0; i < 4; ++i) { ra[i] = *(const u32x4*)(Ag + (size_t)(64 * i) * K + (kt + 2) * 64); rb[i] = *(const u32x4*)(Bg[i] + (kt + 2) * 64); }
;     }
;     __builtin_amdgcn_sched_barrier(0);
;     const u16* as = As0 + (kt & 1) * 256 * LD + (wr * 128 + l31) * LD + h * 8;
;     const u16* bs = Bs0 + (kt & 1) * 256 * LD + (wc * 64 + l31) * LD + h * 8;
;     if (domma)
; #pragma unroll
;     for (int ks = 0; ks < 4; ++ks) {
;       bf16x8 wf[2], xf[4];
; #pragma unroll
;       for (int ct = 0; ct < 2; ++ct) wf[ct] = *(const bf16x8*)(bs + ct * 32 * LD + ks * 16);
; #pragma unroll
;       for (int tt = 0; tt < 4; ++tt) xf[tt] = *(const bf16x8*)(as + tt * 32 * LD + ks * 16);
; #pragma unroll
;       for (int ct = 0; ct < 2; ++ct)
; #pragma unroll
;         for (int tt = 0; tt < 4; ++tt) acc[ct][tt] = __builtin_amdgcn_mfma_f32_32x32x16_bf16(wf[ct], xf[tt], acc[ct][tt], 0, 0, 0);
;     }
	ds_read_b128 v[210:213], v249 offset:36864
	ds_read_b128 v[236:239], v248 offset:36864
	ds_read_b128 v[214:217], v249 offset:41472
	ds_read_b128 v[2:5], v248 offset:41472
	ds_read_b128 v[6:9], v248 offset:46080
	ds_read_b128 v[10:13], v248 offset:50688
	s_waitcnt lgkmcnt(4)
	v_mfma_f32_32x32x16_bf16 v[114:129], v[210:213], v[236:239], v[114:129]
	ds_read_b128 v[228:231], v249 offset:36896
	s_waitcnt lgkmcnt(4)
	v_mfma_f32_32x32x16_bf16 v[130:145], v[214:217], v[236:239], v[130:145]
	ds_read_b128 v[14:17], v248 offset:36896
	s_waitcnt lgkmcnt(4)
	v_mfma_f32_32x32x16_bf16 v[82:97], v[210:213], v[2:5], v[82:97]
	ds_read_b128 v[232:235], v249 offset:41504
	v_mfma_f32_32x32x16_bf16 v[98:113], v[214:217], v[2:5], v[98:113]
	ds_read_b128 v[236:239], v248 offset:41504
	s_waitcnt vmcnt(15)
	ds_write_b128 v250, v[146:149]
	s_waitcnt lgkmcnt(6)
	v_mfma_f32_32x32x16_bf16 v[50:65], v[210:213], v[6:9], v[50:65]
	ds_read_b128 v[2:5], v248 offset:46112
	v_mfma_f32_32x32x16_bf16 v[66:81], v[214:217], v[6:9], v[66:81]
	global_load_dwordx4 v[146:149], v227, s[74:75] offset:1536 sc0
	s_waitcnt lgkmcnt(6)
	v_mfma_f32_32x32x16_bf16 v[18:33], v[210:213], v[10:13], v[18:33]
	ds_read_b128 v[6:9], v248 offset:50720
	s_waitcnt vmcnt(15)
	ds_write_b128 v251, v[178:181]
	v_mfma_f32_32x32x16_bf16 v[34:49], v[214:217], v[10:13], v[34:49]
	s_waitcnt lgkmcnt(6)
	v_mfma_f32_32x32x16_bf16 v[114:129], v[228:231], v[14:17], v[114:129]
	ds_read_b128 v[210:213], v249 offset:36928
	global_load_dwordx4 v[178:181], v227, s[82:83] offset:1536 sc0
	s_waitcnt lgkmcnt(6)
	v_mfma_f32_32x32x16_bf16 v[130:145], v[232:235], v[14:17], v[130:145]
	ds_read_b128 v[10:13], v248 offset:36928
	s_waitcnt vmcnt(15)
	ds_write_b128 v250, v[150:153] offset:9216
	s_waitcnt lgkmcnt(7)
	v_mfma_f32_32x32x16_bf16 v[82:97], v[228:231], v[236:239], v[82:97]
	ds_read_b128 v[214:217], v249 offset:41536
	v_mfma_f32_32x32x16_bf16 v[98:113], v[232:235], v[236:239], v[98:113]
	ds_read_b128 v[14:17], v248 offset:41536
	global_load_dwordx4 v[150:153], v227, s[76:77] offset:1536 sc0
	s_waitcnt lgkmcnt(7)
	v_mfma_f32_32x32x16_bf16 v[50:65], v[228:231], v[2:5], v[50:65]
	ds_read_b128 v[236:239], v248 offset:46144
	s_waitcnt vmcnt(15)
	ds_write_b128 v251, v[182:185] offset:9216
	v_mfma_f32_32x32x16_bf16 v[66:81], v[232:235], v[2:5], v[66:81]
	s_waitcnt lgkmcnt(8)
	v_mfma_f32_32x32x16_bf16 v[18:33], v[228:231], v[6:9], v[18:33]
	ds_read_b128 v[2:5], v248 offset:50752
	global_load_dwordx4 v[182:185], v227, s[84:85] offset:1536 sc0
	v_mfma_f32_32x32x16_bf16 v[34:49], v[232:235], v[6:9], v[34:49]
	s_waitcnt vmcnt(15)
	ds_write_b128 v250, v[154:157] offset:18432
	s_waitcnt lgkmcnt(7)
	v_mfma_f32_32x32x16_bf16 v[114:129], v[210:213], v[10:13], v[114:129]
	ds_read_b128 v[228:231], v249 offset:36960
	s_waitcnt lgkmcnt(6)
	v_mfma_f32_32x32x16_bf16 v[130:145], v[214:217], v[10:13], v[130:145]
	ds_read_b128 v[6:9], v248 offset:36960
	global_load_dwordx4 v[154:157], v227, s[78:79] offset:1536 sc0
	s_waitcnt lgkmcnt(6)
	v_mfma_f32_32x32x16_bf16 v[82:97], v[210:213], v[14:17], v[82:97]
	ds_read_b128 v[232:235], v249 offset:41568
	s_waitcnt vmcnt(15)
	ds_write_b128 v251, v[186:189] offset:18432
	v_mfma_f32_32x32x16_bf16 v[98:113], v[214:217], v[14:17], v[98:113]
	ds_read_b128 v[10:13], v248 offset:41568
	s_waitcnt lgkmcnt(8)
	v_mfma_f32_32x32x16_bf16 v[50:65], v[210:213], v[236:239], v[50:65]
	ds_read_b128 v[14:17], v248 offset:46176
	global_load_dwordx4 v[186:189], v227, s[86:87] offset:1536 sc0
	v_mfma_f32_32x32x16_bf16 v[66:81], v[214:217], v[236:239], v[66:81]
	s_waitcnt vmcnt(15)
	ds_write_b128 v250, v[158:161] offset:27648
	s_waitcnt lgkmcnt(8)
	v_mfma_f32_32x32x16_bf16 v[18:33], v[210:213], v[2:5], v[18:33]
	ds_read_b128 v[236:239], v248 offset:50784
	v_mfma_f32_32x32x16_bf16 v[34:49], v[214:217], v[2:5], v[34:49]
	global_load_dwordx4 v[158:161], v227, s[80:81] offset:1536 sc0
	s_waitcnt lgkmcnt(6)
	v_mfma_f32_32x32x16_bf16 v[114:129], v[228:231], v[6:9], v[114:129]
	s_waitcnt vmcnt(15)
	ds_write_b128 v251, v[190:193] offset:27648
	s_waitcnt lgkmcnt(6)
	v_mfma_f32_32x32x16_bf16 v[130:145], v[232:235], v[6:9], v[130:145]
	s_waitcnt lgkmcnt(4)
	v_mfma_f32_32x32x16_bf16 v[82:97], v[228:231], v[10:13], v[82:97]
	global_load_dwordx4 v[190:193], v227, s[92:93] offset:1536 sc0
	v_mfma_f32_32x32x16_bf16 v[98:113], v[232:235], v[10:13], v[98:113]
	s_waitcnt lgkmcnt(3)
	v_mfma_f32_32x32x16_bf16 v[50:65], v[228:231], v[14:17], v[50:65]
	v_mfma_f32_32x32x16_bf16 v[66:81], v[232:235], v[14:17], v[66:81]
	s_waitcnt lgkmcnt(1)
	v_mfma_f32_32x32x16_bf16 v[18:33], v[228:231], v[236:239], v[18:33]
	v_mfma_f32_32x32x16_bf16 v[34:49], v[232:235], v[236:239], v[34:49]
	s_waitcnt lgkmcnt(0)
	s_barrier
;     ...
;   for (int kt = 0; kt < nk; ++kt) {
;     __syncthreads();
;     if (kt + 1 < nk) {
;       u16* aw = As0 + ((kt + 1) & 1) * 256 * LD;
;       u16* bw = Bs0 + ((kt + 1) & 1) * 256 * LD;
; #pragma unroll
;       for (int i = 0; i < 4; ++i) { *(u32x4*)(aw + (srow + 64 * i) * LD + skc * 8) = ra[i]; *(u32x4*)(bw + (srow + 64 * i) * LD + skc * 8) = rb[i]; }
;     }
;     if (kt + 2 < nk) {
; #pragma unroll
;       for (int i = 0; i < 4; ++i) { ra[i] = *(const u32x4*)(Ag + (size_t)(64 * i) * K + (kt + 2) * 64); rb[i] = *(const u32x4*)(Bg[i] + (kt + 2) * 64); }
;     }
;     __builtin_amdgcn_sched_barrier(0);
;     const u16* as = As0 + (kt & 1) * 256 * LD + (wr * 128 + l31) * LD + h * 8;
;     const u16* bs = Bs0 + (kt & 1) * 256 * LD + (wc * 64 + l31) * LD + h * 8;
;     if (domma)
; #pragma unroll
;     for (int ks = 0; ks < 4; ++ks) {
;       bf16x8 wf[2], xf[4];
; #pragma unroll
;       for (int ct = 0; ct < 2; ++ct) wf[ct] = *(const bf16x8*)(bs + ct * 32 * LD + ks * 16);
; #pragma unroll
;       for (int tt = 0; tt < 4; ++tt) xf[tt] = *(const bf16x8*)(as + tt * 32 * LD + ks * 16);
; #pragma unroll
;       for (int ct = 0; ct < 2; ++ct)
; #pragma unroll
;         for (int tt = 0; tt < 4; ++tt) acc[ct][tt] = __builtin_amdgcn_mfma_f32_32x32x16_bf16(wf[ct], xf[tt], acc[ct][tt], 0, 0, 0);
;     }
	ds_read_b128 v[210:213], v249
	ds_read_b128 v[236:239], v248
	ds_read_b128 v[214:217], v249 offset:4608
	ds_read_b128 v[2:5], v248 offset:4608
	ds_read_b128 v[6:9], v248 offset:9216
	ds_read_b128 v[10:13], v248 offset:13824
	s_waitcnt lgkmcnt(4)
	v_mfma_f32_32x32x16_bf16 v[114:129], v[210:213], v[236:239], v[114:129]
	ds_read_b128 v[228:231], v249 offset:32
	s_waitcnt lgkmcnt(4)
	v_mfma_f32_32x32x16_bf16 v[130:145], v[214:217], v[236:239], v[130:145]
	ds_read_b128 v[14:17], v248 offset:32
	s_waitcnt lgkmcnt(4)
	v_mfma_f32_32x32x16_bf16 v[82:97], v[210:213], v[2:5], v[82:97]
	ds_read_b128 v[232:235], v249 offset:4640
	v_mfma_f32_32x32x16_bf16 v[98:113], v[214:217], v[2:5], v[98:113]
	ds_read_b128 v[236:239], v248 offset:4640
	s_waitcnt vmcnt(15)
	ds_write_b128 v250, v[162:165] offset:36864
	s_waitcnt lgkmcnt(6)
	v_mfma_f32_32x32x16_bf16 v[50:65], v[210:213], v[6:9], v[50:65]
	ds_read_b128 v[2:5], v248 offset:9248
	v_mfma_f32_32x32x16_bf16 v[66:81], v[214:217], v[6:9], v[66:81]
	global_load_dwordx4 v[162:165], v227, s[74:75] offset:1664 sc0
	s_waitcnt lgkmcnt(6)
	v_mfma_f32_32x32x16_bf16 v[18:33], v[210:213], v[10:13], v[18:33]
	ds_read_b128 v[6:9], v248 offset:13856
	s_waitcnt vmcnt(15)
	ds_write_b128 v251, v[194:197] offset:36864
	v_mfma_f32_32x32x16_bf16 v[34:49], v[214:217], v[10:13], v[34:49]
	s_waitcnt lgkmcnt(6)
	v_mfma_f32_32x32x16_bf16 v[114:129], v[228:231], v[14:17], v[114:129]
	ds_read_b128 v[210:213], v249 offset:64
	global_load_dwordx4 v[194:197], v227, s[82:83] offset:1664 sc0
	s_waitcnt lgkmcnt(6)
	v_mfma_f32_32x32x16_bf16 v[130:145], v[232:235], v[14:17], v[130:145]
	ds_read_b128 v[10:13], v248 offset:64
	s_waitcnt vmcnt(15)
	ds_write_b128 v250, v[166:169] offset:46080
	s_waitcnt lgkmcnt(7)
	v_mfma_f32_32x32x16_bf16 v[82:97], v[228:231], v[236:239], v[82:97]
	ds_read_b128 v[214:217], v249 offset:4672
	v_mfma_f32_32x32x16_bf16 v[98:113], v[232:235], v[236:239], v[98:113]
	ds_read_b128 v[14:17], v248 offset:4672
	global_load_dwordx4 v[166:169], v227, s[76:77] offset:1664 sc0
	s_waitcnt lgkmcnt(7)
	v_mfma_f32_32x32x16_bf16 v[50:65], v[228:231], v[2:5], v[50:65]
	ds_read_b128 v[236:239], v248 offset:9280
	s_waitcnt vmcnt(15)
	ds_write_b128 v251, v[198:201] offset:46080
	v_mfma_f32_32x32x16_bf16 v[66:81], v[232:235], v[2:5], v[66:81]
	s_waitcnt lgkmcnt(8)
	v_mfma_f32_32x32x16_bf16 v[18:33], v[228:231], v[6:9], v[18:33]
	ds_read_b128 v[2:5], v248 offset:13888
	global_load_dwordx4 v[198:201], v227, s[84:85] offset:1664 sc0
	v_mfma_f32_32x32x16_bf16 v[34:49], v[232:235], v[6:9], v[34:49]
	s_waitcnt vmcnt(15)
	ds_write_b128 v250, v[170:173] offset:55296
	s_waitcnt lgkmcnt(7)
	v_mfma_f32_32x32x16_bf16 v[114:129], v[210:213], v[10:13], v[114:129]
	ds_read_b128 v[228:231], v249 offset:96
	s_waitcnt lgkmcnt(6)
	v_mfma_f32_32x32x16_bf16 v[130:145], v[214:217], v[10:13], v[130:145]
	ds_read_b128 v[6:9], v248 offset:96
	global_load_dwordx4 v[170:173], v227, s[78:79] offset:1664 sc0
	s_waitcnt lgkmcnt(6)
	v_mfma_f32_32x32x16_bf16 v[82:97], v[210:213], v[14:17], v[82:97]
	ds_read_b128 v[232:235], v249 offset:4704
	s_waitcnt vmcnt(15)
	ds_write_b128 v251, v[202:205] offset:55296
	v_mfma_f32_32x32x16_bf16 v[98:113], v[214:217], v[14:17], v[98:113]
	ds_read_b128 v[10:13], v248 offset:4704
	s_waitcnt lgkmcnt(8)
	v_mfma_f32_32x32x16_bf16 v[50:65], v[210:213], v[236:239], v[50:65]
	ds_read_b128 v[14:17], v248 offset:9312
	global_load_dwordx4 v[202:205], v227, s[86:87] offset:1664 sc0
	v_mfma_f32_32x32x16_bf16 v[66:81], v[214:217], v[236:239], v[66:81]
	s_waitcnt vmcnt(15)
	ds_write_b128 v250, v[174:177] offset:64512
	s_waitcnt lgkmcnt(8)
	v_mfma_f32_32x32x16_bf16 v[18:33], v[210:213], v[2:5], v[18:33]
	ds_read_b128 v[236:239], v248 offset:13920
	v_mfma_f32_32x32x16_bf16 v[34:49], v[214:217], v[2:5], v[34:49]
	global_load_dwordx4 v[174:177], v227, s[80:81] offset:1664 sc0
	s_waitcnt lgkmcnt(6)
	v_mfma_f32_32x32x16_bf16 v[114:129], v[228:231], v[6:9], v[114:129]
	s_waitcnt vmcnt(15)
	ds_write_b128 v251, v[206:209] offset:64512
	s_waitcnt lgkmcnt(6)
	v_mfma_f32_32x32x16_bf16 v[130:145], v[232:235], v[6:9], v[130:145]
	s_waitcnt lgkmcnt(4)
	v_mfma_f32_32x32x16_bf16 v[82:97], v[228:231], v[10:13], v[82:97]
	global_load_dwordx4 v[206:209], v227, s[92:93] offset:1664 sc0
	v_mfma_f32_32x32x16_bf16 v[98:113], v[232:235], v[10:13], v[98:113]
	s_waitcnt lgkmcnt(3)
	v_mfma_f32_32x32x16_bf16 v[50:65], v[228:231], v[14:17], v[50:65]
	v_mfma_f32_32x32x16_bf16 v[66:81], v[232:235], v[14:17], v[66:81]
	s_waitcnt lgkmcnt(1)
	v_mfma_f32_32x32x16_bf16 v[18:33], v[228:231], v[236:239], v[18:33]
	v_mfma_f32_32x32x16_bf16 v[34:49], v[232:235], v[236:239], v[34:49]
	s_waitcnt lgkmcnt(0)
	s_barrier
;     ...
;   for (int kt = 0; kt < nk; ++kt) {
;     __syncthreads();
;     if (kt + 1 < nk) {
;       u16* aw = As0 + ((kt + 1) & 1) * 256 * LD;
;       u16* bw = Bs0 + ((kt + 1) & 1) * 256 * LD;
; #pragma unroll
;       for (int i = 0; i < 4; ++i) { *(u32x4*)(aw + (srow + 64 * i) * LD + skc * 8) = ra[i]; *(u32x4*)(bw + (srow + 64 * i) * LD + skc * 8) = rb[i]; }
;     }
;     if (kt + 2 < nk) {
; #pragma unroll
;       for (int i = 0; i < 4; ++i) { ra[i] = *(const u32x4*)(Ag + (size_t)(64 * i) * K + (kt + 2) * 64); rb[i] = *(const u32x4*)(Bg[i] + (kt + 2) * 64); }
;     }
;     __builtin_amdgcn_sched_barrier(0);
;     const u16* as = As0 + (kt & 1) * 256 * LD + (wr * 128 + l31) * LD + h * 8;
;     const u16* bs = Bs0 + (kt & 1) * 256 * LD + (wc * 64 + l31) * LD + h * 8;
;     if (domma)
; #pragma unroll
;     for (int ks = 0; ks < 4; ++ks) {
;       bf16x8 wf[2], xf[4];
; #pragma unroll
;       for (int ct = 0; ct < 2; ++ct) wf[ct] = *(const bf16x8*)(bs + ct * 32 * LD + ks * 16);
; #pragma unroll
;       for (int tt = 0; tt < 4; ++tt) xf[tt] = *(const bf16x8*)(as + tt * 32 * LD + ks * 16);
; #pragma unroll
;       for (int ct = 0; ct < 2; ++ct)
; #pragma unroll
;         for (int tt = 0; tt < 4; ++tt) acc[ct][tt] = __builtin_amdgcn_mfma_f32_32x32x16_bf16(wf[ct], xf[tt], acc[ct][tt], 0, 0, 0);
;     }
	ds_read_b128 v[210:213], v249 offset:36864
	ds_read_b128 v[236:239], v248 offset:36864
	ds_read_b128 v[214:217], v249 offset:41472
	ds_read_b128 v[2:5], v248 offset:41472
	ds_read_b128 v[6:9], v248 offset:46080
	ds_read_b128 v[10:13], v248 offset:50688
	s_waitcnt lgkmcnt(4)
	v_mfma_f32_32x32x16_bf16 v[114:129], v[210:213], v[236:239], v[114:129]
	ds_read_b128 v[228:231], v249 offset:36896
	s_waitcnt lgkmcnt(4)
	v_mfma_f32_32x32x16_bf16 v[130:145], v[214:217], v[236:239], v[130:145]
	ds_read_b128 v[14:17], v248 offset:36896
	s_waitcnt lgkmcnt(4)
	v_mfma_f32_32x32x16_bf16 v[82:97], v[210:213], v[2:5], v[82:97]
	ds_read_b128 v[232:235], v249 offset:41504
	v_mfma_f32_32x32x16_bf16 v[98:113], v[214:217], v[2:5], v[98:113]
	ds_read_b128 v[236:239], v248 offset:41504
	s_waitcnt vmcnt(15)
	ds_write_b128 v250, v[146:149]
	s_waitcnt lgkmcnt(6)
	v_mfma_f32_32x32x16_bf16 v[50:65], v[210:213], v[6:9], v[50:65]
	ds_read_b128 v[2:5], v248 offset:46112
	v_mfma_f32_32x32x16_bf16 v[66:81], v[214:217], v[6:9], v[66:81]
	global_load_dwordx4 v[146:149], v227, s[74:75] offset:1792 sc0
	s_waitcnt lgkmcnt(6)
	v_mfma_f32_32x32x16_bf16 v[18:33], v[210:213], v[10:13], v[18:33]
	ds_read_b128 v[6:9], v248 offset:50720
	s_waitcnt vmcnt(15)
	ds_write_b128 v251, v[178:181]
	v_mfma_f32_32x32x16_bf16 v[34:49], v[214:217], v[10:13], v[34:49]
	s_waitcnt lgkmcnt(6)
	v_mfma_f32_32x32x16_bf16 v[114:129], v[228:231], v[14:17], v[114:129]
	ds_read_b128 v[210:213], v249 offset:36928
	global_load_dwordx4 v[178:181], v227, s[82:83] offset:1792 sc0
	s_waitcnt lgkmcnt(6)
	v_mfma_f32_32x32x16_bf16 v[130:145], v[232:235], v[14:17], v[130:145]
	ds_read_b128 v[10:13], v248 offset:36928
	s_waitcnt vmcnt(15)
	ds_write_b128 v250, v[150:153] offset:9216
	s_waitcnt lgkmcnt(7)
	v_mfma_f32_32x32x16_bf16 v[82:97], v[228:231], v[236:239], v[82:97]
	ds_read_b128 v[214:217], v249 offset:41536
	v_mfma_f32_32x32x16_bf16 v[98:113], v[232:235], v[236:239], v[98:113]
	ds_read_b128 v[14:17], v248 offset:41536
	global_load_dwordx4 v[150:153], v227, s[76:77] offset:1792 sc0
	s_waitcnt lgkmcnt(7)
	v_mfma_f32_32x32x16_bf16 v[50:65], v[228:231], v[2:5], v[50:65]
	ds_read_b128 v[236:239], v248 offset:46144
	s_waitcnt vmcnt(15)
	ds_write_b128 v251, v[182:185] offset:9216
	v_mfma_f32_32x32x16_bf16 v[66:81], v[232:235], v[2:5], v[66:81]
	s_waitcnt lgkmcnt(8)
	v_mfma_f32_32x32x16_bf16 v[18:33], v[228:231], v[6:9], v[18:33]
	ds_read_b128 v[2:5], v248 offset:50752
	global_load_dwordx4 v[182:185], v227, s[84:85] offset:1792 sc0
	v_mfma_f32_32x32x16_bf16 v[34:49], v[232:235], v[6:9], v[34:49]
	s_waitcnt vmcnt(15)
	ds_write_b128 v250, v[154:157] offset:18432
	s_waitcnt lgkmcnt(7)
	v_mfma_f32_32x32x16_bf16 v[114:129], v[210:213], v[10:13], v[114:129]
	ds_read_b128 v[228:231], v249 offset:36960
	s_waitcnt lgkmcnt(6)
	v_mfma_f32_32x32x16_bf16 v[130:145], v[214:217], v[10:13], v[130:145]
	ds_read_b128 v[6:9], v248 offset:36960
	global_load_dwordx4 v[154:157], v227, s[78:79] offset:1792 sc0
	s_waitcnt lgkmcnt(6)
	v_mfma_f32_32x32x16_bf16 v[82:97], v[210:213], v[14:17], v[82:97]
	ds_read_b128 v[232:235], v249 offset:41568
	s_waitcnt vmcnt(15)
	ds_write_b128 v251, v[186:189] offset:18432
	v_mfma_f32_32x32x16_bf16 v[98:113], v[214:217], v[14:17], v[98:113]
	ds_read_b128 v[10:13], v248 offset:41568
	s_waitcnt lgkmcnt(8)
	v_mfma_f32_32x32x16_bf16 v[50:65], v[210:213], v[236:239], v[50:65]
	ds_read_b128 v[14:17], v248 offset:46176
	global_load_dwordx4 v[186:189], v227, s[86:87] offset:1792 sc0
	v_mfma_f32_32x32x16_bf16 v[66:81], v[214:217], v[236:239], v[66:81]
	s_waitcnt vmcnt(15)
	ds_write_b128 v250, v[158:161] offset:27648
	s_waitcnt lgkmcnt(8)
	v_mfma_f32_32x32x16_bf16 v[18:33], v[210:213], v[2:5], v[18:33]
	ds_read_b128 v[236:239], v248 offset:50784
	v_mfma_f32_32x32x16_bf16 v[34:49], v[214:217], v[2:5], v[34:49]
	global_load_dwordx4 v[158:161], v227, s[80:81] offset:1792 sc0
	s_waitcnt lgkmcnt(6)
	v_mfma_f32_32x32x16_bf16 v[114:129], v[228:231], v[6:9], v[114:129]
	s_waitcnt vmcnt(15)
	ds_write_b128 v251, v[190:193] offset:27648
	s_waitcnt lgkmcnt(6)
	v_mfma_f32_32x32x16_bf16 v[130:145], v[232:235], v[6:9], v[130:145]
	s_waitcnt lgkmcnt(4)
	v_mfma_f32_32x32x16_bf16 v[82:97], v[228:231], v[10:13], v[82:97]
	global_load_dwordx4 v[190:193], v227, s[92:93] offset:1792 sc0
	v_mfma_f32_32x32x16_bf16 v[98:113], v[232:235], v[10:13], v[98:113]
	s_waitcnt lgkmcnt(3)
	v_mfma_f32_32x32x16_bf16 v[50:65], v[228:231], v[14:17], v[50:65]
	v_mfma_f32_32x32x16_bf16 v[66:81], v[232:235], v[14:17], v[66:81]
	s_waitcnt lgkmcnt(1)
	v_mfma_f32_32x32x16_bf16 v[18:33], v[228:231], v[236:239], v[18:33]
	v_mfma_f32_32x32x16_bf16 v[34:49], v[232:235], v[236:239], v[34:49]
	s_waitcnt lgkmcnt(0)
	s_barrier
;     ...
;   for (int kt = 0; kt < nk; ++kt) {
;     __syncthreads();
;     if (kt + 1 < nk) {
;       u16* aw = As0 + ((kt + 1) & 1) * 256 * LD;
;       u16* bw = Bs0 + ((kt + 1) & 1) * 256 * LD;
; #pragma unroll
;       for (int i = 0; i < 4; ++i) { *(u32x4*)(aw + (srow + 64 * i) * LD + skc * 8) = ra[i]; *(u32x4*)(bw + (srow + 64 * i) * LD + skc * 8) = rb[i]; }
;     }
;     if (kt + 2 < nk) {
; #pragma unroll
;       for (int i = 0; i < 4; ++i) { ra[i] = *(const u32x4*)(Ag + (size_t)(64 * i) * K + (kt + 2) * 64); rb[i] = *(const u32x4*)(Bg[i] + (kt + 2) * 64); }
;     }
;     __builtin_amdgcn_sched_barrier(0);
;     const u16* as = As0 + (kt & 1) * 256 * LD + (wr * 128 + l31) * LD + h * 8;
;     const u16* bs = Bs0 + (kt & 1) * 256 * LD + (wc * 64 + l31) * LD + h * 8;
;     if (domma)
; #pragma unroll
;     for (int ks = 0; ks < 4; ++ks) {
;       bf16x8 wf[2], xf[4];
; #pragma unroll
;       for (int ct = 0; ct < 2; ++ct) wf[ct] = *(const bf16x8*)(bs + ct * 32 * LD + ks * 16);
; #pragma unroll
;       for (int tt = 0; tt < 4; ++tt) xf[tt] = *(const bf16x8*)(as + tt * 32 * LD + ks * 16);
; #pragma unroll
;       for (int ct = 0; ct < 2; ++ct)
; #pragma unroll
;         for (int tt = 0; tt < 4; ++tt) acc[ct][tt] = __builtin_amdgcn_mfma_f32_32x32x16_bf16(wf[ct], xf[tt], acc[ct][tt], 0, 0, 0);
;     }
	ds_read_b128 v[210:213], v249
	ds_read_b128 v[236:239], v248
	ds_read_b128 v[214:217], v249 offset:4608
	ds_read_b128 v[2:5], v248 offset:4608
	ds_read_b128 v[6:9], v248 offset:9216
	ds_read_b128 v[10:13], v248 offset:13824
	s_waitcnt lgkmcnt(4)
	v_mfma_f32_32x32x16_bf16 v[114:129], v[210:213], v[236:239], v[114:129]
	ds_read_b128 v[228:231], v249 offset:32
	s_waitcnt lgkmcnt(4)
	v_mfma_f32_32x32x16_bf16 v[130:145], v[214:217], v[236:239], v[130:145]
	ds_read_b128 v[14:17], v248 offset:32
	s_waitcnt lgkmcnt(4)
	v_mfma_f32_32x32x16_bf16 v[82:97], v[210:213], v[2:5], v[82:97]
	ds_read_b128 v[232:235], v249 offset:4640
	v_mfma_f32_32x32x16_bf16 v[98:113], v[214:217], v[2:5], v[98:113]
	ds_read_b128 v[236:239], v248 offset:4640
	s_waitcnt vmcnt(15)
	ds_write_b128 v250, v[162:165] offset:36864
	s_waitcnt lgkmcnt(6)
	v_mfma_f32_32x32x16_bf16 v[50:65], v[210:213], v[6:9], v[50:65]
	ds_read_b128 v[2:5], v248 offset:9248
	v_mfma_f32_32x32x16_bf16 v[66:81], v[214:217], v[6:9], v[66:81]
	global_load_dwordx4 v[162:165], v227, s[74:75] offset:1920 sc0
	s_waitcnt lgkmcnt(6)
	v_mfma_f32_32x32x16_bf16 v[18:33], v[210:213], v[10:13], v[18:33]
	ds_read_b128 v[6:9], v248 offset:13856
	s_waitcnt vmcnt(15)
	ds_write_b128 v251, v[194:197] offset:36864
	v_mfma_f32_32x32x16_bf16 v[34:49], v[214:217], v[10:13], v[34:49]
	s_waitcnt lgkmcnt(6)
	v_mfma_f32_32x32x16_bf16 v[114:129], v[228:231], v[14:17], v[114:129]
	ds_read_b128 v[210:213], v249 offset:64
	global_load_dwordx4 v[194:197], v227, s[82:83] offset:1920 sc0
	s_waitcnt lgkmcnt(6)
	v_mfma_f32_32x32x16_bf16 v[130:145], v[232:235], v[14:17], v[130:145]
	ds_read_b128 v[10:13], v248 offset:64
	s_waitcnt vmcnt(15)
	ds_write_b128 v250, v[166:169] offset:46080
	s_waitcnt lgkmcnt(7)
	v_mfma_f32_32x32x16_bf16 v[82:97], v[228:231], v[236:239], v[82:97]
	ds_read_b128 v[214:217], v249 offset:4672
	v_mfma_f32_32x32x16_bf16 v[98:113], v[232:235], v[236:239], v[98:113]
	ds_read_b128 v[14:17], v248 offset:4672
	global_load_dwordx4 v[166:169], v227, s[76:77] offset:1920 sc0
	s_waitcnt lgkmcnt(7)
	v_mfma_f32_32x32x16_bf16 v[50:65], v[228:231], v[2:5], v[50:65]
	ds_read_b128 v[236:239], v248 offset:9280
	s_waitcnt vmcnt(15)
	ds_write_b128 v251, v[198:201] offset:46080
	v_mfma_f32_32x32x16_bf16 v[66:81], v[232:235], v[2:5], v[66:81]
	s_waitcnt lgkmcnt(8)
	v_mfma_f32_32x32x16_bf16 v[18:33], v[228:231], v[6:9], v[18:33]
	ds_read_b128 v[2:5], v248 offset:13888
	global_load_dwordx4 v[198:201], v227, s[84:85] offset:1920 sc0
	v_mfma_f32_32x32x16_bf16 v[34:49], v[232:235], v[6:9], v[34:49]
	s_waitcnt vmcnt(15)
	ds_write_b128 v250, v[170:173] offset:55296
	s_waitcnt lgkmcnt(7)
	v_mfma_f32_32x32x16_bf16 v[114:129], v[210:213], v[10:13], v[114:129]
	ds_read_b128 v[228:231], v249 offset:96
	s_waitcnt lgkmcnt(6)
	v_mfma_f32_32x32x16_bf16 v[130:145], v[214:217], v[10:13], v[130:145]
	ds_read_b128 v[6:9], v248 offset:96
	global_load_dwordx4 v[170:173], v227, s[78:79] offset:1920 sc0
	s_waitcnt lgkmcnt(6)
	v_mfma_f32_32x32x16_bf16 v[82:97], v[210:213], v[14:17], v[82:97]
	ds_read_b128 v[232:235], v249 offset:4704
	s_waitcnt vmcnt(15)
	ds_write_b128 v251, v[202:205] offset:55296
	v_mfma_f32_32x32x16_bf16 v[98:113], v[214:217], v[14:17], v[98:113]
	ds_read_b128 v[10:13], v248 offset:4704
	s_waitcnt lgkmcnt(8)
	v_mfma_f32_32x32x16_bf16 v[50:65], v[210:213], v[236:239], v[50:65]
	ds_read_b128 v[14:17], v248 offset:9312
	global_load_dwordx4 v[202:205], v227, s[86:87] offset:1920 sc0
	v_mfma_f32_32x32x16_bf16 v[66:81], v[214:217], v[236:239], v[66:81]
	s_waitcnt vmcnt(15)
	ds_write_b128 v250, v[174:177] offset:64512
	s_waitcnt lgkmcnt(8)
	v_mfma_f32_32x32x16_bf16 v[18:33], v[210:213], v[2:5], v[18:33]
	ds_read_b128 v[236:239], v248 offset:13920
	v_mfma_f32_32x32x16_bf16 v[34:49], v[214:217], v[2:5], v[34:49]
	global_load_dwordx4 v[174:177], v227, s[80:81] offset:1920 sc0
	s_waitcnt lgkmcnt(6)
	v_mfma_f32_32x32x16_bf16 v[114:129], v[228:231], v[6:9], v[114:129]
	s_waitcnt vmcnt(15)
	ds_write_b128 v251, v[206:209] offset:64512
	s_waitcnt lgkmcnt(6)
	v_mfma_f32_32x32x16_bf16 v[130:145], v[232:235], v[6:9], v[130:145]
	s_waitcnt lgkmcnt(4)
	v_mfma_f32_32x32x16_bf16 v[82:97], v[228:231], v[10:13], v[82:97]
	global_load_dwordx4 v[206:209], v227, s[92:93] offset:1920 sc0
	v_mfma_f32_32x32x16_bf16 v[98:113], v[232:235], v[10:13], v[98:113]
	s_waitcnt lgkmcnt(3)
	v_mfma_f32_32x32x16_bf16 v[50:65], v[228:231], v[14:17], v[50:65]
	v_mfma_f32_32x32x16_bf16 v[66:81], v[232:235], v[14:17], v[66:81]
	s_waitcnt lgkmcnt(1)
	v_mfma_f32_32x32x16_bf16 v[18:33], v[228:231], v[236:239], v[18:33]
	v_mfma_f32_32x32x16_bf16 v[34:49], v[232:235], v[236:239], v[34:49]
	s_waitcnt lgkmcnt(0)
	s_barrier
;     ...
;   for (int kt = 0; kt < nk; ++kt) {
;     __syncthreads();
;     if (kt + 1 < nk) {
;       u16* aw = As0 + ((kt + 1) & 1) * 256 * LD;
;       u16* bw = Bs0 + ((kt + 1) & 1) * 256 * LD;
; #pragma unroll
;       for (int i = 0; i < 4; ++i) { *(u32x4*)(aw + (srow + 64 * i) * LD + skc * 8) = ra[i]; *(u32x4*)(bw + (srow + 64 * i) * LD + skc * 8) = rb[i]; }
;     }
;     if (kt + 2 < nk) {
; #pragma unroll
;       for (int i = 0; i < 4; ++i) { ra[i] = *(const u32x4*)(Ag + (size_t)(64 * i) * K + (kt + 2) * 64); rb[i] = *(const u32x4*)(Bg[i] + (kt + 2) * 64); }
;     }
;     __builtin_amdgcn_sched_barrier(0);
;     const u16* as = As0 + (kt & 1) * 256 * LD + (wr * 128 + l31) * LD + h * 8;
;     const u16* bs = Bs0 + (kt & 1) * 256 * LD + (wc * 64 + l31) * LD + h * 8;
;     if (domma)
; #pragma unroll
;     for (int ks = 0; ks < 4; ++ks) {
;       bf16x8 wf[2], xf[4];
; #pragma unroll
;       for (int ct = 0; ct < 2; ++ct) wf[ct] = *(const bf16x8*)(bs + ct * 32 * LD + ks * 16);
; #pragma unroll
;       for (int tt = 0; tt < 4; ++tt) xf[tt] = *(const bf16x8*)(as + tt * 32 * LD + ks * 16);
; #pragma unroll
;       for (int ct = 0; ct < 2; ++ct)
; #pragma unroll
;         for (int tt = 0; tt < 4; ++tt) acc[ct][tt] = __builtin_amdgcn_mfma_f32_32x32x16_bf16(wf[ct], xf[tt], acc[ct][tt], 0, 0, 0);
;     }
;     __builtin_amdgcn_sched_barrier(0);
;   }
	ds_read_b128 v[210:213], v249 offset:36864
	ds_read_b128 v[236:239], v248 offset:36864
	ds_read_b128 v[214:217], v249 offset:41472
	ds_read_b128 v[2:5], v248 offset:41472
	ds_read_b128 v[6:9], v248 offset:46080
	ds_read_b128 v[10:13], v248 offset:50688
	s_waitcnt lgkmcnt(4)
	v_mfma_f32_32x32x16_bf16 v[114:129], v[210:213], v[236:239], v[114:129]
	ds_read_b128 v[228:231], v249 offset:36896
	s_waitcnt lgkmcnt(4)
	v_mfma_f32_32x32x16_bf16 v[130:145], v[214:217], v[236:239], v[130:145]
	ds_read_b128 v[14:17], v248 offset:36896
	s_waitcnt lgkmcnt(4)
	v_mfma_f32_32x32x16_bf16 v[82:97], v[210:213], v[2:5], v[82:97]
	ds_read_b128 v[232:235], v249 offset:41504
	v_mfma_f32_32x32x16_bf16 v[98:113], v[214:217], v[2:5], v[98:113]
	ds_read_b128 v[236:239], v248 offset:41504
	s_waitcnt vmcnt(15)
	ds_write_b128 v250, v[146:149]
	s_waitcnt lgkmcnt(6)
	v_mfma_f32_32x32x16_bf16 v[50:65], v[210:213], v[6:9], v[50:65]
	ds_read_b128 v[2:5], v248 offset:46112
	v_mfma_f32_32x32x16_bf16 v[66:81], v[214:217], v[6:9], v[66:81]
	s_waitcnt lgkmcnt(6)
	v_mfma_f32_32x32x16_bf16 v[18:33], v[210:213], v[10:13], v[18:33]
	ds_read_b128 v[6:9], v248 offset:50720
	s_waitcnt vmcnt(14)
	ds_write_b128 v251, v[178:181]
	v_mfma_f32_32x32x16_bf16 v[34:49], v[214:217], v[10:13], v[34:49]
	s_waitcnt lgkmcnt(6)
	v_mfma_f32_32x32x16_bf16 v[114:129], v[228:231], v[14:17], v[114:129]
	ds_read_b128 v[210:213], v249 offset:36928
	s_waitcnt lgkmcnt(6)
	v_mfma_f32_32x32x16_bf16 v[130:145], v[232:235], v[14:17], v[130:145]
	ds_read_b128 v[10:13], v248 offset:36928
	s_waitcnt vmcnt(13)
	ds_write_b128 v250, v[150:153] offset:9216
	s_waitcnt lgkmcnt(7)
	v_mfma_f32_32x32x16_bf16 v[82:97], v[228:231], v[236:239], v[82:97]
	ds_read_b128 v[214:217], v249 offset:41536
	v_mfma_f32_32x32x16_bf16 v[98:113], v[232:235], v[236:239], v[98:113]
	ds_read_b128 v[14:17], v248 offset:41536
	s_waitcnt lgkmcnt(7)
	v_mfma_f32_32x32x16_bf16 v[50:65], v[228:231], v[2:5], v[50:65]
	ds_read_b128 v[236:239], v248 offset:46144
	s_waitcnt vmcnt(12)
	ds_write_b128 v251, v[182:185] offset:9216
	v_mfma_f32_32x32x16_bf16 v[66:81], v[232:235], v[2:5], v[66:81]
	s_waitcnt lgkmcnt(8)
	v_mfma_f32_32x32x16_bf16 v[18:33], v[228:231], v[6:9], v[18:33]
	ds_read_b128 v[2:5], v248 offset:50752
	v_mfma_f32_32x32x16_bf16 v[34:49], v[232:235], v[6:9], v[34:49]
	s_waitcnt vmcnt(11)
	ds_write_b128 v250, v[154:157] offset:18432
	s_waitcnt lgkmcnt(7)
	v_mfma_f32_32x32x16_bf16 v[114:129], v[210:213], v[10:13], v[114:129]
	ds_read_b128 v[228:231], v249 offset:36960
	s_waitcnt lgkmcnt(6)
	v_mfma_f32_32x32x16_bf16 v[130:145], v[214:217], v[10:13], v[130:145]
	ds_read_b128 v[6:9], v248 offset:36960
	s_waitcnt lgkmcnt(6)
	v_mfma_f32_32x32x16_bf16 v[82:97], v[210:213], v[14:17], v[82:97]
	ds_read_b128 v[232:235], v249 offset:41568
	s_waitcnt vmcnt(10)
	ds_write_b128 v251, v[186:189] offset:18432
	v_mfma_f32_32x32x16_bf16 v[98:113], v[214:217], v[14:17], v[98:113]
	ds_read_b128 v[10:13], v248 offset:41568
	s_waitcnt lgkmcnt(8)
	v_mfma_f32_32x32x16_bf16 v[50:65], v[210:213], v[236:239], v[50:65]
	ds_read_b128 v[14:17], v248 offset:46176
	v_mfma_f32_32x32x16_bf16 v[66:81], v[214:217], v[236:239], v[66:81]
	s_waitcnt vmcnt(9)
	ds_write_b128 v250, v[158:161] offset:27648
	s_waitcnt lgkmcnt(8)
	v_mfma_f32_32x32x16_bf16 v[18:33], v[210:213], v[2:5], v[18:33]
	ds_read_b128 v[236:239], v248 offset:50784
	v_mfma_f32_32x32x16_bf16 v[34:49], v[214:217], v[2:5], v[34:49]
	s_waitcnt lgkmcnt(6)
	v_mfma_f32_32x32x16_bf16 v[114:129], v[228:231], v[6:9], v[114:129]
	s_waitcnt vmcnt(8)
	ds_write_b128 v251, v[190:193] offset:27648
	s_waitcnt lgkmcnt(6)
	v_mfma_f32_32x32x16_bf16 v[130:145], v[232:235], v[6:9], v[130:145]
	s_waitcnt lgkmcnt(4)
	v_mfma_f32_32x32x16_bf16 v[82:97], v[228:231], v[10:13], v[82:97]
	v_mfma_f32_32x32x16_bf16 v[98:113], v[232:235], v[10:13], v[98:113]
	s_waitcnt lgkmcnt(3)
	v_mfma_f32_32x32x16_bf16 v[50:65], v[228:231], v[14:17], v[50:65]
	v_mfma_f32_32x32x16_bf16 v[66:81], v[232:235], v[14:17], v[66:81]
	s_waitcnt lgkmcnt(1)
	v_mfma_f32_32x32x16_bf16 v[18:33], v[228:231], v[236:239], v[18:33]
	v_mfma_f32_32x32x16_bf16 v[34:49], v[232:235], v[236:239], v[34:49]
	s_waitcnt lgkmcnt(0)
	s_barrier
	ds_read_b128 v[210:213], v249
	ds_read_b128 v[236:239], v248
	ds_read_b128 v[214:217], v249 offset:4608
	ds_read_b128 v[2:5], v248 offset:4608
	ds_read_b128 v[6:9], v248 offset:9216
	ds_read_b128 v[10:13], v248 offset:13824
	s_waitcnt lgkmcnt(4)
	v_mfma_f32_32x32x16_bf16 v[114:129], v[210:213], v[236:239], v[114:129]
	ds_read_b128 v[228:231], v249 offset:32
	s_waitcnt lgkmcnt(4)
	v_mfma_f32_32x32x16_bf16 v[130:145], v[214:217], v[236:239], v[130:145]
	ds_read_b128 v[14:17], v248 offset:32
	s_waitcnt lgkmcnt(4)
	v_mfma_f32_32x32x16_bf16 v[82:97], v[210:213], v[2:5], v[82:97]
	ds_read_b128 v[232:235], v249 offset:4640
	v_mfma_f32_32x32x16_bf16 v[98:113], v[214:217], v[2:5], v[98:113]
	ds_read_b128 v[236:239], v248 offset:4640
	s_waitcnt vmcnt(7)
	ds_write_b128 v250, v[162:165] offset:36864
	s_waitcnt lgkmcnt(6)
	v_mfma_f32_32x32x16_bf16 v[50:65], v[210:213], v[6:9], v[50:65]
	ds_read_b128 v[2:5], v248 offset:9248
	v_mfma_f32_32x32x16_bf16 v[66:81], v[214:217], v[6:9], v[66:81]
	s_waitcnt lgkmcnt(6)
	v_mfma_f32_32x32x16_bf16 v[18:33], v[210:213], v[10:13], v[18:33]
	ds_read_b128 v[6:9], v248 offset:13856
	s_waitcnt vmcnt(6)
	ds_write_b128 v251, v[194:197] offset:36864
	v_mfma_f32_32x32x16_bf16 v[34:49], v[214:217], v[10:13], v[34:49]
	s_waitcnt lgkmcnt(6)
	v_mfma_f32_32x32x16_bf16 v[114:129], v[228:231], v[14:17], v[114:129]
	ds_read_b128 v[210:213], v249 offset:64
	s_waitcnt lgkmcnt(6)
;     ...
;   for (int kt = 0; kt < nk; ++kt) {
;     __syncthreads();
;     if (kt + 1 < nk) {
;       u16* aw = As0 + ((kt + 1) & 1) * 256 * LD;
;       u16* bw = Bs0 + ((kt + 1) & 1) * 256 * LD;
; #pragma unroll
;       for (int i = 0; i < 4; ++i) { *(u32x4*)(aw + (srow + 64 * i) * LD + skc * 8) = ra[i]; *(u32x4*)(bw + (srow + 64 * i) * LD + skc * 8) = rb[i]; }
;     }
;     if (kt + 2 < nk) {
; #pragma unroll
;       for (int i = 0; i < 4; ++i) { ra[i] = *(const u32x4*)(Ag + (size_t)(64 * i) * K + (kt + 2) * 64); rb[i] = *(const u32x4*)(Bg[i] + (kt + 2) * 64); }
;     }
;     __builtin_amdgcn_sched_barrier(0);
;     const u16* as = As0 + (kt & 1) * 256 * LD + (wr * 128 + l31) * LD + h * 8;
;     const u16* bs = Bs0 + (kt & 1) * 256 * LD + (wc * 64 + l31) * LD + h * 8;
;     if (domma)
; #pragma unroll
;     for (int ks = 0; ks < 4; ++ks) {
;       bf16x8 wf[2], xf[4];
; #pragma unroll
;       for (int ct = 0; ct < 2; ++ct) wf[ct] = *(const bf16x8*)(bs + ct * 32 * LD + ks * 16);
; #pragma unroll
;       for (int tt = 0; tt < 4; ++tt) xf[tt] = *(const bf16x8*)(as + tt * 32 * LD + ks * 16);
; #pragma unroll
;       for (int ct = 0; ct < 2; ++ct)
; #pragma unroll
;         for (int tt = 0; tt < 4; ++tt) acc[ct][tt] = __builtin_amdgcn_mfma_f32_32x32x16_bf16(wf[ct], xf[tt], acc[ct][tt], 0, 0, 0);
;     }
;     __builtin_amdgcn_sched_barrier(0);
;   }
	v_mfma_f32_32x32x16_bf16 v[130:145], v[232:235], v[14:17], v[130:145]
	ds_read_b128 v[10:13], v248 offset:64
	s_waitcnt vmcnt(5)
	ds_write_b128 v250, v[166:169] offset:46080
	s_waitcnt lgkmcnt(7)
	v_mfma_f32_32x32x16_bf16 v[82:97], v[228:231], v[236:239], v[82:97]
	ds_read_b128 v[214:217], v249 offset:4672
	v_mfma_f32_32x32x16_bf16 v[98:113], v[232:235], v[236:239], v[98:113]
	ds_read_b128 v[14:17], v248 offset:4672
	s_waitcnt lgkmcnt(7)
	v_mfma_f32_32x32x16_bf16 v[50:65], v[228:231], v[2:5], v[50:65]
	ds_read_b128 v[236:239], v248 offset:9280
	s_waitcnt vmcnt(4)
	ds_write_b128 v251, v[198:201] offset:46080
	v_mfma_f32_32x32x16_bf16 v[66:81], v[232:235], v[2:5], v[66:81]
	s_waitcnt lgkmcnt(8)
	v_mfma_f32_32x32x16_bf16 v[18:33], v[228:231], v[6:9], v[18:33]
	ds_read_b128 v[2:5], v248 offset:13888
	v_mfma_f32_32x32x16_bf16 v[34:49], v[232:235], v[6:9], v[34:49]
	s_waitcnt vmcnt(3)
	ds_write_b128 v250, v[170:173] offset:55296
	s_waitcnt lgkmcnt(7)
	v_mfma_f32_32x32x16_bf16 v[114:129], v[210:213], v[10:13], v[114:129]
	ds_read_b128 v[228:231], v249 offset:96
	s_waitcnt lgkmcnt(6)
	v_mfma_f32_32x32x16_bf16 v[130:145], v[214:217], v[10:13], v[130:145]
	ds_read_b128 v[6:9], v248 offset:96
	s_waitcnt lgkmcnt(6)
	v_mfma_f32_32x32x16_bf16 v[82:97], v[210:213], v[14:17], v[82:97]
	ds_read_b128 v[232:235], v249 offset:4704
	s_waitcnt vmcnt(2)
	ds_write_b128 v251, v[202:205] offset:55296
	v_mfma_f32_32x32x16_bf16 v[98:113], v[214:217], v[14:17], v[98:113]
	ds_read_b128 v[10:13], v248 offset:4704
	s_waitcnt lgkmcnt(8)
	v_mfma_f32_32x32x16_bf16 v[50:65], v[210:213], v[236:239], v[50:65]
	ds_read_b128 v[14:17], v248 offset:9312
	v_mfma_f32_32x32x16_bf16 v[66:81], v[214:217], v[236:239], v[66:81]
	s_waitcnt vmcnt(1)
	ds_write_b128 v250, v[174:177] offset:64512
	s_waitcnt lgkmcnt(8)
	v_mfma_f32_32x32x16_bf16 v[18:33], v[210:213], v[2:5], v[18:33]
	ds_read_b128 v[236:239], v248 offset:13920
	v_mfma_f32_32x32x16_bf16 v[34:49], v[214:217], v[2:5], v[34:49]
	s_waitcnt lgkmcnt(6)
	v_mfma_f32_32x32x16_bf16 v[114:129], v[228:231], v[6:9], v[114:129]
	s_waitcnt vmcnt(0)
	ds_write_b128 v251, v[206:209] offset:64512
	s_waitcnt lgkmcnt(6)
	v_mfma_f32_32x32x16_bf16 v[130:145], v[232:235], v[6:9], v[130:145]
	s_waitcnt lgkmcnt(4)
	v_mfma_f32_32x32x16_bf16 v[82:97], v[228:231], v[10:13], v[82:97]
	v_mfma_f32_32x32x16_bf16 v[98:113], v[232:235], v[10:13], v[98:113]
	s_waitcnt lgkmcnt(3)
	v_mfma_f32_32x32x16_bf16 v[50:65], v[228:231], v[14:17], v[50:65]
	v_mfma_f32_32x32x16_bf16 v[66:81], v[232:235], v[14:17], v[66:81]
	s_waitcnt lgkmcnt(1)
	v_mfma_f32_32x32x16_bf16 v[18:33], v[228:231], v[236:239], v[18:33]
	v_mfma_f32_32x32x16_bf16 v[34:49], v[232:235], v[236:239], v[34:49]
	s_waitcnt lgkmcnt(0)
	s_barrier
	ds_read_b128 v[210:213], v249 offset:36864
	ds_read_b128 v[236:239], v248 offset:36864
	ds_read_b128 v[214:217], v249 offset:41472
	ds_read_b128 v[2:5], v248 offset:41472
	ds_read_b128 v[6:9], v248 offset:46080
	ds_read_b128 v[10:13], v248 offset:50688
	s_waitcnt lgkmcnt(4)
	v_mfma_f32_32x32x16_bf16 v[114:129], v[210:213], v[236:239], v[114:129]
	ds_read_b128 v[228:231], v249 offset:36896
	s_waitcnt lgkmcnt(4)
	v_mfma_f32_32x32x16_bf16 v[130:145], v[214:217], v[236:239], v[130:145]
	ds_read_b128 v[14:17], v248 offset:36896
	s_waitcnt lgkmcnt(4)
	v_mfma_f32_32x32x16_bf16 v[82:97], v[210:213], v[2:5], v[82:97]
	ds_read_b128 v[232:235], v249 offset:41504
	v_mfma_f32_32x32x16_bf16 v[98:113], v[214:217], v[2:5], v[98:113]
	ds_read_b128 v[236:239], v248 offset:41504
	s_waitcnt lgkmcnt(5)
	v_mfma_f32_32x32x16_bf16 v[50:65], v[210:213], v[6:9], v[50:65]
	ds_read_b128 v[2:5], v248 offset:46112
	v_mfma_f32_32x32x16_bf16 v[66:81], v[214:217], v[6:9], v[66:81]
	s_waitcnt lgkmcnt(5)
	v_mfma_f32_32x32x16_bf16 v[18:33], v[210:213], v[10:13], v[18:33]
	ds_read_b128 v[6:9], v248 offset:50720
	v_mfma_f32_32x32x16_bf16 v[34:49], v[214:217], v[10:13], v[34:49]
	s_waitcnt lgkmcnt(4)
	v_mfma_f32_32x32x16_bf16 v[114:129], v[228:231], v[14:17], v[114:129]
	ds_read_b128 v[210:213], v249 offset:36928
	s_waitcnt lgkmcnt(4)
	v_mfma_f32_32x32x16_bf16 v[130:145], v[232:235], v[14:17], v[130:145]
	ds_read_b128 v[10:13], v248 offset:36928
	s_waitcnt lgkmcnt(4)
	v_mfma_f32_32x32x16_bf16 v[82:97], v[228:231], v[236:239], v[82:97]
	ds_read_b128 v[214:217], v249 offset:41536
	v_mfma_f32_32x32x16_bf16 v[98:113], v[232:235], v[236:239], v[98:113]
	ds_read_b128 v[14:17], v248 offset:41536
	s_waitcnt lgkmcnt(5)
	v_mfma_f32_32x32x16_bf16 v[50:65], v[228:231], v[2:5], v[50:65]
	ds_read_b128 v[236:239], v248 offset:46144
	v_mfma_f32_32x32x16_bf16 v[66:81], v[232:235], v[2:5], v[66:81]
	s_waitcnt lgkmcnt(5)
	v_mfma_f32_32x32x16_bf16 v[18:33], v[228:231], v[6:9], v[18:33]
	ds_read_b128 v[2:5], v248 offset:50752
	v_mfma_f32_32x32x16_bf16 v[34:49], v[232:235], v[6:9], v[34:49]
	s_waitcnt lgkmcnt(4)
	v_mfma_f32_32x32x16_bf16 v[114:129], v[210:213], v[10:13], v[114:129]
	ds_read_b128 v[228:231], v249 offset:36960
	s_waitcnt lgkmcnt(4)
	v_mfma_f32_32x32x16_bf16 v[130:145], v[214:217], v[10:13], v[130:145]
	ds_read_b128 v[6:9], v248 offset:36960
	s_waitcnt lgkmcnt(4)
	v_mfma_f32_32x32x16_bf16 v[82:97], v[210:213], v[14:17], v[82:97]
	ds_read_b128 v[232:235], v249 offset:41568
	v_mfma_f32_32x32x16_bf16 v[98:113], v[214:217], v[14:17], v[98:113]
	ds_read_b128 v[10:13], v248 offset:41568
	s_waitcnt lgkmcnt(5)
	v_mfma_f32_32x32x16_bf16 v[50:65], v[210:213], v[236:239], v[50:65]
	ds_read_b128 v[14:17], v248 offset:46176
	v_mfma_f32_32x32x16_bf16 v[66:81], v[214:217], v[236:239], v[66:81]
	s_waitcnt lgkmcnt(5)
	v_mfma_f32_32x32x16_bf16 v[18:33], v[210:213], v[2:5], v[18:33]
	ds_read_b128 v[236:239], v248 offset:50784
	v_mfma_f32_32x32x16_bf16 v[34:49], v[214:217], v[2:5], v[34:49]
	s_waitcnt lgkmcnt(4)
	v_mfma_f32_32x32x16_bf16 v[114:129], v[228:231], v[6:9], v[114:129]
	s_waitcnt lgkmcnt(3)
	v_mfma_f32_32x32x16_bf16 v[130:145], v[232:235], v[6:9], v[130:145]
	s_waitcnt lgkmcnt(2)
	v_mfma_f32_32x32x16_bf16 v[82:97], v[228:231], v[10:13], v[82:97]
	v_mfma_f32_32x32x16_bf16 v[98:113], v[232:235], v[10:13], v[98:113]
	s_waitcnt lgkmcnt(1)
	v_mfma_f32_32x32x16_bf16 v[50:65], v[228:231], v[14:17], v[50:65]
	v_mfma_f32_32x32x16_bf16 v[66:81], v[232:235], v[14:17], v[66:81]
	s_waitcnt lgkmcnt(0)
	v_mfma_f32_32x32x16_bf16 v[18:33], v[228:231], v[236:239], v[18:33]
	v_mfma_f32_32x32x16_bf16 v[34:49], v[232:235], v[236:239], v[34:49]
	v_mov_b32_e32 v3, 0
	v_mov_b32_e32 v227, v223
	s_branch .LBB0_139
;     ...
;   if (nk > 1) {
; #pragma unroll
;     for (int i = 0; i < 4; ++i) { ra[i] = *(const u32x4*)(Ag + (size_t)(64 * i) * K + 64); rb[i] = *(const u32x4*)(Bg[i] + 64); }
;   }
;   for (int kt = 0; kt < nk; ++kt) {
;     __syncthreads();
;     if (kt + 1 < nk) {
;       u16* aw = As0 + ((kt + 1) & 1) * 256 * LD;
;       u16* bw = Bs0 + ((kt + 1) & 1) * 256 * LD;
; #pragma unroll
;       for (int i = 0; i < 4; ++i) { *(u32x4*)(aw + (srow + 64 * i) * LD + skc * 8) = ra[i]; *(u32x4*)(bw + (srow + 64 * i) * LD + skc * 8) = rb[i]; }
;     }
;     if (kt + 2 < nk) {
; #pragma unroll
;       for (int i = 0; i < 4; ++i) { ra[i] = *(const u32x4*)(Ag + (size_t)(64 * i) * K + (kt + 2) * 64); rb[i] = *(const u32x4*)(Bg[i] + (kt + 2) * 64); }
;     }
.Lp1_stage_only:
	v_lshrrev_b32_e32 v227, 3, v223
	v_lshlrev_b32_e32 v227, 11, v227
	v_lshlrev_b32_e32 v2, 4, v223
	v_and_b32_e32 v2, 0x70, v2
	v_or_b32_e32 v227, v227, v2
	s_lshl_b32 s6, s35, 11
	s_add_u32 s74, s16, s6
	s_addc_u32 s75, s17, 0
	s_add_u32 s76, s74, 0x20000
	s_addc_u32 s77, s75, 0
	s_add_u32 s78, s74, 0x40000
	s_addc_u32 s79, s75, 0
	s_add_u32 s80, s74, 0x60000
	s_addc_u32 s81, s75, 0
	s_lshl_b32 s6, s59, 11
	s_add_u32 s82, s18, s6
	s_addc_u32 s83, s19, 0
	s_add_u32 s84, s82, 0x20000
	s_addc_u32 s85, s83, 0
	s_add_u32 s86, s82, 0x40000
	s_addc_u32 s87, s83, 0
	s_add_u32 s92, s82, 0x60000
	s_addc_u32 s93, s83, 0
	global_load_dwordx4 v[146:149], v227, s[74:75] offset:256 sc0
	global_load_dwordx4 v[178:181], v227, s[82:83] offset:256 sc0
	global_load_dwordx4 v[150:153], v227, s[76:77] offset:256 sc0
	global_load_dwordx4 v[182:185], v227, s[84:85] offset:256 sc0
	global_load_dwordx4 v[154:157], v227, s[78:79] offset:256 sc0
	global_load_dwordx4 v[186:189], v227, s[86:87] offset:256 sc0
	global_load_dwordx4 v[158:161], v227, s[80:81] offset:256 sc0
	global_load_dwordx4 v[190:193], v227, s[92:93] offset:256 sc0
	global_load_dwordx4 v[162:165], v227, s[74:75] offset:384 sc0
	global_load_dwordx4 v[194:197], v227, s[82:83] offset:384 sc0
	global_load_dwordx4 v[166:169], v227, s[76:77] offset:384 sc0
	global_load_dwordx4 v[198:201], v227, s[84:85] offset:384 sc0
	global_load_dwordx4 v[170:173], v227, s[78:79] offset:384 sc0
	global_load_dwordx4 v[202:205], v227, s[86:87] offset:384 sc0
	global_load_dwordx4 v[174:177], v227, s[80:81] offset:384 sc0
	global_load_dwordx4 v[206:209], v227, s[92:93] offset:384 sc0
	s_waitcnt vmcnt(23)
	ds_write_b128 v251, v[36:39] offset:36864
	s_waitcnt vmcnt(22)
	ds_write_b128 v251, v[40:43] offset:46080
	s_waitcnt vmcnt(21)
	ds_write_b128 v251, v[44:47] offset:55296
	s_waitcnt vmcnt(20)
	ds_write_b128 v251, v[48:51] offset:64512
	s_waitcnt vmcnt(19)
	ds_write_b128 v250, v[52:55] offset:36864
	s_waitcnt vmcnt(18)
	ds_write_b128 v250, v[56:59] offset:46080
	s_waitcnt vmcnt(17)
	ds_write_b128 v250, v[60:63] offset:55296
	s_waitcnt vmcnt(16)
	ds_write_b128 v250, v[64:67] offset:64512
	s_waitcnt lgkmcnt(0)
	s_barrier
	s_waitcnt vmcnt(15)
	ds_write_b128 v250, v[146:149]
	global_load_dwordx4 v[146:149], v227, s[74:75] offset:512 sc0
	s_waitcnt vmcnt(15)
	ds_write_b128 v251, v[178:181]
	global_load_dwordx4 v[178:181], v227, s[82:83] offset:512 sc0
	s_waitcnt vmcnt(15)
	ds_write_b128 v250, v[150:153] offset:9216
	global_load_dwordx4 v[150:153], v227, s[76:77] offset:512 sc0
	s_waitcnt vmcnt(15)
	ds_write_b128 v251, v[182:185] offset:9216
	global_load_dwordx4 v[182:185], v227, s[84:85] offset:512 sc0
	s_waitcnt vmcnt(15)
	ds_write_b128 v250, v[154:157] offset:18432
	global_load_dwordx4 v[154:157], v227, s[78:79] offset:512 sc0
	s_waitcnt vmcnt(15)
	ds_write_b128 v251, v[186:189] offset:18432
	global_load_dwordx4 v[186:189], v227, s[86:87] offset:512 sc0
	s_waitcnt vmcnt(15)
	ds_write_b128 v250, v[158:161] offset:27648
	global_load_dwordx4 v[158:161], v227, s[80:81] offset:512 sc0
	s_waitcnt vmcnt(15)
	ds_write_b128 v251, v[190:193] offset:27648
	global_load_dwordx4 v[190:193], v227, s[92:93] offset:512 sc0
	s_waitcnt lgkmcnt(0)
	s_barrier
	s_waitcnt vmcnt(15)
	ds_write_b128 v250, v[162:165] offset:36864
	global_load_dwordx4 v[162:165], v227, s[74:75] offset:640 sc0
	s_waitcnt vmcnt(15)
	ds_write_b128 v251, v[194:197] offset:36864
	global_load_dwordx4 v[194:197], v227, s[82:83] offset:640 sc0
	s_waitcnt vmcnt(15)
	ds_write_b128 v250, v[166:169] offset:46080
	global_load_dwordx4 v[166:169], v227, s[76:77] offset:640 sc0
	s_waitcnt vmcnt(15)
	ds_write_b128 v251, v[198:201] offset:46080
	global_load_dwordx4 v[198:201], v227, s[84:85] offset:640 sc0
	s_waitcnt vmcnt(15)
	ds_write_b128 v250, v[170:173] offset:55296
	global_load_dwordx4 v[170:173], v227, s[78:79] offset:640 sc0
	s_waitcnt vmcnt(15)
	ds_write_b128 v251, v[202:205] offset:55296
	global_load_dwordx4 v[202:205], v227, s[86:87] offset:640 sc0
	s_waitcnt vmcnt(15)
	ds_write_b128 v250, v[174:177] offset:64512
	global_load_dwordx4 v[174:177], v227, s[80:81] offset:640 sc0
	s_waitcnt vmcnt(15)
	ds_write_b128 v251, v[206:209] offset:64512
	global_load_dwordx4 v[206:209], v227, s[92:93] offset:640 sc0
	s_waitcnt lgkmcnt(0)
	s_barrier
	s_waitcnt vmcnt(15)
	ds_write_b128 v250, v[146:149]
	global_load_dwordx4 v[146:149], v227, s[74:75] offset:768 sc0
	s_waitcnt vmcnt(15)
	ds_write_b128 v251, v[178:181]
	global_load_dwordx4 v[178:181], v227, s[82:83] offset:768 sc0
	s_waitcnt vmcnt(15)
	ds_write_b128 v250, v[150:153] offset:9216
	global_load_dwordx4 v[150:153], v227, s[76:77] offset:768 sc0
	s_waitcnt vmcnt(15)
	ds_write_b128 v251, v[182:185] offset:9216
	global_load_dwordx4 v[182:185], v227, s[84:85] offset:768 sc0
	s_waitcnt vmcnt(15)
	ds_write_b128 v250, v[154:157] offset:18432
	global_load_dwordx4 v[154:157], v227, s[78:79] offset:768 sc0
	s_waitcnt vmcnt(15)
	ds_write_b128 v251, v[186:189] offset:18432
	global_load_dwordx4 v[186:189], v227, s[86:87] offset:768 sc0
	s_waitcnt vmcnt(15)
	ds_write_b128 v250, v[158:161] offset:27648
	global_load_dwordx4 v[158:161], v227, s[80:81] offset:768 sc0
	s_waitcnt vmcnt(15)
	ds_write_b128 v251, v[190:193] offset:27648
	global_load_dwordx4 v[190:193], v227, s[92:93] offset:768 sc0
	s_waitcnt lgkmcnt(0)
	s_barrier
;     ...
;   if (nk > 1) {
; #pragma unroll
;     for (int i = 0; i < 4; ++i) { ra[i] = *(const u32x4*)(Ag + (size_t)(64 * i) * K + 64); rb[i] = *(const u32x4*)(Bg[i] + 64); }
;   }
;   for (int kt = 0; kt < nk; ++kt) {
;     __syncthreads();
;     if (kt + 1 < nk) {
;       u16* aw = As0 + ((kt + 1) & 1) * 256 * LD;
;       u16* bw = Bs0 + ((kt + 1) & 1) * 256 * LD;
; #pragma unroll
;       for (int i = 0; i < 4; ++i) { *(u32x4*)(aw + (srow + 64 * i) * LD + skc * 8) = ra[i]; *(u32x4*)(bw + (srow + 64 * i) * LD + skc * 8) = rb[i]; }
;     }
;     if (kt + 2 < nk) {
; #pragma unroll
;       for (int i = 0; i < 4; ++i) { ra[i] = *(const u32x4*)(Ag + (size_t)(64 * i) * K + (kt + 2) * 64); rb[i] = *(const u32x4*)(Bg[i] + (kt + 2) * 64); }
;     }
	s_waitcnt vmcnt(15)
	ds_write_b128 v250, v[162:165] offset:36864
	global_load_dwordx4 v[162:165], v227, s[74:75] offset:896 sc0
	s_waitcnt vmcnt(15)
	ds_write_b128 v251, v[194:197] offset:36864
	global_load_dwordx4 v[194:197], v227, s[82:83] offset:896 sc0
	s_waitcnt vmcnt(15)
	ds_write_b128 v250, v[166:169] offset:46080
	global_load_dwordx4 v[166:169], v227, s[76:77] offset:896 sc0
	s_waitcnt vmcnt(15)
	ds_write_b128 v251, v[198:201] offset:46080
	global_load_dwordx4 v[198:201], v227, s[84:85] offset:896 sc0
	s_waitcnt vmcnt(15)
	ds_write_b128 v250, v[170:173] offset:55296
	global_load_dwordx4 v[170:173], v227, s[78:79] offset:896 sc0
	s_waitcnt vmcnt(15)
	ds_write_b128 v251, v[202:205] offset:55296
	global_load_dwordx4 v[202:205], v227, s[86:87] offset:896 sc0
	s_waitcnt vmcnt(15)
	ds_write_b128 v250, v[174:177] offset:64512
	global_load_dwordx4 v[174:177], v227, s[80:81] offset:896 sc0
	s_waitcnt vmcnt(15)
	ds_write_b128 v251, v[206:209] offset:64512
	global_load_dwordx4 v[206:209], v227, s[92:93] offset:896 sc0
	s_waitcnt lgkmcnt(0)
	s_barrier
	s_waitcnt vmcnt(15)
	ds_write_b128 v250, v[146:149]
	global_load_dwordx4 v[146:149], v227, s[74:75] offset:1024 sc0
	s_waitcnt vmcnt(15)
	ds_write_b128 v251, v[178:181]
	global_load_dwordx4 v[178:181], v227, s[82:83] offset:1024 sc0
	s_waitcnt vmcnt(15)
	ds_write_b128 v250, v[150:153] offset:9216
	global_load_dwordx4 v[150:153], v227, s[76:77] offset:1024 sc0
	s_waitcnt vmcnt(15)
	ds_write_b128 v251, v[182:185] offset:9216
	global_load_dwordx4 v[182:185], v227, s[84:85] offset:1024 sc0
	s_waitcnt vmcnt(15)
	ds_write_b128 v250, v[154:157] offset:18432
	global_load_dwordx4 v[154:157], v227, s[78:79] offset:1024 sc0
	s_waitcnt vmcnt(15)
	ds_write_b128 v251, v[186:189] offset:18432
	global_load_dwordx4 v[186:189], v227, s[86:87] offset:1024 sc0
	s_waitcnt vmcnt(15)
	ds_write_b128 v250, v[158:161] offset:27648
	global_load_dwordx4 v[158:161], v227, s[80:81] offset:1024 sc0
	s_waitcnt vmcnt(15)
	ds_write_b128 v251, v[190:193] offset:27648
	global_load_dwordx4 v[190:193], v227, s[92:93] offset:1024 sc0
	s_waitcnt lgkmcnt(0)
	s_barrier
	s_waitcnt vmcnt(15)
	ds_write_b128 v250, v[162:165] offset:36864
	global_load_dwordx4 v[162:165], v227, s[74:75] offset:1152 sc0
	s_waitcnt vmcnt(15)
	ds_write_b128 v251, v[194:197] offset:36864
	global_load_dwordx4 v[194:197], v227, s[82:83] offset:1152 sc0
	s_waitcnt vmcnt(15)
	ds_write_b128 v250, v[166:169] offset:46080
	global_load_dwordx4 v[166:169], v227, s[76:77] offset:1152 sc0
	s_waitcnt vmcnt(15)
	ds_write_b128 v251, v[198:201] offset:46080
	global_load_dwordx4 v[198:201], v227, s[84:85] offset:1152 sc0
	s_waitcnt vmcnt(15)
	ds_write_b128 v250, v[170:173] offset:55296
	global_load_dwordx4 v[170:173], v227, s[78:79] offset:1152 sc0
	s_waitcnt vmcnt(15)
	ds_write_b128 v251, v[202:205] offset:55296
	global_load_dwordx4 v[202:205], v227, s[86:87] offset:1152 sc0
	s_waitcnt vmcnt(15)
	ds_write_b128 v250, v[174:177] offset:64512
	global_load_dwordx4 v[174:177], v227, s[80:81] offset:1152 sc0
	s_waitcnt vmcnt(15)
	ds_write_b128 v251, v[206:209] offset:64512
	global_load_dwordx4 v[206:209], v227, s[92:93] offset:1152 sc0
	s_waitcnt lgkmcnt(0)
	s_barrier
	s_waitcnt vmcnt(15)
	ds_write_b128 v250, v[146:149]
	global_load_dwordx4 v[146:149], v227, s[74:75] offset:1280 sc0
	s_waitcnt vmcnt(15)
	ds_write_b128 v251, v[178:181]
	global_load_dwordx4 v[178:181], v227, s[82:83] offset:1280 sc0
	s_waitcnt vmcnt(15)
	ds_write_b128 v250, v[150:153] offset:9216
	global_load_dwordx4 v[150:153], v227, s[76:77] offset:1280 sc0
	s_waitcnt vmcnt(15)
	ds_write_b128 v251, v[182:185] offset:9216
	global_load_dwordx4 v[182:185], v227, s[84:85] offset:1280 sc0
	s_waitcnt vmcnt(15)
	ds_write_b128 v250, v[154:157] offset:18432
	global_load_dwordx4 v[154:157], v227, s[78:79] offset:1280 sc0
	s_waitcnt vmcnt(15)
	ds_write_b128 v251, v[186:189] offset:18432
	global_load_dwordx4 v[186:189], v227, s[86:87] offset:1280 sc0
	s_waitcnt vmcnt(15)
	ds_write_b128 v250, v[158:161] offset:27648
	global_load_dwordx4 v[158:161], v227, s[80:81] offset:1280 sc0
	s_waitcnt vmcnt(15)
	ds_write_b128 v251, v[190:193] offset:27648
	global_load_dwordx4 v[190:193], v227, s[92:93] offset:1280 sc0
	s_waitcnt lgkmcnt(0)
	s_barrier
	s_waitcnt vmcnt(15)
	ds_write_b128 v250, v[162:165] offset:36864
	global_load_dwordx4 v[162:165], v227, s[74:75] offset:1408 sc0
	s_waitcnt vmcnt(15)
	ds_write_b128 v251, v[194:197] offset:36864
	global_load_dwordx4 v[194:197], v227, s[82:83] offset:1408 sc0
	s_waitcnt vmcnt(15)
	ds_write_b128 v250, v[166:169] offset:46080
	global_load_dwordx4 v[166:169], v227, s[76:77] offset:1408 sc0
	s_waitcnt vmcnt(15)
	ds_write_b128 v251, v[198:201] offset:46080
	global_load_dwordx4 v[198:201], v227, s[84:85] offset:1408 sc0
	s_waitcnt vmcnt(15)
	ds_write_b128 v250, v[170:173] offset:55296
	global_load_dwordx4 v[170:173], v227, s[78:79] offset:1408 sc0
	s_waitcnt vmcnt(15)
	ds_write_b128 v251, v[202:205] offset:55296
	global_load_dwordx4 v[202:205], v227, s[86:87] offset:1408 sc0
	s_waitcnt vmcnt(15)
	ds_write_b128 v250, v[174:177] offset:64512
	global_load_dwordx4 v[174:177], v227, s[80:81] offset:1408 sc0
	s_waitcnt vmcnt(15)
	ds_write_b128 v251, v[206:209] offset:64512
	global_load_dwordx4 v[206:209], v227, s[92:93] offset:1408 sc0
	s_waitcnt lgkmcnt(0)
	s_barrier
;     ...
;   if (nk > 1) {
; #pragma unroll
;     for (int i = 0; i < 4; ++i) { ra[i] = *(const u32x4*)(Ag + (size_t)(64 * i) * K + 64); rb[i] = *(const u32x4*)(Bg[i] + 64); }
;   }
;   for (int kt = 0; kt < nk; ++kt) {
;     __syncthreads();
;     if (kt + 1 < nk) {
;       u16* aw = As0 + ((kt + 1) & 1) * 256 * LD;
;       u16* bw = Bs0 + ((kt + 1) & 1) * 256 * LD;
; #pragma unroll
;       for (int i = 0; i < 4; ++i) { *(u32x4*)(aw + (srow + 64 * i) * LD + skc * 8) = ra[i]; *(u32x4*)(bw + (srow + 64 * i) * LD + skc * 8) = rb[i]; }
;     }
;     if (kt + 2 < nk) {
; #pragma unroll
;       for (int i = 0; i < 4; ++i) { ra[i] = *(const u32x4*)(Ag + (size_t)(64 * i) * K + (kt + 2) * 64); rb[i] = *(const u32x4*)(Bg[i] + (kt + 2) * 64); }
;     }
	s_waitcnt vmcnt(15)
	ds_write_b128 v250, v[146:149]
	global_load_dwordx4 v[146:149], v227, s[74:75] offset:1536 sc0
	s_waitcnt vmcnt(15)
	ds_write_b128 v251, v[178:181]
	global_load_dwordx4 v[178:181], v227, s[82:83] offset:1536 sc0
	s_waitcnt vmcnt(15)
	ds_write_b128 v250, v[150:153] offset:9216
	global_load_dwordx4 v[150:153], v227, s[76:77] offset:1536 sc0
	s_waitcnt vmcnt(15)
	ds_write_b128 v251, v[182:185] offset:9216
	global_load_dwordx4 v[182:185], v227, s[84:85] offset:1536 sc0
	s_waitcnt vmcnt(15)
	ds_write_b128 v250, v[154:157] offset:18432
	global_load_dwordx4 v[154:157], v227, s[78:79] offset:1536 sc0
	s_waitcnt vmcnt(15)
	ds_write_b128 v251, v[186:189] offset:18432
	global_load_dwordx4 v[186:189], v227, s[86:87] offset:1536 sc0
	s_waitcnt vmcnt(15)
	ds_write_b128 v250, v[158:161] offset:27648
	global_load_dwordx4 v[158:161], v227, s[80:81] offset:1536 sc0
	s_waitcnt vmcnt(15)
	ds_write_b128 v251, v[190:193] offset:27648
	global_load_dwordx4 v[190:193], v227, s[92:93] offset:1536 sc0
	s_waitcnt lgkmcnt(0)
	s_barrier
	s_waitcnt vmcnt(15)
	ds_write_b128 v250, v[162:165] offset:36864
	global_load_dwordx4 v[162:165], v227, s[74:75] offset:1664 sc0
	s_waitcnt vmcnt(15)
	ds_write_b128 v251, v[194:197] offset:36864
	global_load_dwordx4 v[194:197], v227, s[82:83] offset:1664 sc0
	s_waitcnt vmcnt(15)
	ds_write_b128 v250, v[166:169] offset:46080
	global_load_dwordx4 v[166:169], v227, s[76:77] offset:1664 sc0
	s_waitcnt vmcnt(15)
	ds_write_b128 v251, v[198:201] offset:46080
	global_load_dwordx4 v[198:201], v227, s[84:85] offset:1664 sc0
	s_waitcnt vmcnt(15)
	ds_write_b128 v250, v[170:173] offset:55296
	global_load_dwordx4 v[170:173], v227, s[78:79] offset:1664 sc0
	s_waitcnt vmcnt(15)
	ds_write_b128 v251, v[202:205] offset:55296
	global_load_dwordx4 v[202:205], v227, s[86:87] offset:1664 sc0
	s_waitcnt vmcnt(15)
	ds_write_b128 v250, v[174:177] offset:64512
	global_load_dwordx4 v[174:177], v227, s[80:81] offset:1664 sc0
	s_waitcnt vmcnt(15)
	ds_write_b128 v251, v[206:209] offset:64512
	global_load_dwordx4 v[206:209], v227, s[92:93] offset:1664 sc0
	s_waitcnt lgkmcnt(0)
	s_barrier
	s_waitcnt vmcnt(15)
	ds_write_b128 v250, v[146:149]
	global_load_dwordx4 v[146:149], v227, s[74:75] offset:1792 sc0
	s_waitcnt vmcnt(15)
	ds_write_b128 v251, v[178:181]
	global_load_dwordx4 v[178:181], v227, s[82:83] offset:1792 sc0
	s_waitcnt vmcnt(15)
	ds_write_b128 v250, v[150:153] offset:9216
	global_load_dwordx4 v[150:153], v227, s[76:77] offset:1792 sc0
	s_waitcnt vmcnt(15)
	ds_write_b128 v251, v[182:185] offset:9216
	global_load_dwordx4 v[182:185], v227, s[84:85] offset:1792 sc0
	s_waitcnt vmcnt(15)
	ds_write_b128 v250, v[154:157] offset:18432
	global_load_dwordx4 v[154:157], v227, s[78:79] offset:1792 sc0
	s_waitcnt vmcnt(15)
	ds_write_b128 v251, v[186:189] offset:18432
	global_load_dwordx4 v[186:189], v227, s[86:87] offset:1792 sc0
	s_waitcnt vmcnt(15)
	ds_write_b128 v250, v[158:161] offset:27648
	global_load_dwordx4 v[158:161], v227, s[80:81] offset:1792 sc0
	s_waitcnt vmcnt(15)
	ds_write_b128 v251, v[190:193] offset:27648
	global_load_dwordx4 v[190:193], v227, s[92:93] offset:1792 sc0
	s_waitcnt lgkmcnt(0)
	s_barrier
	s_waitcnt vmcnt(15)
	ds_write_b128 v250, v[162:165] offset:36864
	global_load_dwordx4 v[162:165], v227, s[74:75] offset:1920 sc0
	s_waitcnt vmcnt(15)
	ds_write_b128 v251, v[194:197] offset:36864
	global_load_dwordx4 v[194:197], v227, s[82:83] offset:1920 sc0
	s_waitcnt vmcnt(15)
	ds_write_b128 v250, v[166:169] offset:46080
	global_load_dwordx4 v[166:169], v227, s[76:77] offset:1920 sc0
	s_waitcnt vmcnt(15)
	ds_write_b128 v251, v[198:201] offset:46080
	global_load_dwordx4 v[198:201], v227, s[84:85] offset:1920 sc0
	s_waitcnt vmcnt(15)
	ds_write_b128 v250, v[170:173] offset:55296
	global_load_dwordx4 v[170:173], v227, s[78:79] offset:1920 sc0
	s_waitcnt vmcnt(15)
	ds_write_b128 v251, v[202:205] offset:55296
	global_load_dwordx4 v[202:205], v227, s[86:87] offset:1920 sc0
	s_waitcnt vmcnt(15)
	ds_write_b128 v250, v[174:177] offset:64512
	global_load_dwordx4 v[174:177], v227, s[80:81] offset:1920 sc0
	s_waitcnt vmcnt(15)
	ds_write_b128 v251, v[206:209] offset:64512
	global_load_dwordx4 v[206:209], v227, s[92:93] offset:1920 sc0
	s_waitcnt lgkmcnt(0)
	s_barrier
	s_waitcnt vmcnt(15)
	ds_write_b128 v250, v[146:149]
	s_waitcnt vmcnt(14)
	ds_write_b128 v251, v[178:181]
	s_waitcnt vmcnt(13)
	ds_write_b128 v250, v[150:153] offset:9216
	s_waitcnt vmcnt(12)
	ds_write_b128 v251, v[182:185] offset:9216
	s_waitcnt vmcnt(11)
	ds_write_b128 v250, v[154:157] offset:18432
	s_waitcnt vmcnt(10)
	ds_write_b128 v251, v[186:189] offset:18432
	s_waitcnt vmcnt(9)
	ds_write_b128 v250, v[158:161] offset:27648
	s_waitcnt vmcnt(8)
	ds_write_b128 v251, v[190:193] offset:27648
	s_waitcnt lgkmcnt(0)
	s_barrier
	s_waitcnt vmcnt(7)
	ds_write_b128 v250, v[162:165] offset:36864
	s_waitcnt vmcnt(6)
	ds_write_b128 v251, v[194:197] offset:36864
	s_waitcnt vmcnt(5)
	ds_write_b128 v250, v[166:169] offset:46080
	s_waitcnt vmcnt(4)
	ds_write_b128 v251, v[198:201] offset:46080
	s_waitcnt vmcnt(3)
	ds_write_b128 v250, v[170:173] offset:55296
	s_waitcnt vmcnt(2)
	ds_write_b128 v251, v[202:205] offset:55296
	s_waitcnt vmcnt(1)
	ds_write_b128 v250, v[174:177] offset:64512
	s_waitcnt vmcnt(0)
	ds_write_b128 v251, v[206:209] offset:64512
	s_waitcnt lgkmcnt(0)
	s_barrier
	v_mov_b32_e32 v3, 0
	v_mov_b32_e32 v227, v223
	s_branch .LBB0_139

;     ...
;   const int srow = tid >> 3, skc = tid & 7;
;   const u16* Ag = A + (size_t)(m0 + srow) * K + skc * 8;
;   const u16* Bg[4];
; #pragma unroll
;   for (int i = 0; i < 4; ++i) { int n = n0 + srow + 64 * i; n = n < nmax ? n : nmax - 1; Bg[i] = Bt + (size_t)n * K + skc * 8; }
;   const int nk = nk_override ? nk_override : K / 64;
; #pragma unroll
;   for (int i = 0; i < 4; ++i) { ra[i] = *(const u32x4*)(Ag + (size_t)(64 * i) * K); rb[i] = *(const u32x4*)(Bg[i]); }
; #pragma unroll
;   for (int i = 0; i < 4; ++i) { *(u32x4*)(As0 + (srow + 64 * i) * LD + skc * 8) = ra[i]; *(u32x4*)(Bs0 + (srow + 64 * i) * LD + skc * 8) = rb[i]; }
;   if (nk > 1) {
; #pragma unroll
;     for (int i = 0; i < 4; ++i) { ra[i] = *(const u32x4*)(Ag + (size_t)(64 * i) * K + 64); rb[i] = *(const u32x4*)(Bg[i] + 64); }
;   }
;   for (int kt = 0; kt < nk; ++kt) {
;     __syncthreads();
;     if (kt + 1 < nk) {
;       u16* aw = As0 + ((kt + 1) & 1) * 256 * LD;
;       u16* bw = Bs0 + ((kt + 1) & 1) * 256 * LD;
; #pragma unroll
;       for (int i = 0; i < 4; ++i) { *(u32x4*)(aw + (srow + 64 * i) * LD + skc * 8) = ra[i]; *(u32x4*)(bw + (srow + 64 * i) * LD + skc * 8) = rb[i]; }
;     }
;     if (kt + 2 < nk) {
; #pragma unroll
;       for (int i = 0; i < 4; ++i) { ra[i] = *(const u32x4*)(Ag + (size_t)(64 * i) * K + (kt + 2) * 64); rb[i] = *(const u32x4*)(Bg[i] + (kt + 2) * 64); }
.LBB0_554:
	s_ashr_i32 s4, s3, 31
	s_lshr_b32 s4, s4, 30
	s_add_i32 s4, s3, s4
	s_and_b32 s5, s4, 0xfffffc
	s_sub_i32 s5, s3, s5
	v_mov_b32_e32 v66, v223
	s_lshl_b32 s34, s5, 8
	s_lshl_b32 s4, s4, 6
	v_ashrrev_i32_e32 v40, 3, v66
	v_add_u32_e32 v8, s34, v40
	s_and_b32 s38, s4, 0xffffff00
	v_lshlrev_b32_e32 v4, 4, v66
	v_min_i32_e32 v6, 0x3ff, v8
	s_add_i32 s38, s38, s44
	v_and_b32_e32 v150, 0x70, v4
	v_ashrrev_i32_e32 v7, 31, v6
	v_add_u32_e32 v2, s38, v40
	s_waitcnt lgkmcnt(0)
	v_lshl_add_u64 v[4:5], s[22:23], 0, v[150:151]
	v_lshlrev_b64 v[6:7], 11, v[6:7]
	v_ashrrev_i32_e32 v3, 31, v2
	v_lshl_add_u64 v[130:131], v[4:5], 0, v[6:7]
	v_min_i32_e32 v6, 0x3bf, v8
	v_lshlrev_b64 v[2:3], 11, v[2:3]
	v_ashrrev_i32_e32 v7, 31, v6
	v_lshlrev_b64 v[6:7], 11, v[6:7]
	v_lshl_add_u64 v[2:3], s[16:17], 0, v[2:3]
	v_lshl_add_u64 v[34:35], v[4:5], 0, v[6:7]
	v_min_i32_e32 v6, 0x37f, v8
	v_lshl_add_u64 v[132:133], v[2:3], 0, v[150:151]
	v_ashrrev_i32_e32 v7, 31, v6
	v_add_co_u32_e32 v134, vcc, s45, v132
	v_lshlrev_b64 v[6:7], 11, v[6:7]
	s_nop 0
	v_addc_co_u32_e32 v135, vcc, 0, v133, vcc
	v_lshl_add_u64 v[36:37], v[4:5], 0, v[6:7]
	v_min_i32_e32 v6, 0x33f, v8
	v_add_co_u32_e32 v14, vcc, s45, v34
	v_ashrrev_i32_e32 v7, 31, v6
	s_nop 0
	v_addc_co_u32_e32 v15, vcc, 0, v35, vcc
	v_lshlrev_b64 v[6:7], 11, v[6:7]
	v_add_co_u32_e32 v136, vcc, s46, v132
	v_lshl_add_u64 v[38:39], v[4:5], 0, v[6:7]
	global_load_dwordx4 v[2:5], v[132:133], off
	global_load_dwordx4 v[6:9], v[130:131], off
	v_addc_co_u32_e32 v137, vcc, 0, v133, vcc
	v_add_co_u32_e32 v22, vcc, s46, v36
	global_load_dwordx4 v[10:13], v[134:135], off
	global_load_dwordx4 v[18:21], v[136:137], off
	v_addc_co_u32_e32 v23, vcc, 0, v37, vcc
	global_load_dwordx4 v[14:17], v[14:15], off
	v_add_co_u32_e32 v138, vcc, s47, v132
	global_load_dwordx4 v[22:25], v[22:23], off
	s_nop 0
	v_addc_co_u32_e32 v139, vcc, 0, v133, vcc
	v_add_co_u32_e32 v30, vcc, s47, v38
	global_load_dwordx4 v[26:29], v[138:139], off
	s_nop 0
	v_addc_co_u32_e32 v31, vcc, 0, v39, vcc
	global_load_dwordx4 v[30:33], v[30:31], off
	v_mul_lo_u32 v40, v40, s52
	v_add3_u32 v149, 0, v150, v40
	v_lshl_add_u64 v[144:145], v[38:39], 0, s[30:31]
	v_add3_u32 v152, s51, v150, v40
	v_lshl_add_u64 v[140:141], v[34:35], 0, s[26:27]
	v_lshl_add_u64 v[142:143], v[36:37], 0, s[28:29]
	global_load_dwordx4 v[34:37], v[132:133], off offset:128
	global_load_dwordx4 v[38:41], v[130:131], off offset:128
	global_load_dwordx4 v[42:45], v[134:135], off offset:128
	global_load_dwordx4 v[46:49], v[136:137], off offset:128
	global_load_dwordx4 v[50:53], v[140:141], off offset:128
	global_load_dwordx4 v[54:57], v[142:143], off offset:128
	global_load_dwordx4 v[58:61], v[138:139], off offset:128
	global_load_dwordx4 v[62:65], v[144:145], off offset:128
	v_readfirstlane_b32 s5, v66
	s_and_b32 s4, s5, 0xc0
	s_ashr_i32 s5, s5, 1
	v_and_b32_e32 v146, 31, v66
	s_and_b32 s5, s5, 0xffffff80
	v_bfe_u32 v159, v66, 5, 1
	v_lshlrev_b32_e32 v150, 4, v159
	s_waitcnt vmcnt(15)
	ds_write_b128 v149, v[2:5]
	s_waitcnt vmcnt(14)
	ds_write_b128 v152, v[6:9]
	s_waitcnt vmcnt(13)
	ds_write_b128 v149, v[10:13] offset:9216
	s_waitcnt vmcnt(11)
	ds_write_b128 v152, v[14:17] offset:9216
	ds_write_b128 v149, v[18:21] offset:18432
	s_waitcnt vmcnt(10)
	ds_write_b128 v152, v[22:25] offset:18432
	s_waitcnt vmcnt(9)
	ds_write_b128 v149, v[26:29] offset:27648
	s_waitcnt vmcnt(8)
	ds_write_b128 v152, v[30:33] offset:27648
	s_waitcnt lgkmcnt(0)
	s_barrier
	v_or_b32_e32 v2, s5, v146
	v_mul_lo_u32 v2, v2, s52
	v_add3_u32 v147, 0, v2, v150
	v_or_b32_e32 v2, s4, v146
	v_mul_u32_u24_e32 v2, 0x90, v2
	v_add3_u32 v148, s51, v2, v150
	v_lshrrev_b32_e32 v153, 3, v223
	v_lshlrev_b32_e32 v153, 11, v153
	v_lshlrev_b32_e32 v2, 4, v223
	v_and_b32_e32 v2, 0x70, v2
	v_or_b32_e32 v153, v153, v2
	s_lshl_b32 s53, s38, 11
	s_add_u32 s74, s16, s53
	s_addc_u32 s75, s17, 0
	s_add_u32 s76, s74, 0x20000
	s_addc_u32 s77, s75, 0
	s_add_u32 s78, s74, 0x40000
	s_addc_u32 s79, s75, 0
	s_add_u32 s80, s74, 0x60000
	s_addc_u32 s81, s75, 0
	s_lshl_b32 s53, s34, 11
	s_add_u32 s82, s22, s53
	s_addc_u32 s83, s23, 0
	s_add_u32 s84, s82, 0x20000
	s_addc_u32 s85, s83, 0
	s_add_u32 s86, s82, 0x40000
	s_addc_u32 s87, s83, 0
	s_add_u32 s92, s82, 0x60000
	s_addc_u32 s93, s83, 0
	global_load_dwordx4 v[130:133], v153, s[74:75] offset:256 sc0
	global_load_dwordx4 v[176:179], v153, s[82:83] offset:256 sc0
	global_load_dwordx4 v[134:137], v153, s[76:77] offset:256 sc0
	global_load_dwordx4 v[180:183], v153, s[84:85] offset:256 sc0
	global_load_dwordx4 v[138:141], v153, s[78:79] offset:256 sc0
	global_load_dwordx4 v[184:187], v153, s[86:87] offset:256 sc0
	global_load_dwordx4 v[142:145], v153, s[80:81] offset:256 sc0
	global_load_dwordx4 v[188:191], v153, s[92:93] offset:256 sc0
	global_load_dwordx4 v[160:163], v153, s[74:75] offset:384 sc0
	global_load_dwordx4 v[192:195], v153, s[82:83] offset:384 sc0
	global_load_dwordx4 v[164:167], v153, s[76:77] offset:384 sc0
	global_load_dwordx4 v[196:199], v153, s[84:85] offset:384 sc0
	global_load_dwordx4 v[168:171], v153, s[78:79] offset:384 sc0
	global_load_dwordx4 v[200:203], v153, s[86:87] offset:384 sc0
	global_load_dwordx4 v[172:175], v153, s[80:81] offset:384 sc0
	global_load_dwordx4 v[204:207], v153, s[92:93] offset:384 sc0
	s_waitcnt vmcnt(23)
	ds_write_b128 v149, v[34:37] offset:36864
	s_waitcnt vmcnt(22)
	ds_write_b128 v152, v[38:41] offset:36864
	s_waitcnt vmcnt(21)
	ds_write_b128 v149, v[42:45] offset:46080
	s_waitcnt vmcnt(20)
	ds_write_b128 v149, v[46:49] offset:55296
	s_waitcnt vmcnt(19)
	ds_write_b128 v152, v[50:53] offset:46080
	s_waitcnt vmcnt(18)
	ds_write_b128 v152, v[54:57] offset:55296
	s_waitcnt vmcnt(17)
;     ...
;   for (int kt = 0; kt < nk; ++kt) {
;     __syncthreads();
;     if (kt + 1 < nk) {
;       u16* aw = As0 + ((kt + 1) & 1) * 256 * LD;
;       u16* bw = Bs0 + ((kt + 1) & 1) * 256 * LD;
; #pragma unroll
;       for (int i = 0; i < 4; ++i) { *(u32x4*)(aw + (srow + 64 * i) * LD + skc * 8) = ra[i]; *(u32x4*)(bw + (srow + 64 * i) * LD + skc * 8) = rb[i]; }
;     }
;     if (kt + 2 < nk) {
; #pragma unroll
;       for (int i = 0; i < 4; ++i) { ra[i] = *(const u32x4*)(Ag + (size_t)(64 * i) * K + (kt + 2) * 64); rb[i] = *(const u32x4*)(Bg[i] + (kt + 2) * 64); }
;     }
;     __builtin_amdgcn_sched_barrier(0);
;     const u16* as = As0 + (kt & 1) * 256 * LD + (wr * 128 + l31) * LD + h * 8;
;     const u16* bs = Bs0 + (kt & 1) * 256 * LD + (wc * 64 + l31) * LD + h * 8;
;     if (domma)
; #pragma unroll
;     for (int ks = 0; ks < 4; ++ks) {
;       bf16x8 wf[2], xf[4];
; #pragma unroll
;       for (int ct = 0; ct < 2; ++ct) wf[ct] = *(const bf16x8*)(bs + ct * 32 * LD + ks * 16);
; #pragma unroll
;       for (int tt = 0; tt < 4; ++tt) xf[tt] = *(const bf16x8*)(as + tt * 32 * LD + ks * 16);
; #pragma unroll
;       for (int ct = 0; ct < 2; ++ct)
; #pragma unroll
;         for (int tt = 0; tt < 4; ++tt) acc[ct][tt] = __builtin_amdgcn_mfma_f32_32x32x16_bf16(wf[ct], xf[tt], acc[ct][tt], 0, 0, 0);
;     }
	ds_write_b128 v149, v[58:61] offset:64512
	s_waitcnt vmcnt(16)
	ds_write_b128 v152, v[62:65] offset:64512
	ds_read_b128 v[208:211], v148
	ds_read_b128 v[228:231], v147
	ds_read_b128 v[212:215], v148 offset:4608
	ds_read_b128 v[232:235], v147 offset:4608
	ds_read_b128 v[236:239], v147 offset:9216
	ds_read_b128 v[240:243], v147 offset:13824
	s_waitcnt lgkmcnt(4)
	v_mfma_f32_32x32x16_bf16 v[98:113], v[208:211], v[228:231], 0
	ds_read_b128 v[216:219], v148 offset:32
	s_waitcnt lgkmcnt(4)
	v_mfma_f32_32x32x16_bf16 v[114:129], v[212:215], v[228:231], 0
	ds_read_b128 v[244:247], v147 offset:32
	s_waitcnt lgkmcnt(4)
	v_mfma_f32_32x32x16_bf16 v[82:97], v[208:211], v[232:235], 0
	ds_read_b128 v[224:227], v148 offset:4640
	v_mfma_f32_32x32x16_bf16 v[66:81], v[212:215], v[232:235], 0
	ds_read_b128 v[228:231], v147 offset:4640
	s_waitcnt lgkmcnt(5)
	v_mfma_f32_32x32x16_bf16 v[50:65], v[208:211], v[236:239], 0
	ds_read_b128 v[232:235], v147 offset:9248
	v_mfma_f32_32x32x16_bf16 v[34:49], v[212:215], v[236:239], 0
	s_waitcnt lgkmcnt(5)
	v_mfma_f32_32x32x16_bf16 v[18:33], v[208:211], v[240:243], 0
	ds_read_b128 v[236:239], v147 offset:13856
	v_mfma_f32_32x32x16_bf16 v[2:17], v[212:215], v[240:243], 0
	s_waitcnt lgkmcnt(4)
	v_mfma_f32_32x32x16_bf16 v[98:113], v[216:219], v[244:247], v[98:113]
	ds_read_b128 v[208:211], v148 offset:64
	s_waitcnt lgkmcnt(4)
	v_mfma_f32_32x32x16_bf16 v[114:129], v[224:227], v[244:247], v[114:129]
	ds_read_b128 v[240:243], v147 offset:64
	s_waitcnt lgkmcnt(4)
	v_mfma_f32_32x32x16_bf16 v[82:97], v[216:219], v[228:231], v[82:97]
	ds_read_b128 v[212:215], v148 offset:4672
	v_mfma_f32_32x32x16_bf16 v[66:81], v[224:227], v[228:231], v[66:81]
	ds_read_b128 v[244:247], v147 offset:4672
	s_waitcnt lgkmcnt(5)
	v_mfma_f32_32x32x16_bf16 v[50:65], v[216:219], v[232:235], v[50:65]
	ds_read_b128 v[228:231], v147 offset:9280
	v_mfma_f32_32x32x16_bf16 v[34:49], v[224:227], v[232:235], v[34:49]
	s_waitcnt lgkmcnt(5)
	v_mfma_f32_32x32x16_bf16 v[18:33], v[216:219], v[236:239], v[18:33]
	ds_read_b128 v[232:235], v147 offset:13888
	v_mfma_f32_32x32x16_bf16 v[2:17], v[224:227], v[236:239], v[2:17]
	s_waitcnt lgkmcnt(4)
	v_mfma_f32_32x32x16_bf16 v[98:113], v[208:211], v[240:243], v[98:113]
	ds_read_b128 v[216:219], v148 offset:96
	s_waitcnt lgkmcnt(4)
	v_mfma_f32_32x32x16_bf16 v[114:129], v[212:215], v[240:243], v[114:129]
	ds_read_b128 v[236:239], v147 offset:96
	s_waitcnt lgkmcnt(4)
	v_mfma_f32_32x32x16_bf16 v[82:97], v[208:211], v[244:247], v[82:97]
	ds_read_b128 v[224:227], v148 offset:4704
	v_mfma_f32_32x32x16_bf16 v[66:81], v[212:215], v[244:247], v[66:81]
	ds_read_b128 v[240:243], v147 offset:4704
	s_waitcnt lgkmcnt(5)
	v_mfma_f32_32x32x16_bf16 v[50:65], v[208:211], v[228:231], v[50:65]
	ds_read_b128 v[244:247], v147 offset:9312
	v_mfma_f32_32x32x16_bf16 v[34:49], v[212:215], v[228:231], v[34:49]
	s_waitcnt lgkmcnt(5)
	v_mfma_f32_32x32x16_bf16 v[18:33], v[208:211], v[232:235], v[18:33]
	ds_read_b128 v[228:231], v147 offset:13920
	v_mfma_f32_32x32x16_bf16 v[2:17], v[212:215], v[232:235], v[2:17]
	s_waitcnt lgkmcnt(4)
	v_mfma_f32_32x32x16_bf16 v[98:113], v[216:219], v[236:239], v[98:113]
	s_waitcnt lgkmcnt(3)
	v_mfma_f32_32x32x16_bf16 v[114:129], v[224:227], v[236:239], v[114:129]
	s_waitcnt lgkmcnt(2)
	v_mfma_f32_32x32x16_bf16 v[82:97], v[216:219], v[240:243], v[82:97]
	v_mfma_f32_32x32x16_bf16 v[66:81], v[224:227], v[240:243], v[66:81]
	s_waitcnt lgkmcnt(1)
	v_mfma_f32_32x32x16_bf16 v[50:65], v[216:219], v[244:247], v[50:65]
	v_mfma_f32_32x32x16_bf16 v[34:49], v[224:227], v[244:247], v[34:49]
	s_waitcnt lgkmcnt(0)
	v_mfma_f32_32x32x16_bf16 v[18:33], v[216:219], v[228:231], v[18:33]
	v_mfma_f32_32x32x16_bf16 v[2:17], v[224:227], v[228:231], v[2:17]
	s_barrier
	ds_read_b128 v[208:211], v148 offset:36864
	ds_read_b128 v[228:231], v147 offset:36864
	ds_read_b128 v[212:215], v148 offset:41472
	ds_read_b128 v[232:235], v147 offset:41472
	ds_read_b128 v[236:239], v147 offset:46080
	ds_read_b128 v[240:243], v147 offset:50688
	s_waitcnt lgkmcnt(4)
	v_mfma_f32_32x32x16_bf16 v[98:113], v[208:211], v[228:231], v[98:113]
	ds_read_b128 v[216:219], v148 offset:36896
	s_waitcnt lgkmcnt(4)
	v_mfma_f32_32x32x16_bf16 v[114:129], v[212:215], v[228:231], v[114:129]
	ds_read_b128 v[244:247], v147 offset:36896
	s_waitcnt lgkmcnt(4)
	v_mfma_f32_32x32x16_bf16 v[82:97], v[208:211], v[232:235], v[82:97]
	ds_read_b128 v[224:227], v148 offset:41504
	v_mfma_f32_32x32x16_bf16 v[66:81], v[212:215], v[232:235], v[66:81]
	ds_read_b128 v[228:231], v147 offset:41504
	s_waitcnt vmcnt(15)
	ds_write_b128 v149, v[130:133]
	s_waitcnt lgkmcnt(6)
	v_mfma_f32_32x32x16_bf16 v[50:65], v[208:211], v[236:239], v[50:65]
	ds_read_b128 v[232:235], v147 offset:46112
	v_mfma_f32_32x32x16_bf16 v[34:49], v[212:215], v[236:239], v[34:49]
	global_load_dwordx4 v[130:133], v153, s[74:75] offset:512 sc0
	s_waitcnt lgkmcnt(6)
	v_mfma_f32_32x32x16_bf16 v[18:33], v[208:211], v[240:243], v[18:33]
	ds_read_b128 v[236:239], v147 offset:50720
	s_waitcnt vmcnt(15)
	ds_write_b128 v152, v[176:179]
	v_mfma_f32_32x32x16_bf16 v[2:17], v[212:215], v[240:243], v[2:17]
	s_waitcnt lgkmcnt(6)
	v_mfma_f32_32x32x16_bf16 v[98:113], v[216:219], v[244:247], v[98:113]
	ds_read_b128 v[208:211], v148 offset:36928
	global_load_dwordx4 v[176:179], v153, s[82:83] offset:512 sc0
	s_waitcnt lgkmcnt(6)
	v_mfma_f32_32x32x16_bf16 v[114:129], v[224:227], v[244:247], v[114:129]
	ds_read_b128 v[240:243], v147 offset:36928
	s_waitcnt vmcnt(15)
	ds_write_b128 v149, v[134:137] offset:9216
	s_waitcnt lgkmcnt(7)
;     ...
;   for (int kt = 0; kt < nk; ++kt) {
;     __syncthreads();
;     if (kt + 1 < nk) {
;       u16* aw = As0 + ((kt + 1) & 1) * 256 * LD;
;       u16* bw = Bs0 + ((kt + 1) & 1) * 256 * LD;
; #pragma unroll
;       for (int i = 0; i < 4; ++i) { *(u32x4*)(aw + (srow + 64 * i) * LD + skc * 8) = ra[i]; *(u32x4*)(bw + (srow + 64 * i) * LD + skc * 8) = rb[i]; }
;     }
;     if (kt + 2 < nk) {
; #pragma unroll
;       for (int i = 0; i < 4; ++i) { ra[i] = *(const u32x4*)(Ag + (size_t)(64 * i) * K + (kt + 2) * 64); rb[i] = *(const u32x4*)(Bg[i] + (kt + 2) * 64); }
;     }
;     __builtin_amdgcn_sched_barrier(0);
;     const u16* as = As0 + (kt & 1) * 256 * LD + (wr * 128 + l31) * LD + h * 8;
;     const u16* bs = Bs0 + (kt & 1) * 256 * LD + (wc * 64 + l31) * LD + h * 8;
;     if (domma)
; #pragma unroll
;     for (int ks = 0; ks < 4; ++ks) {
;       bf16x8 wf[2], xf[4];
; #pragma unroll
;       for (int ct = 0; ct < 2; ++ct) wf[ct] = *(const bf16x8*)(bs + ct * 32 * LD + ks * 16);
; #pragma unroll
;       for (int tt = 0; tt < 4; ++tt) xf[tt] = *(const bf16x8*)(as + tt * 32 * LD + ks * 16);
; #pragma unroll
;       for (int ct = 0; ct < 2; ++ct)
; #pragma unroll
;         for (int tt = 0; tt < 4; ++tt) acc[ct][tt] = __builtin_amdgcn_mfma_f32_32x32x16_bf16(wf[ct], xf[tt], acc[ct][tt], 0, 0, 0);
;     }
	v_mfma_f32_32x32x16_bf16 v[82:97], v[216:219], v[228:231], v[82:97]
	ds_read_b128 v[212:215], v148 offset:41536
	v_mfma_f32_32x32x16_bf16 v[66:81], v[224:227], v[228:231], v[66:81]
	ds_read_b128 v[244:247], v147 offset:41536
	global_load_dwordx4 v[134:137], v153, s[76:77] offset:512 sc0
	s_waitcnt lgkmcnt(7)
	v_mfma_f32_32x32x16_bf16 v[50:65], v[216:219], v[232:235], v[50:65]
	ds_read_b128 v[228:231], v147 offset:46144
	s_waitcnt vmcnt(15)
	ds_write_b128 v152, v[180:183] offset:9216
	v_mfma_f32_32x32x16_bf16 v[34:49], v[224:227], v[232:235], v[34:49]
	s_waitcnt lgkmcnt(8)
	v_mfma_f32_32x32x16_bf16 v[18:33], v[216:219], v[236:239], v[18:33]
	ds_read_b128 v[232:235], v147 offset:50752
	global_load_dwordx4 v[180:183], v153, s[84:85] offset:512 sc0
	v_mfma_f32_32x32x16_bf16 v[2:17], v[224:227], v[236:239], v[2:17]
	s_waitcnt vmcnt(15)
	ds_write_b128 v149, v[138:141] offset:18432
	s_waitcnt lgkmcnt(7)
	v_mfma_f32_32x32x16_bf16 v[98:113], v[208:211], v[240:243], v[98:113]
	ds_read_b128 v[216:219], v148 offset:36960
	s_waitcnt lgkmcnt(6)
	v_mfma_f32_32x32x16_bf16 v[114:129], v[212:215], v[240:243], v[114:129]
	ds_read_b128 v[236:239], v147 offset:36960
	global_load_dwordx4 v[138:141], v153, s[78:79] offset:512 sc0
	s_waitcnt lgkmcnt(6)
	v_mfma_f32_32x32x16_bf16 v[82:97], v[208:211], v[244:247], v[82:97]
	ds_read_b128 v[224:227], v148 offset:41568
	s_waitcnt vmcnt(15)
	ds_write_b128 v152, v[184:187] offset:18432
	v_mfma_f32_32x32x16_bf16 v[66:81], v[212:215], v[244:247], v[66:81]
	ds_read_b128 v[240:243], v147 offset:41568
	s_waitcnt lgkmcnt(8)
	v_mfma_f32_32x32x16_bf16 v[50:65], v[208:211], v[228:231], v[50:65]
	ds_read_b128 v[244:247], v147 offset:46176
	global_load_dwordx4 v[184:187], v153, s[86:87] offset:512 sc0
	v_mfma_f32_32x32x16_bf16 v[34:49], v[212:215], v[228:231], v[34:49]
	s_waitcnt vmcnt(15)
	ds_write_b128 v149, v[142:145] offset:27648
	s_waitcnt lgkmcnt(8)
	v_mfma_f32_32x32x16_bf16 v[18:33], v[208:211], v[232:235], v[18:33]
	ds_read_b128 v[228:231], v147 offset:50784
	v_mfma_f32_32x32x16_bf16 v[2:17], v[212:215], v[232:235], v[2:17]
	global_load_dwordx4 v[142:145], v153, s[80:81] offset:512 sc0
	s_waitcnt lgkmcnt(6)
	v_mfma_f32_32x32x16_bf16 v[98:113], v[216:219], v[236:239], v[98:113]
	s_waitcnt vmcnt(15)
	ds_write_b128 v152, v[188:191] offset:27648
	s_waitcnt lgkmcnt(6)
	v_mfma_f32_32x32x16_bf16 v[114:129], v[224:227], v[236:239], v[114:129]
	s_waitcnt lgkmcnt(4)
	v_mfma_f32_32x32x16_bf16 v[82:97], v[216:219], v[240:243], v[82:97]
	global_load_dwordx4 v[188:191], v153, s[92:93] offset:512 sc0
	v_mfma_f32_32x32x16_bf16 v[66:81], v[224:227], v[240:243], v[66:81]
	s_waitcnt lgkmcnt(3)
	v_mfma_f32_32x32x16_bf16 v[50:65], v[216:219], v[244:247], v[50:65]
	v_mfma_f32_32x32x16_bf16 v[34:49], v[224:227], v[244:247], v[34:49]
	s_waitcnt lgkmcnt(1)
	v_mfma_f32_32x32x16_bf16 v[18:33], v[216:219], v[228:231], v[18:33]
	v_mfma_f32_32x32x16_bf16 v[2:17], v[224:227], v[228:231], v[2:17]
	s_waitcnt lgkmcnt(0)
	s_barrier
	ds_read_b128 v[208:211], v148
	ds_read_b128 v[228:231], v147
	ds_read_b128 v[212:215], v148 offset:4608
	ds_read_b128 v[232:235], v147 offset:4608
	ds_read_b128 v[236:239], v147 offset:9216
	ds_read_b128 v[240:243], v147 offset:13824
	s_waitcnt lgkmcnt(4)
	v_mfma_f32_32x32x16_bf16 v[98:113], v[208:211], v[228:231], v[98:113]
	ds_read_b128 v[216:219], v148 offset:32
	s_waitcnt lgkmcnt(4)
	v_mfma_f32_32x32x16_bf16 v[114:129], v[212:215], v[228:231], v[114:129]
	ds_read_b128 v[244:247], v147 offset:32
	s_waitcnt lgkmcnt(4)
	v_mfma_f32_32x32x16_bf16 v[82:97], v[208:211], v[232:235], v[82:97]
	ds_read_b128 v[224:227], v148 offset:4640
	v_mfma_f32_32x32x16_bf16 v[66:81], v[212:215], v[232:235], v[66:81]
	ds_read_b128 v[228:231], v147 offset:4640
	s_waitcnt vmcnt(15)
	ds_write_b128 v149, v[160:163] offset:36864
	s_waitcnt lgkmcnt(6)
	v_mfma_f32_32x32x16_bf16 v[50:65], v[208:211], v[236:239], v[50:65]
	ds_read_b128 v[232:235], v147 offset:9248
	v_mfma_f32_32x32x16_bf16 v[34:49], v[212:215], v[236:239], v[34:49]
	global_load_dwordx4 v[160:163], v153, s[74:75] offset:640 sc0
	s_waitcnt lgkmcnt(6)
	v_mfma_f32_32x32x16_bf16 v[18:33], v[208:211], v[240:243], v[18:33]
	ds_read_b128 v[236:239], v147 offset:13856
	s_waitcnt vmcnt(15)
	ds_write_b128 v152, v[192:195] offset:36864
	v_mfma_f32_32x32x16_bf16 v[2:17], v[212:215], v[240:243], v[2:17]
	s_waitcnt lgkmcnt(6)
	v_mfma_f32_32x32x16_bf16 v[98:113], v[216:219], v[244:247], v[98:113]
	ds_read_b128 v[208:211], v148 offset:64
	global_load_dwordx4 v[192:195], v153, s[82:83] offset:640 sc0
	s_waitcnt lgkmcnt(6)
	v_mfma_f32_32x32x16_bf16 v[114:129], v[224:227], v[244:247], v[114:129]
	ds_read_b128 v[240:243], v147 offset:64
	s_waitcnt vmcnt(15)
	ds_write_b128 v149, v[164:167] offset:46080
	s_waitcnt lgkmcnt(7)
	v_mfma_f32_32x32x16_bf16 v[82:97], v[216:219], v[228:231], v[82:97]
	ds_read_b128 v[212:215], v148 offset:4672
	v_mfma_f32_32x32x16_bf16 v[66:81], v[224:227], v[228:231], v[66:81]
	ds_read_b128 v[244:247], v147 offset:4672
	global_load_dwordx4 v[164:167], v153, s[76:77] offset:640 sc0
	s_waitcnt lgkmcnt(7)
	v_mfma_f32_32x32x16_bf16 v[50:65], v[216:219], v[232:235], v[50:65]
	ds_read_b128 v[228:231], v147 offset:9280
	s_waitcnt vmcnt(15)
	ds_write_b128 v152, v[196:199] offset:46080
	v_mfma_f32_32x32x16_bf16 v[34:49], v[224:227], v[232:235], v[34:49]
	s_waitcnt lgkmcnt(8)
	v_mfma_f32_32x32x16_bf16 v[18:33], v[216:219], v[236:239], v[18:33]
	ds_read_b128 v[232:235], v147 offset:13888
	global_load_dwordx4 v[196:199], v153, s[84:85] offset:640 sc0
	v_mfma_f32_32x32x16_bf16 v[2:17], v[224:227], v[236:239], v[2:17]
	s_waitcnt vmcnt(15)
	ds_write_b128 v149, v[168:171] offset:55296
	s_waitcnt lgkmcnt(7)
;     ...
;   for (int kt = 0; kt < nk; ++kt) {
;     __syncthreads();
;     if (kt + 1 < nk) {
;       u16* aw = As0 + ((kt + 1) & 1) * 256 * LD;
;       u16* bw = Bs0 + ((kt + 1) & 1) * 256 * LD;
; #pragma unroll
;       for (int i = 0; i < 4; ++i) { *(u32x4*)(aw + (srow + 64 * i) * LD + skc * 8) = ra[i]; *(u32x4*)(bw + (srow + 64 * i) * LD + skc * 8) = rb[i]; }
;     }
;     if (kt + 2 < nk) {
; #pragma unroll
;       for (int i = 0; i < 4; ++i) { ra[i] = *(const u32x4*)(Ag + (size_t)(64 * i) * K + (kt + 2) * 64); rb[i] = *(const u32x4*)(Bg[i] + (kt + 2) * 64); }
;     }
;     __builtin_amdgcn_sched_barrier(0);
;     const u16* as = As0 + (kt & 1) * 256 * LD + (wr * 128 + l31) * LD + h * 8;
;     const u16* bs = Bs0 + (kt & 1) * 256 * LD + (wc * 64 + l31) * LD + h * 8;
;     if (domma)
; #pragma unroll
;     for (int ks = 0; ks < 4; ++ks) {
;       bf16x8 wf[2], xf[4];
; #pragma unroll
;       for (int ct = 0; ct < 2; ++ct) wf[ct] = *(const bf16x8*)(bs + ct * 32 * LD + ks * 16);
; #pragma unroll
;       for (int tt = 0; tt < 4; ++tt) xf[tt] = *(const bf16x8*)(as + tt * 32 * LD + ks * 16);
; #pragma unroll
;       for (int ct = 0; ct < 2; ++ct)
; #pragma unroll
;         for (int tt = 0; tt < 4; ++tt) acc[ct][tt] = __builtin_amdgcn_mfma_f32_32x32x16_bf16(wf[ct], xf[tt], acc[ct][tt], 0, 0, 0);
;     }
	v_mfma_f32_32x32x16_bf16 v[98:113], v[208:211], v[240:243], v[98:113]
	ds_read_b128 v[216:219], v148 offset:96
	s_waitcnt lgkmcnt(6)
	v_mfma_f32_32x32x16_bf16 v[114:129], v[212:215], v[240:243], v[114:129]
	ds_read_b128 v[236:239], v147 offset:96
	global_load_dwordx4 v[168:171], v153, s[78:79] offset:640 sc0
	s_waitcnt lgkmcnt(6)
	v_mfma_f32_32x32x16_bf16 v[82:97], v[208:211], v[244:247], v[82:97]
	ds_read_b128 v[224:227], v148 offset:4704
	s_waitcnt vmcnt(15)
	ds_write_b128 v152, v[200:203] offset:55296
	v_mfma_f32_32x32x16_bf16 v[66:81], v[212:215], v[244:247], v[66:81]
	ds_read_b128 v[240:243], v147 offset:4704
	s_waitcnt lgkmcnt(8)
	v_mfma_f32_32x32x16_bf16 v[50:65], v[208:211], v[228:231], v[50:65]
	ds_read_b128 v[244:247], v147 offset:9312
	global_load_dwordx4 v[200:203], v153, s[86:87] offset:640 sc0
	v_mfma_f32_32x32x16_bf16 v[34:49], v[212:215], v[228:231], v[34:49]
	s_waitcnt vmcnt(15)
	ds_write_b128 v149, v[172:175] offset:64512
	s_waitcnt lgkmcnt(8)
	v_mfma_f32_32x32x16_bf16 v[18:33], v[208:211], v[232:235], v[18:33]
	ds_read_b128 v[228:231], v147 offset:13920
	v_mfma_f32_32x32x16_bf16 v[2:17], v[212:215], v[232:235], v[2:17]
	global_load_dwordx4 v[172:175], v153, s[80:81] offset:640 sc0
	s_waitcnt lgkmcnt(6)
	v_mfma_f32_32x32x16_bf16 v[98:113], v[216:219], v[236:239], v[98:113]
	s_waitcnt vmcnt(15)
	ds_write_b128 v152, v[204:207] offset:64512
	s_waitcnt lgkmcnt(6)
	v_mfma_f32_32x32x16_bf16 v[114:129], v[224:227], v[236:239], v[114:129]
	s_waitcnt lgkmcnt(4)
	v_mfma_f32_32x32x16_bf16 v[82:97], v[216:219], v[240:243], v[82:97]
	global_load_dwordx4 v[204:207], v153, s[92:93] offset:640 sc0
	v_mfma_f32_32x32x16_bf16 v[66:81], v[224:227], v[240:243], v[66:81]
	s_waitcnt lgkmcnt(3)
	v_mfma_f32_32x32x16_bf16 v[50:65], v[216:219], v[244:247], v[50:65]
	v_mfma_f32_32x32x16_bf16 v[34:49], v[224:227], v[244:247], v[34:49]
	s_waitcnt lgkmcnt(1)
	v_mfma_f32_32x32x16_bf16 v[18:33], v[216:219], v[228:231], v[18:33]
	v_mfma_f32_32x32x16_bf16 v[2:17], v[224:227], v[228:231], v[2:17]
	s_waitcnt lgkmcnt(0)
	s_barrier
	ds_read_b128 v[208:211], v148 offset:36864
	ds_read_b128 v[228:231], v147 offset:36864
	ds_read_b128 v[212:215], v148 offset:41472
	ds_read_b128 v[232:235], v147 offset:41472
	ds_read_b128 v[236:239], v147 offset:46080
	ds_read_b128 v[240:243], v147 offset:50688
	s_waitcnt lgkmcnt(4)
	v_mfma_f32_32x32x16_bf16 v[98:113], v[208:211], v[228:231], v[98:113]
	ds_read_b128 v[216:219], v148 offset:36896
	s_waitcnt lgkmcnt(4)
	v_mfma_f32_32x32x16_bf16 v[114:129], v[212:215], v[228:231], v[114:129]
	ds_read_b128 v[244:247], v147 offset:36896
	s_waitcnt lgkmcnt(4)
	v_mfma_f32_32x32x16_bf16 v[82:97], v[208:211], v[232:235], v[82:97]
	ds_read_b128 v[224:227], v148 offset:41504
	v_mfma_f32_32x32x16_bf16 v[66:81], v[212:215], v[232:235], v[66:81]
	ds_read_b128 v[228:231], v147 offset:41504
	s_waitcnt vmcnt(15)
	ds_write_b128 v149, v[130:133]
	s_waitcnt lgkmcnt(6)
	v_mfma_f32_32x32x16_bf16 v[50:65], v[208:211], v[236:239], v[50:65]
	ds_read_b128 v[232:235], v147 offset:46112
	v_mfma_f32_32x32x16_bf16 v[34:49], v[212:215], v[236:239], v[34:49]
	global_load_dwordx4 v[130:133], v153, s[74:75] offset:768 sc0
	s_waitcnt lgkmcnt(6)
	v_mfma_f32_32x32x16_bf16 v[18:33], v[208:211], v[240:243], v[18:33]
	ds_read_b128 v[236:239], v147 offset:50720
	s_waitcnt vmcnt(15)
	ds_write_b128 v152, v[176:179]
	v_mfma_f32_32x32x16_bf16 v[2:17], v[212:215], v[240:243], v[2:17]
	s_waitcnt lgkmcnt(6)
	v_mfma_f32_32x32x16_bf16 v[98:113], v[216:219], v[244:247], v[98:113]
	ds_read_b128 v[208:211], v148 offset:36928
	global_load_dwordx4 v[176:179], v153, s[82:83] offset:768 sc0
	s_waitcnt lgkmcnt(6)
	v_mfma_f32_32x32x16_bf16 v[114:129], v[224:227], v[244:247], v[114:129]
	ds_read_b128 v[240:243], v147 offset:36928
	s_waitcnt vmcnt(15)
	ds_write_b128 v149, v[134:137] offset:9216
	s_waitcnt lgkmcnt(7)
	v_mfma_f32_32x32x16_bf16 v[82:97], v[216:219], v[228:231], v[82:97]
	ds_read_b128 v[212:215], v148 offset:41536
	v_mfma_f32_32x32x16_bf16 v[66:81], v[224:227], v[228:231], v[66:81]
	ds_read_b128 v[244:247], v147 offset:41536
	global_load_dwordx4 v[134:137], v153, s[76:77] offset:768 sc0
	s_waitcnt lgkmcnt(7)
	v_mfma_f32_32x32x16_bf16 v[50:65], v[216:219], v[232:235], v[50:65]
	ds_read_b128 v[228:231], v147 offset:46144
	s_waitcnt vmcnt(15)
	ds_write_b128 v152, v[180:183] offset:9216
	v_mfma_f32_32x32x16_bf16 v[34:49], v[224:227], v[232:235], v[34:49]
	s_waitcnt lgkmcnt(8)
	v_mfma_f32_32x32x16_bf16 v[18:33], v[216:219], v[236:239], v[18:33]
	ds_read_b128 v[232:235], v147 offset:50752
	global_load_dwordx4 v[180:183], v153, s[84:85] offset:768 sc0
	v_mfma_f32_32x32x16_bf16 v[2:17], v[224:227], v[236:239], v[2:17]
	s_waitcnt vmcnt(15)
	ds_write_b128 v149, v[138:141] offset:18432
	s_waitcnt lgkmcnt(7)
	v_mfma_f32_32x32x16_bf16 v[98:113], v[208:211], v[240:243], v[98:113]
	ds_read_b128 v[216:219], v148 offset:36960
	s_waitcnt lgkmcnt(6)
	v_mfma_f32_32x32x16_bf16 v[114:129], v[212:215], v[240:243], v[114:129]
	ds_read_b128 v[236:239], v147 offset:36960
	global_load_dwordx4 v[138:141], v153, s[78:79] offset:768 sc0
	s_waitcnt lgkmcnt(6)
	v_mfma_f32_32x32x16_bf16 v[82:97], v[208:211], v[244:247], v[82:97]
	ds_read_b128 v[224:227], v148 offset:41568
	s_waitcnt vmcnt(15)
	ds_write_b128 v152, v[184:187] offset:18432
	v_mfma_f32_32x32x16_bf16 v[66:81], v[212:215], v[244:247], v[66:81]
	ds_read_b128 v[240:243], v147 offset:41568
	s_waitcnt lgkmcnt(8)
	v_mfma_f32_32x32x16_bf16 v[50:65], v[208:211], v[228:231], v[50:65]
	ds_read_b128 v[244:247], v147 offset:46176
	global_load_dwordx4 v[184:187], v153, s[86:87] offset:768 sc0
	v_mfma_f32_32x32x16_bf16 v[34:49], v[212:215], v[228:231], v[34:49]
	s_waitcnt vmcnt(15)
	ds_write_b128 v149, v[142:145] offset:27648
	s_waitcnt lgkmcnt(8)
	v_mfma_f32_32x32x16_bf16 v[18:33], v[208:211], v[232:235], v[18:33]
	ds_read_b128 v[228:231], v147 offset:50784
	v_mfma_f32_32x32x16_bf16 v[2:17], v[212:215], v[232:235], v[2:17]
	global_load_dwordx4 v[142:145], v153, s[80:81] offset:768 sc0
	s_waitcnt lgkmcnt(6)
	v_mfma_f32_32x32x16_bf16 v[98:113], v[216:219], v[236:239], v[98:113]
	s_waitcnt vmcnt(15)
	ds_write_b128 v152, v[188:191] offset:27648
	s_waitcnt lgkmcnt(6)
	v_mfma_f32_32x32x16_bf16 v[114:129], v[224:227], v[236:239], v[114:129]
	s_waitcnt lgkmcnt(4)
	v_mfma_f32_32x32x16_bf16 v[82:97], v[216:219], v[240:243], v[82:97]
	global_load_dwordx4 v[188:191], v153, s[92:93] offset:768 sc0
	v_mfma_f32_32x32x16_bf16 v[66:81], v[224:227], v[240:243], v[66:81]
	s_waitcnt lgkmcnt(3)
	v_mfma_f32_32x32x16_bf16 v[50:65], v[216:219], v[244:247], v[50:65]
	v_mfma_f32_32x32x16_bf16 v[34:49], v[224:227], v[244:247], v[34:49]
	s_waitcnt lgkmcnt(1)
	v_mfma_f32_32x32x16_bf16 v[18:33], v[216:219], v[228:231], v[18:33]
	v_mfma_f32_32x32x16_bf16 v[2:17], v[224:227], v[228:231], v[2:17]
	s_waitcnt lgkmcnt(0)
	s_barrier
;     ...
;   for (int kt = 0; kt < nk; ++kt) {
;     __syncthreads();
;     if (kt + 1 < nk) {
;       u16* aw = As0 + ((kt + 1) & 1) * 256 * LD;
;       u16* bw = Bs0 + ((kt + 1) & 1) * 256 * LD;
; #pragma unroll
;       for (int i = 0; i < 4; ++i) { *(u32x4*)(aw + (srow + 64 * i) * LD + skc * 8) = ra[i]; *(u32x4*)(bw + (srow + 64 * i) * LD + skc * 8) = rb[i]; }
;     }
;     if (kt + 2 < nk) {
; #pragma unroll
;       for (int i = 0; i < 4; ++i) { ra[i] = *(const u32x4*)(Ag + (size_t)(64 * i) * K + (kt + 2) * 64); rb[i] = *(const u32x4*)(Bg[i] + (kt + 2) * 64); }
;     }
;     __builtin_amdgcn_sched_barrier(0);
;     const u16* as = As0 + (kt & 1) * 256 * LD + (wr * 128 + l31) * LD + h * 8;
;     const u16* bs = Bs0 + (kt & 1) * 256 * LD + (wc * 64 + l31) * LD + h * 8;
;     if (domma)
; #pragma unroll
;     for (int ks = 0; ks < 4; ++ks) {
;       bf16x8 wf[2], xf[4];
; #pragma unroll
;       for (int ct = 0; ct < 2; ++ct) wf[ct] = *(const bf16x8*)(bs + ct * 32 * LD + ks * 16);
; #pragma unroll
;       for (int tt = 0; tt < 4; ++tt) xf[tt] = *(const bf16x8*)(as + tt * 32 * LD + ks * 16);
; #pragma unroll
;       for (int ct = 0; ct < 2; ++ct)
; #pragma unroll
;         for (int tt = 0; tt < 4; ++tt) acc[ct][tt] = __builtin_amdgcn_mfma_f32_32x32x16_bf16(wf[ct], xf[tt], acc[ct][tt], 0, 0, 0);
;     }
	ds_read_b128 v[208:211], v148
	ds_read_b128 v[228:231], v147
	ds_read_b128 v[212:215], v148 offset:4608
	ds_read_b128 v[232:235], v147 offset:4608
	ds_read_b128 v[236:239], v147 offset:9216
	ds_read_b128 v[240:243], v147 offset:13824
	s_waitcnt lgkmcnt(4)
	v_mfma_f32_32x32x16_bf16 v[98:113], v[208:211], v[228:231], v[98:113]
	ds_read_b128 v[216:219], v148 offset:32
	s_waitcnt lgkmcnt(4)
	v_mfma_f32_32x32x16_bf16 v[114:129], v[212:215], v[228:231], v[114:129]
	ds_read_b128 v[244:247], v147 offset:32
	s_waitcnt lgkmcnt(4)
	v_mfma_f32_32x32x16_bf16 v[82:97], v[208:211], v[232:235], v[82:97]
	ds_read_b128 v[224:227], v148 offset:4640
	v_mfma_f32_32x32x16_bf16 v[66:81], v[212:215], v[232:235], v[66:81]
	ds_read_b128 v[228:231], v147 offset:4640
	s_waitcnt vmcnt(15)
	ds_write_b128 v149, v[160:163] offset:36864
	s_waitcnt lgkmcnt(6)
	v_mfma_f32_32x32x16_bf16 v[50:65], v[208:211], v[236:239], v[50:65]
	ds_read_b128 v[232:235], v147 offset:9248
	v_mfma_f32_32x32x16_bf16 v[34:49], v[212:215], v[236:239], v[34:49]
	global_load_dwordx4 v[160:163], v153, s[74:75] offset:896 sc0
	s_waitcnt lgkmcnt(6)
	v_mfma_f32_32x32x16_bf16 v[18:33], v[208:211], v[240:243], v[18:33]
	ds_read_b128 v[236:239], v147 offset:13856
	s_waitcnt vmcnt(15)
	ds_write_b128 v152, v[192:195] offset:36864
	v_mfma_f32_32x32x16_bf16 v[2:17], v[212:215], v[240:243], v[2:17]
	s_waitcnt lgkmcnt(6)
	v_mfma_f32_32x32x16_bf16 v[98:113], v[216:219], v[244:247], v[98:113]
	ds_read_b128 v[208:211], v148 offset:64
	global_load_dwordx4 v[192:195], v153, s[82:83] offset:896 sc0
	s_waitcnt lgkmcnt(6)
	v_mfma_f32_32x32x16_bf16 v[114:129], v[224:227], v[244:247], v[114:129]
	ds_read_b128 v[240:243], v147 offset:64
	s_waitcnt vmcnt(15)
	ds_write_b128 v149, v[164:167] offset:46080
	s_waitcnt lgkmcnt(7)
	v_mfma_f32_32x32x16_bf16 v[82:97], v[216:219], v[228:231], v[82:97]
	ds_read_b128 v[212:215], v148 offset:4672
	v_mfma_f32_32x32x16_bf16 v[66:81], v[224:227], v[228:231], v[66:81]
	ds_read_b128 v[244:247], v147 offset:4672
	global_load_dwordx4 v[164:167], v153, s[76:77] offset:896 sc0
	s_waitcnt lgkmcnt(7)
	v_mfma_f32_32x32x16_bf16 v[50:65], v[216:219], v[232:235], v[50:65]
	ds_read_b128 v[228:231], v147 offset:9280
	s_waitcnt vmcnt(15)
	ds_write_b128 v152, v[196:199] offset:46080
	v_mfma_f32_32x32x16_bf16 v[34:49], v[224:227], v[232:235], v[34:49]
	s_waitcnt lgkmcnt(8)
	v_mfma_f32_32x32x16_bf16 v[18:33], v[216:219], v[236:239], v[18:33]
	ds_read_b128 v[232:235], v147 offset:13888
	global_load_dwordx4 v[196:199], v153, s[84:85] offset:896 sc0
	v_mfma_f32_32x32x16_bf16 v[2:17], v[224:227], v[236:239], v[2:17]
	s_waitcnt vmcnt(15)
	ds_write_b128 v149, v[168:171] offset:55296
	s_waitcnt lgkmcnt(7)
	v_mfma_f32_32x32x16_bf16 v[98:113], v[208:211], v[240:243], v[98:113]
	ds_read_b128 v[216:219], v148 offset:96
	s_waitcnt lgkmcnt(6)
	v_mfma_f32_32x32x16_bf16 v[114:129], v[212:215], v[240:243], v[114:129]
	ds_read_b128 v[236:239], v147 offset:96
	global_load_dwordx4 v[168:171], v153, s[78:79] offset:896 sc0
	s_waitcnt lgkmcnt(6)
	v_mfma_f32_32x32x16_bf16 v[82:97], v[208:211], v[244:247], v[82:97]
	ds_read_b128 v[224:227], v148 offset:4704
	s_waitcnt vmcnt(15)
	ds_write_b128 v152, v[200:203] offset:55296
	v_mfma_f32_32x32x16_bf16 v[66:81], v[212:215], v[244:247], v[66:81]
	ds_read_b128 v[240:243], v147 offset:4704
	s_waitcnt lgkmcnt(8)
	v_mfma_f32_32x32x16_bf16 v[50:65], v[208:211], v[228:231], v[50:65]
	ds_read_b128 v[244:247], v147 offset:9312
	global_load_dwordx4 v[200:203], v153, s[86:87] offset:896 sc0
	v_mfma_f32_32x32x16_bf16 v[34:49], v[212:215], v[228:231], v[34:49]
	s_waitcnt vmcnt(15)
	ds_write_b128 v149, v[172:175] offset:64512
	s_waitcnt lgkmcnt(8)
	v_mfma_f32_32x32x16_bf16 v[18:33], v[208:211], v[232:235], v[18:33]
	ds_read_b128 v[228:231], v147 offset:13920
	v_mfma_f32_32x32x16_bf16 v[2:17], v[212:215], v[232:235], v[2:17]
	global_load_dwordx4 v[172:175], v153, s[80:81] offset:896 sc0
	s_waitcnt lgkmcnt(6)
	v_mfma_f32_32x32x16_bf16 v[98:113], v[216:219], v[236:239], v[98:113]
	s_waitcnt vmcnt(15)
	ds_write_b128 v152, v[204:207] offset:64512
	s_waitcnt lgkmcnt(6)
	v_mfma_f32_32x32x16_bf16 v[114:129], v[224:227], v[236:239], v[114:129]
	s_waitcnt lgkmcnt(4)
	v_mfma_f32_32x32x16_bf16 v[82:97], v[216:219], v[240:243], v[82:97]
	global_load_dwordx4 v[204:207], v153, s[92:93] offset:896 sc0
	v_mfma_f32_32x32x16_bf16 v[66:81], v[224:227], v[240:243], v[66:81]
	s_waitcnt lgkmcnt(3)
	v_mfma_f32_32x32x16_bf16 v[50:65], v[216:219], v[244:247], v[50:65]
	v_mfma_f32_32x32x16_bf16 v[34:49], v[224:227], v[244:247], v[34:49]
	s_waitcnt lgkmcnt(1)
	v_mfma_f32_32x32x16_bf16 v[18:33], v[216:219], v[228:231], v[18:33]
	v_mfma_f32_32x32x16_bf16 v[2:17], v[224:227], v[228:231], v[2:17]
	s_waitcnt lgkmcnt(0)
	s_barrier
;     ...
;   for (int kt = 0; kt < nk; ++kt) {
;     __syncthreads();
;     if (kt + 1 < nk) {
;       u16* aw = As0 + ((kt + 1) & 1) * 256 * LD;
;       u16* bw = Bs0 + ((kt + 1) & 1) * 256 * LD;
; #pragma unroll
;       for (int i = 0; i < 4; ++i) { *(u32x4*)(aw + (srow + 64 * i) * LD + skc * 8) = ra[i]; *(u32x4*)(bw + (srow + 64 * i) * LD + skc * 8) = rb[i]; }
;     }
;     if (kt + 2 < nk) {
; #pragma unroll
;       for (int i = 0; i < 4; ++i) { ra[i] = *(const u32x4*)(Ag + (size_t)(64 * i) * K + (kt + 2) * 64); rb[i] = *(const u32x4*)(Bg[i] + (kt + 2) * 64); }
;     }
;     __builtin_amdgcn_sched_barrier(0);
;     const u16* as = As0 + (kt & 1) * 256 * LD + (wr * 128 + l31) * LD + h * 8;
;     const u16* bs = Bs0 + (kt & 1) * 256 * LD + (wc * 64 + l31) * LD + h * 8;
;     if (domma)
; #pragma unroll
;     for (int ks = 0; ks < 4; ++ks) {
;       bf16x8 wf[2], xf[4];
; #pragma unroll
;       for (int ct = 0; ct < 2; ++ct) wf[ct] = *(const bf16x8*)(bs + ct * 32 * LD + ks * 16);
; #pragma unroll
;       for (int tt = 0; tt < 4; ++tt) xf[tt] = *(const bf16x8*)(as + tt * 32 * LD + ks * 16);
; #pragma unroll
;       for (int ct = 0; ct < 2; ++ct)
; #pragma unroll
;         for (int tt = 0; tt < 4; ++tt) acc[ct][tt] = __builtin_amdgcn_mfma_f32_32x32x16_bf16(wf[ct], xf[tt], acc[ct][tt], 0, 0, 0);
;     }
	ds_read_b128 v[208:211], v148 offset:36864
	ds_read_b128 v[228:231], v147 offset:36864
	ds_read_b128 v[212:215], v148 offset:41472
	ds_read_b128 v[232:235], v147 offset:41472
	ds_read_b128 v[236:239], v147 offset:46080
	ds_read_b128 v[240:243], v147 offset:50688
	s_waitcnt lgkmcnt(4)
	v_mfma_f32_32x32x16_bf16 v[98:113], v[208:211], v[228:231], v[98:113]
	ds_read_b128 v[216:219], v148 offset:36896
	s_waitcnt lgkmcnt(4)
	v_mfma_f32_32x32x16_bf16 v[114:129], v[212:215], v[228:231], v[114:129]
	ds_read_b128 v[244:247], v147 offset:36896
	s_waitcnt lgkmcnt(4)
	v_mfma_f32_32x32x16_bf16 v[82:97], v[208:211], v[232:235], v[82:97]
	ds_read_b128 v[224:227], v148 offset:41504
	v_mfma_f32_32x32x16_bf16 v[66:81], v[212:215], v[232:235], v[66:81]
	ds_read_b128 v[228:231], v147 offset:41504
	s_waitcnt vmcnt(15)
	ds_write_b128 v149, v[130:133]
	s_waitcnt lgkmcnt(6)
	v_mfma_f32_32x32x16_bf16 v[50:65], v[208:211], v[236:239], v[50:65]
	ds_read_b128 v[232:235], v147 offset:46112
	v_mfma_f32_32x32x16_bf16 v[34:49], v[212:215], v[236:239], v[34:49]
	global_load_dwordx4 v[130:133], v153, s[74:75] offset:1024 sc0
	s_waitcnt lgkmcnt(6)
	v_mfma_f32_32x32x16_bf16 v[18:33], v[208:211], v[240:243], v[18:33]
	ds_read_b128 v[236:239], v147 offset:50720
	s_waitcnt vmcnt(15)
	ds_write_b128 v152, v[176:179]
	v_mfma_f32_32x32x16_bf16 v[2:17], v[212:215], v[240:243], v[2:17]
	s_waitcnt lgkmcnt(6)
	v_mfma_f32_32x32x16_bf16 v[98:113], v[216:219], v[244:247], v[98:113]
	ds_read_b128 v[208:211], v148 offset:36928
	global_load_dwordx4 v[176:179], v153, s[82:83] offset:1024 sc0
	s_waitcnt lgkmcnt(6)
	v_mfma_f32_32x32x16_bf16 v[114:129], v[224:227], v[244:247], v[114:129]
	ds_read_b128 v[240:243], v147 offset:36928
	s_waitcnt vmcnt(15)
	ds_write_b128 v149, v[134:137] offset:9216
	s_waitcnt lgkmcnt(7)
	v_mfma_f32_32x32x16_bf16 v[82:97], v[216:219], v[228:231], v[82:97]
	ds_read_b128 v[212:215], v148 offset:41536
	v_mfma_f32_32x32x16_bf16 v[66:81], v[224:227], v[228:231], v[66:81]
	ds_read_b128 v[244:247], v147 offset:41536
	global_load_dwordx4 v[134:137], v153, s[76:77] offset:1024 sc0
	s_waitcnt lgkmcnt(7)
	v_mfma_f32_32x32x16_bf16 v[50:65], v[216:219], v[232:235], v[50:65]
	ds_read_b128 v[228:231], v147 offset:46144
	s_waitcnt vmcnt(15)
	ds_write_b128 v152, v[180:183] offset:9216
	v_mfma_f32_32x32x16_bf16 v[34:49], v[224:227], v[232:235], v[34:49]
	s_waitcnt lgkmcnt(8)
	v_mfma_f32_32x32x16_bf16 v[18:33], v[216:219], v[236:239], v[18:33]
	ds_read_b128 v[232:235], v147 offset:50752
	global_load_dwordx4 v[180:183], v153, s[84:85] offset:1024 sc0
	v_mfma_f32_32x32x16_bf16 v[2:17], v[224:227], v[236:239], v[2:17]
	s_waitcnt vmcnt(15)
	ds_write_b128 v149, v[138:141] offset:18432
	s_waitcnt lgkmcnt(7)
	v_mfma_f32_32x32x16_bf16 v[98:113], v[208:211], v[240:243], v[98:113]
	ds_read_b128 v[216:219], v148 offset:36960
	s_waitcnt lgkmcnt(6)
	v_mfma_f32_32x32x16_bf16 v[114:129], v[212:215], v[240:243], v[114:129]
	ds_read_b128 v[236:239], v147 offset:36960
	global_load_dwordx4 v[138:141], v153, s[78:79] offset:1024 sc0
	s_waitcnt lgkmcnt(6)
	v_mfma_f32_32x32x16_bf16 v[82:97], v[208:211], v[244:247], v[82:97]
	ds_read_b128 v[224:227], v148 offset:41568
	s_waitcnt vmcnt(15)
	ds_write_b128 v152, v[184:187] offset:18432
	v_mfma_f32_32x32x16_bf16 v[66:81], v[212:215], v[244:247], v[66:81]
	ds_read_b128 v[240:243], v147 offset:41568
	s_waitcnt lgkmcnt(8)
	v_mfma_f32_32x32x16_bf16 v[50:65], v[208:211], v[228:231], v[50:65]
	ds_read_b128 v[244:247], v147 offset:46176
	global_load_dwordx4 v[184:187], v153, s[86:87] offset:1024 sc0
	v_mfma_f32_32x32x16_bf16 v[34:49], v[212:215], v[228:231], v[34:49]
	s_waitcnt vmcnt(15)
	ds_write_b128 v149, v[142:145] offset:27648
	s_waitcnt lgkmcnt(8)
	v_mfma_f32_32x32x16_bf16 v[18:33], v[208:211], v[232:235], v[18:33]
	ds_read_b128 v[228:231], v147 offset:50784
	v_mfma_f32_32x32x16_bf16 v[2:17], v[212:215], v[232:235], v[2:17]
	global_load_dwordx4 v[142:145], v153, s[80:81] offset:1024 sc0
	s_waitcnt lgkmcnt(6)
	v_mfma_f32_32x32x16_bf16 v[98:113], v[216:219], v[236:239], v[98:113]
	s_waitcnt vmcnt(15)
	ds_write_b128 v152, v[188:191] offset:27648
	s_waitcnt lgkmcnt(6)
	v_mfma_f32_32x32x16_bf16 v[114:129], v[224:227], v[236:239], v[114:129]
	s_waitcnt lgkmcnt(4)
	v_mfma_f32_32x32x16_bf16 v[82:97], v[216:219], v[240:243], v[82:97]
	global_load_dwordx4 v[188:191], v153, s[92:93] offset:1024 sc0
	v_mfma_f32_32x32x16_bf16 v[66:81], v[224:227], v[240:243], v[66:81]
	s_waitcnt lgkmcnt(3)
	v_mfma_f32_32x32x16_bf16 v[50:65], v[216:219], v[244:247], v[50:65]
	v_mfma_f32_32x32x16_bf16 v[34:49], v[224:227], v[244:247], v[34:49]
	s_waitcnt lgkmcnt(1)
	v_mfma_f32_32x32x16_bf16 v[18:33], v[216:219], v[228:231], v[18:33]
	v_mfma_f32_32x32x16_bf16 v[2:17], v[224:227], v[228:231], v[2:17]
	s_waitcnt lgkmcnt(0)
	s_barrier
;     ...
;   for (int kt = 0; kt < nk; ++kt) {
;     __syncthreads();
;     if (kt + 1 < nk) {
;       u16* aw = As0 + ((kt + 1) & 1) * 256 * LD;
;       u16* bw = Bs0 + ((kt + 1) & 1) * 256 * LD;
; #pragma unroll
;       for (int i = 0; i < 4; ++i) { *(u32x4*)(aw + (srow + 64 * i) * LD + skc * 8) = ra[i]; *(u32x4*)(bw + (srow + 64 * i) * LD + skc * 8) = rb[i]; }
;     }
;     if (kt + 2 < nk) {
; #pragma unroll
;       for (int i = 0; i < 4; ++i) { ra[i] = *(const u32x4*)(Ag + (size_t)(64 * i) * K + (kt + 2) * 64); rb[i] = *(const u32x4*)(Bg[i] + (kt + 2) * 64); }
;     }
;     __builtin_amdgcn_sched_barrier(0);
;     const u16* as = As0 + (kt & 1) * 256 * LD + (wr * 128 + l31) * LD + h * 8;
;     const u16* bs = Bs0 + (kt & 1) * 256 * LD + (wc * 64 + l31) * LD + h * 8;
;     if (domma)
; #pragma unroll
;     for (int ks = 0; ks < 4; ++ks) {
;       bf16x8 wf[2], xf[4];
; #pragma unroll
;       for (int ct = 0; ct < 2; ++ct) wf[ct] = *(const bf16x8*)(bs + ct * 32 * LD + ks * 16);
; #pragma unroll
;       for (int tt = 0; tt < 4; ++tt) xf[tt] = *(const bf16x8*)(as + tt * 32 * LD + ks * 16);
; #pragma unroll
;       for (int ct = 0; ct < 2; ++ct)
; #pragma unroll
;         for (int tt = 0; tt < 4; ++tt) acc[ct][tt] = __builtin_amdgcn_mfma_f32_32x32x16_bf16(wf[ct], xf[tt], acc[ct][tt], 0, 0, 0);
;     }
	ds_read_b128 v[208:211], v148
	ds_read_b128 v[228:231], v147
	ds_read_b128 v[212:215], v148 offset:4608
	ds_read_b128 v[232:235], v147 offset:4608
	ds_read_b128 v[236:239], v147 offset:9216
	ds_read_b128 v[240:243], v147 offset:13824
	s_waitcnt lgkmcnt(4)
	v_mfma_f32_32x32x16_bf16 v[98:113], v[208:211], v[228:231], v[98:113]
	ds_read_b128 v[216:219], v148 offset:32
	s_waitcnt lgkmcnt(4)
	v_mfma_f32_32x32x16_bf16 v[114:129], v[212:215], v[228:231], v[114:129]
	ds_read_b128 v[244:247], v147 offset:32
	s_waitcnt lgkmcnt(4)
	v_mfma_f32_32x32x16_bf16 v[82:97], v[208:211], v[232:235], v[82:97]
	ds_read_b128 v[224:227], v148 offset:4640
	v_mfma_f32_32x32x16_bf16 v[66:81], v[212:215], v[232:235], v[66:81]
	ds_read_b128 v[228:231], v147 offset:4640
	s_waitcnt vmcnt(15)
	ds_write_b128 v149, v[160:163] offset:36864
	s_waitcnt lgkmcnt(6)
	v_mfma_f32_32x32x16_bf16 v[50:65], v[208:211], v[236:239], v[50:65]
	ds_read_b128 v[232:235], v147 offset:9248
	v_mfma_f32_32x32x16_bf16 v[34:49], v[212:215], v[236:239], v[34:49]
	global_load_dwordx4 v[160:163], v153, s[74:75] offset:1152 sc0
	s_waitcnt lgkmcnt(6)
	v_mfma_f32_32x32x16_bf16 v[18:33], v[208:211], v[240:243], v[18:33]
	ds_read_b128 v[236:239], v147 offset:13856
	s_waitcnt vmcnt(15)
	ds_write_b128 v152, v[192:195] offset:36864
	v_mfma_f32_32x32x16_bf16 v[2:17], v[212:215], v[240:243], v[2:17]
	s_waitcnt lgkmcnt(6)
	v_mfma_f32_32x32x16_bf16 v[98:113], v[216:219], v[244:247], v[98:113]
	ds_read_b128 v[208:211], v148 offset:64
	global_load_dwordx4 v[192:195], v153, s[82:83] offset:1152 sc0
	s_waitcnt lgkmcnt(6)
	v_mfma_f32_32x32x16_bf16 v[114:129], v[224:227], v[244:247], v[114:129]
	ds_read_b128 v[240:243], v147 offset:64
	s_waitcnt vmcnt(15)
	ds_write_b128 v149, v[164:167] offset:46080
	s_waitcnt lgkmcnt(7)
	v_mfma_f32_32x32x16_bf16 v[82:97], v[216:219], v[228:231], v[82:97]
	ds_read_b128 v[212:215], v148 offset:4672
	v_mfma_f32_32x32x16_bf16 v[66:81], v[224:227], v[228:231], v[66:81]
	ds_read_b128 v[244:247], v147 offset:4672
	global_load_dwordx4 v[164:167], v153, s[76:77] offset:1152 sc0
	s_waitcnt lgkmcnt(7)
	v_mfma_f32_32x32x16_bf16 v[50:65], v[216:219], v[232:235], v[50:65]
	ds_read_b128 v[228:231], v147 offset:9280
	s_waitcnt vmcnt(15)
	ds_write_b128 v152, v[196:199] offset:46080
	v_mfma_f32_32x32x16_bf16 v[34:49], v[224:227], v[232:235], v[34:49]
	s_waitcnt lgkmcnt(8)
	v_mfma_f32_32x32x16_bf16 v[18:33], v[216:219], v[236:239], v[18:33]
	ds_read_b128 v[232:235], v147 offset:13888
	global_load_dwordx4 v[196:199], v153, s[84:85] offset:1152 sc0
	v_mfma_f32_32x32x16_bf16 v[2:17], v[224:227], v[236:239], v[2:17]
	s_waitcnt vmcnt(15)
	ds_write_b128 v149, v[168:171] offset:55296
	s_waitcnt lgkmcnt(7)
	v_mfma_f32_32x32x16_bf16 v[98:113], v[208:211], v[240:243], v[98:113]
	ds_read_b128 v[216:219], v148 offset:96
	s_waitcnt lgkmcnt(6)
	v_mfma_f32_32x32x16_bf16 v[114:129], v[212:215], v[240:243], v[114:129]
	ds_read_b128 v[236:239], v147 offset:96
	global_load_dwordx4 v[168:171], v153, s[78:79] offset:1152 sc0
	s_waitcnt lgkmcnt(6)
	v_mfma_f32_32x32x16_bf16 v[82:97], v[208:211], v[244:247], v[82:97]
	ds_read_b128 v[224:227], v148 offset:4704
	s_waitcnt vmcnt(15)
	ds_write_b128 v152, v[200:203] offset:55296
	v_mfma_f32_32x32x16_bf16 v[66:81], v[212:215], v[244:247], v[66:81]
	ds_read_b128 v[240:243], v147 offset:4704
	s_waitcnt lgkmcnt(8)
	v_mfma_f32_32x32x16_bf16 v[50:65], v[208:211], v[228:231], v[50:65]
	ds_read_b128 v[244:247], v147 offset:9312
	global_load_dwordx4 v[200:203], v153, s[86:87] offset:1152 sc0
	v_mfma_f32_32x32x16_bf16 v[34:49], v[212:215], v[228:231], v[34:49]
	s_waitcnt vmcnt(15)
	ds_write_b128 v149, v[172:175] offset:64512
	s_waitcnt lgkmcnt(8)
	v_mfma_f32_32x32x16_bf16 v[18:33], v[208:211], v[232:235], v[18:33]
	ds_read_b128 v[228:231], v147 offset:13920
	v_mfma_f32_32x32x16_bf16 v[2:17], v[212:215], v[232:235], v[2:17]
	global_load_dwordx4 v[172:175], v153, s[80:81] offset:1152 sc0
	s_waitcnt lgkmcnt(6)
	v_mfma_f32_32x32x16_bf16 v[98:113], v[216:219], v[236:239], v[98:113]
	s_waitcnt vmcnt(15)
	ds_write_b128 v152, v[204:207] offset:64512
	s_waitcnt lgkmcnt(6)
	v_mfma_f32_32x32x16_bf16 v[114:129], v[224:227], v[236:239], v[114:129]
	s_waitcnt lgkmcnt(4)
	v_mfma_f32_32x32x16_bf16 v[82:97], v[216:219], v[240:243], v[82:97]
	global_load_dwordx4 v[204:207], v153, s[92:93] offset:1152 sc0
	v_mfma_f32_32x32x16_bf16 v[66:81], v[224:227], v[240:243], v[66:81]
	s_waitcnt lgkmcnt(3)
	v_mfma_f32_32x32x16_bf16 v[50:65], v[216:219], v[244:247], v[50:65]
	v_mfma_f32_32x32x16_bf16 v[34:49], v[224:227], v[244:247], v[34:49]
	s_waitcnt lgkmcnt(1)
	v_mfma_f32_32x32x16_bf16 v[18:33], v[216:219], v[228:231], v[18:33]
	v_mfma_f32_32x32x16_bf16 v[2:17], v[224:227], v[228:231], v[2:17]
	s_waitcnt lgkmcnt(0)
	s_barrier
;     ...
;   for (int kt = 0; kt < nk; ++kt) {
;     __syncthreads();
;     if (kt + 1 < nk) {
;       u16* aw = As0 + ((kt + 1) & 1) * 256 * LD;
;       u16* bw = Bs0 + ((kt + 1) & 1) * 256 * LD;
; #pragma unroll
;       for (int i = 0; i < 4; ++i) { *(u32x4*)(aw + (srow + 64 * i) * LD + skc * 8) = ra[i]; *(u32x4*)(bw + (srow + 64 * i) * LD + skc * 8) = rb[i]; }
;     }
;     if (kt + 2 < nk) {
; #pragma unroll
;       for (int i = 0; i < 4; ++i) { ra[i] = *(const u32x4*)(Ag + (size_t)(64 * i) * K + (kt + 2) * 64); rb[i] = *(const u32x4*)(Bg[i] + (kt + 2) * 64); }
;     }
;     __builtin_amdgcn_sched_barrier(0);
;     const u16* as = As0 + (kt & 1) * 256 * LD + (wr * 128 + l31) * LD + h * 8;
;     const u16* bs = Bs0 + (kt & 1) * 256 * LD + (wc * 64 + l31) * LD + h * 8;
;     if (domma)
; #pragma unroll
;     for (int ks = 0; ks < 4; ++ks) {
;       bf16x8 wf[2], xf[4];
; #pragma unroll
;       for (int ct = 0; ct < 2; ++ct) wf[ct] = *(const bf16x8*)(bs + ct * 32 * LD + ks * 16);
; #pragma unroll
;       for (int tt = 0; tt < 4; ++tt) xf[tt] = *(const bf16x8*)(as + tt * 32 * LD + ks * 16);
; #pragma unroll
;       for (int ct = 0; ct < 2; ++ct)
; #pragma unroll
;         for (int tt = 0; tt < 4; ++tt) acc[ct][tt] = __builtin_amdgcn_mfma_f32_32x32x16_bf16(wf[ct], xf[tt], acc[ct][tt], 0, 0, 0);
;     }
	ds_read_b128 v[208:211], v148 offset:36864
	ds_read_b128 v[228:231], v147 offset:36864
	ds_read_b128 v[212:215], v148 offset:41472
	ds_read_b128 v[232:235], v147 offset:41472
	ds_read_b128 v[236:239], v147 offset:46080
	ds_read_b128 v[240:243], v147 offset:50688
	s_waitcnt lgkmcnt(4)
	v_mfma_f32_32x32x16_bf16 v[98:113], v[208:211], v[228:231], v[98:113]
	ds_read_b128 v[216:219], v148 offset:36896
	s_waitcnt lgkmcnt(4)
	v_mfma_f32_32x32x16_bf16 v[114:129], v[212:215], v[228:231], v[114:129]
	ds_read_b128 v[244:247], v147 offset:36896
	s_waitcnt lgkmcnt(4)
	v_mfma_f32_32x32x16_bf16 v[82:97], v[208:211], v[232:235], v[82:97]
	ds_read_b128 v[224:227], v148 offset:41504
	v_mfma_f32_32x32x16_bf16 v[66:81], v[212:215], v[232:235], v[66:81]
	ds_read_b128 v[228:231], v147 offset:41504
	s_waitcnt vmcnt(15)
	ds_write_b128 v149, v[130:133]
	s_waitcnt lgkmcnt(6)
	v_mfma_f32_32x32x16_bf16 v[50:65], v[208:211], v[236:239], v[50:65]
	ds_read_b128 v[232:235], v147 offset:46112
	v_mfma_f32_32x32x16_bf16 v[34:49], v[212:215], v[236:239], v[34:49]
	global_load_dwordx4 v[130:133], v153, s[74:75] offset:1280 sc0
	s_waitcnt lgkmcnt(6)
	v_mfma_f32_32x32x16_bf16 v[18:33], v[208:211], v[240:243], v[18:33]
	ds_read_b128 v[236:239], v147 offset:50720
	s_waitcnt vmcnt(15)
	ds_write_b128 v152, v[176:179]
	v_mfma_f32_32x32x16_bf16 v[2:17], v[212:215], v[240:243], v[2:17]
	s_waitcnt lgkmcnt(6)
	v_mfma_f32_32x32x16_bf16 v[98:113], v[216:219], v[244:247], v[98:113]
	ds_read_b128 v[208:211], v148 offset:36928
	global_load_dwordx4 v[176:179], v153, s[82:83] offset:1280 sc0
	s_waitcnt lgkmcnt(6)
	v_mfma_f32_32x32x16_bf16 v[114:129], v[224:227], v[244:247], v[114:129]
	ds_read_b128 v[240:243], v147 offset:36928
	s_waitcnt vmcnt(15)
	ds_write_b128 v149, v[134:137] offset:9216
	s_waitcnt lgkmcnt(7)
	v_mfma_f32_32x32x16_bf16 v[82:97], v[216:219], v[228:231], v[82:97]
	ds_read_b128 v[212:215], v148 offset:41536
	v_mfma_f32_32x32x16_bf16 v[66:81], v[224:227], v[228:231], v[66:81]
	ds_read_b128 v[244:247], v147 offset:41536
	global_load_dwordx4 v[134:137], v153, s[76:77] offset:1280 sc0
	s_waitcnt lgkmcnt(7)
	v_mfma_f32_32x32x16_bf16 v[50:65], v[216:219], v[232:235], v[50:65]
	ds_read_b128 v[228:231], v147 offset:46144
	s_waitcnt vmcnt(15)
	ds_write_b128 v152, v[180:183] offset:9216
	v_mfma_f32_32x32x16_bf16 v[34:49], v[224:227], v[232:235], v[34:49]
	s_waitcnt lgkmcnt(8)
	v_mfma_f32_32x32x16_bf16 v[18:33], v[216:219], v[236:239], v[18:33]
	ds_read_b128 v[232:235], v147 offset:50752
	global_load_dwordx4 v[180:183], v153, s[84:85] offset:1280 sc0
	v_mfma_f32_32x32x16_bf16 v[2:17], v[224:227], v[236:239], v[2:17]
	s_waitcnt vmcnt(15)
	ds_write_b128 v149, v[138:141] offset:18432
	s_waitcnt lgkmcnt(7)
	v_mfma_f32_32x32x16_bf16 v[98:113], v[208:211], v[240:243], v[98:113]
	ds_read_b128 v[216:219], v148 offset:36960
	s_waitcnt lgkmcnt(6)
	v_mfma_f32_32x32x16_bf16 v[114:129], v[212:215], v[240:243], v[114:129]
	ds_read_b128 v[236:239], v147 offset:36960
	global_load_dwordx4 v[138:141], v153, s[78:79] offset:1280 sc0
	s_waitcnt lgkmcnt(6)
	v_mfma_f32_32x32x16_bf16 v[82:97], v[208:211], v[244:247], v[82:97]
	ds_read_b128 v[224:227], v148 offset:41568
	s_waitcnt vmcnt(15)
	ds_write_b128 v152, v[184:187] offset:18432
	v_mfma_f32_32x32x16_bf16 v[66:81], v[212:215], v[244:247], v[66:81]
	ds_read_b128 v[240:243], v147 offset:41568
	s_waitcnt lgkmcnt(8)
	v_mfma_f32_32x32x16_bf16 v[50:65], v[208:211], v[228:231], v[50:65]
	ds_read_b128 v[244:247], v147 offset:46176
	global_load_dwordx4 v[184:187], v153, s[86:87] offset:1280 sc0
	v_mfma_f32_32x32x16_bf16 v[34:49], v[212:215], v[228:231], v[34:49]
	s_waitcnt vmcnt(15)
	ds_write_b128 v149, v[142:145] offset:27648
	s_waitcnt lgkmcnt(8)
	v_mfma_f32_32x32x16_bf16 v[18:33], v[208:211], v[232:235], v[18:33]
	ds_read_b128 v[228:231], v147 offset:50784
	v_mfma_f32_32x32x16_bf16 v[2:17], v[212:215], v[232:235], v[2:17]
	global_load_dwordx4 v[142:145], v153, s[80:81] offset:1280 sc0
	s_waitcnt lgkmcnt(6)
	v_mfma_f32_32x32x16_bf16 v[98:113], v[216:219], v[236:239], v[98:113]
	s_waitcnt vmcnt(15)
	ds_write_b128 v152, v[188:191] offset:27648
	s_waitcnt lgkmcnt(6)
	v_mfma_f32_32x32x16_bf16 v[114:129], v[224:227], v[236:239], v[114:129]
	s_waitcnt lgkmcnt(4)
	v_mfma_f32_32x32x16_bf16 v[82:97], v[216:219], v[240:243], v[82:97]
	global_load_dwordx4 v[188:191], v153, s[92:93] offset:1280 sc0
	v_mfma_f32_32x32x16_bf16 v[66:81], v[224:227], v[240:243], v[66:81]
	s_waitcnt lgkmcnt(3)
	v_mfma_f32_32x32x16_bf16 v[50:65], v[216:219], v[244:247], v[50:65]
	v_mfma_f32_32x32x16_bf16 v[34:49], v[224:227], v[244:247], v[34:49]
	s_waitcnt lgkmcnt(1)
	v_mfma_f32_32x32x16_bf16 v[18:33], v[216:219], v[228:231], v[18:33]
	v_mfma_f32_32x32x16_bf16 v[2:17], v[224:227], v[228:231], v[2:17]
	s_waitcnt lgkmcnt(0)
	s_barrier
;     ...
;   for (int kt = 0; kt < nk; ++kt) {
;     __syncthreads();
;     if (kt + 1 < nk) {
;       u16* aw = As0 + ((kt + 1) & 1) * 256 * LD;
;       u16* bw = Bs0 + ((kt + 1) & 1) * 256 * LD;
; #pragma unroll
;       for (int i = 0; i < 4; ++i) { *(u32x4*)(aw + (srow + 64 * i) * LD + skc * 8) = ra[i]; *(u32x4*)(bw + (srow + 64 * i) * LD + skc * 8) = rb[i]; }
;     }
;     if (kt + 2 < nk) {
; #pragma unroll
;       for (int i = 0; i < 4; ++i) { ra[i] = *(const u32x4*)(Ag + (size_t)(64 * i) * K + (kt + 2) * 64); rb[i] = *(const u32x4*)(Bg[i] + (kt + 2) * 64); }
;     }
;     __builtin_amdgcn_sched_barrier(0);
;     const u16* as = As0 + (kt & 1) * 256 * LD + (wr * 128 + l31) * LD + h * 8;
;     const u16* bs = Bs0 + (kt & 1) * 256 * LD + (wc * 64 + l31) * LD + h * 8;
;     if (domma)
; #pragma unroll
;     for (int ks = 0; ks < 4; ++ks) {
;       bf16x8 wf[2], xf[4];
; #pragma unroll
;       for (int ct = 0; ct < 2; ++ct) wf[ct] = *(const bf16x8*)(bs + ct * 32 * LD + ks * 16);
; #pragma unroll
;       for (int tt = 0; tt < 4; ++tt) xf[tt] = *(const bf16x8*)(as + tt * 32 * LD + ks * 16);
; #pragma unroll
;       for (int ct = 0; ct < 2; ++ct)
; #pragma unroll
;         for (int tt = 0; tt < 4; ++tt) acc[ct][tt] = __builtin_amdgcn_mfma_f32_32x32x16_bf16(wf[ct], xf[tt], acc[ct][tt], 0, 0, 0);
;     }
	ds_read_b128 v[208:211], v148
	ds_read_b128 v[228:231], v147
	ds_read_b128 v[212:215], v148 offset:4608
	ds_read_b128 v[232:235], v147 offset:4608
	ds_read_b128 v[236:239], v147 offset:9216
	ds_read_b128 v[240:243], v147 offset:13824
	s_waitcnt lgkmcnt(4)
	v_mfma_f32_32x32x16_bf16 v[98:113], v[208:211], v[228:231], v[98:113]
	ds_read_b128 v[216:219], v148 offset:32
	s_waitcnt lgkmcnt(4)
	v_mfma_f32_32x32x16_bf16 v[114:129], v[212:215], v[228:231], v[114:129]
	ds_read_b128 v[244:247], v147 offset:32
	s_waitcnt lgkmcnt(4)
	v_mfma_f32_32x32x16_bf16 v[82:97], v[208:211], v[232:235], v[82:97]
	ds_read_b128 v[224:227], v148 offset:4640
	v_mfma_f32_32x32x16_bf16 v[66:81], v[212:215], v[232:235], v[66:81]
	ds_read_b128 v[228:231], v147 offset:4640
	s_waitcnt vmcnt(15)
	ds_write_b128 v149, v[160:163] offset:36864
	s_waitcnt lgkmcnt(6)
	v_mfma_f32_32x32x16_bf16 v[50:65], v[208:211], v[236:239], v[50:65]
	ds_read_b128 v[232:235], v147 offset:9248
	v_mfma_f32_32x32x16_bf16 v[34:49], v[212:215], v[236:239], v[34:49]
	global_load_dwordx4 v[160:163], v153, s[74:75] offset:1408 sc0
	s_waitcnt lgkmcnt(6)
	v_mfma_f32_32x32x16_bf16 v[18:33], v[208:211], v[240:243], v[18:33]
	ds_read_b128 v[236:239], v147 offset:13856
	s_waitcnt vmcnt(15)
	ds_write_b128 v152, v[192:195] offset:36864
	v_mfma_f32_32x32x16_bf16 v[2:17], v[212:215], v[240:243], v[2:17]
	s_waitcnt lgkmcnt(6)
	v_mfma_f32_32x32x16_bf16 v[98:113], v[216:219], v[244:247], v[98:113]
	ds_read_b128 v[208:211], v148 offset:64
	global_load_dwordx4 v[192:195], v153, s[82:83] offset:1408 sc0
	s_waitcnt lgkmcnt(6)
	v_mfma_f32_32x32x16_bf16 v[114:129], v[224:227], v[244:247], v[114:129]
	ds_read_b128 v[240:243], v147 offset:64
	s_waitcnt vmcnt(15)
	ds_write_b128 v149, v[164:167] offset:46080
	s_waitcnt lgkmcnt(7)
	v_mfma_f32_32x32x16_bf16 v[82:97], v[216:219], v[228:231], v[82:97]
	ds_read_b128 v[212:215], v148 offset:4672
	v_mfma_f32_32x32x16_bf16 v[66:81], v[224:227], v[228:231], v[66:81]
	ds_read_b128 v[244:247], v147 offset:4672
	global_load_dwordx4 v[164:167], v153, s[76:77] offset:1408 sc0
	s_waitcnt lgkmcnt(7)
	v_mfma_f32_32x32x16_bf16 v[50:65], v[216:219], v[232:235], v[50:65]
	ds_read_b128 v[228:231], v147 offset:9280
	s_waitcnt vmcnt(15)
	ds_write_b128 v152, v[196:199] offset:46080
	v_mfma_f32_32x32x16_bf16 v[34:49], v[224:227], v[232:235], v[34:49]
	s_waitcnt lgkmcnt(8)
	v_mfma_f32_32x32x16_bf16 v[18:33], v[216:219], v[236:239], v[18:33]
	ds_read_b128 v[232:235], v147 offset:13888
	global_load_dwordx4 v[196:199], v153, s[84:85] offset:1408 sc0
	v_mfma_f32_32x32x16_bf16 v[2:17], v[224:227], v[236:239], v[2:17]
	s_waitcnt vmcnt(15)
	ds_write_b128 v149, v[168:171] offset:55296
	s_waitcnt lgkmcnt(7)
	v_mfma_f32_32x32x16_bf16 v[98:113], v[208:211], v[240:243], v[98:113]
	ds_read_b128 v[216:219], v148 offset:96
	s_waitcnt lgkmcnt(6)
	v_mfma_f32_32x32x16_bf16 v[114:129], v[212:215], v[240:243], v[114:129]
	ds_read_b128 v[236:239], v147 offset:96
	global_load_dwordx4 v[168:171], v153, s[78:79] offset:1408 sc0
	s_waitcnt lgkmcnt(6)
	v_mfma_f32_32x32x16_bf16 v[82:97], v[208:211], v[244:247], v[82:97]
	ds_read_b128 v[224:227], v148 offset:4704
	s_waitcnt vmcnt(15)
	ds_write_b128 v152, v[200:203] offset:55296
	v_mfma_f32_32x32x16_bf16 v[66:81], v[212:215], v[244:247], v[66:81]
	ds_read_b128 v[240:243], v147 offset:4704
	s_waitcnt lgkmcnt(8)
	v_mfma_f32_32x32x16_bf16 v[50:65], v[208:211], v[228:231], v[50:65]
	ds_read_b128 v[244:247], v147 offset:9312
	global_load_dwordx4 v[200:203], v153, s[86:87] offset:1408 sc0
	v_mfma_f32_32x32x16_bf16 v[34:49], v[212:215], v[228:231], v[34:49]
	s_waitcnt vmcnt(15)
	ds_write_b128 v149, v[172:175] offset:64512
	s_waitcnt lgkmcnt(8)
	v_mfma_f32_32x32x16_bf16 v[18:33], v[208:211], v[232:235], v[18:33]
	ds_read_b128 v[228:231], v147 offset:13920
	v_mfma_f32_32x32x16_bf16 v[2:17], v[212:215], v[232:235], v[2:17]
	global_load_dwordx4 v[172:175], v153, s[80:81] offset:1408 sc0
	s_waitcnt lgkmcnt(6)
	v_mfma_f32_32x32x16_bf16 v[98:113], v[216:219], v[236:239], v[98:113]
	s_waitcnt vmcnt(15)
	ds_write_b128 v152, v[204:207] offset:64512
	s_waitcnt lgkmcnt(6)
	v_mfma_f32_32x32x16_bf16 v[114:129], v[224:227], v[236:239], v[114:129]
	s_waitcnt lgkmcnt(4)
	v_mfma_f32_32x32x16_bf16 v[82:97], v[216:219], v[240:243], v[82:97]
	global_load_dwordx4 v[204:207], v153, s[92:93] offset:1408 sc0
	v_mfma_f32_32x32x16_bf16 v[66:81], v[224:227], v[240:243], v[66:81]
	s_waitcnt lgkmcnt(3)
	v_mfma_f32_32x32x16_bf16 v[50:65], v[216:219], v[244:247], v[50:65]
	v_mfma_f32_32x32x16_bf16 v[34:49], v[224:227], v[244:247], v[34:49]
	s_waitcnt lgkmcnt(1)
	v_mfma_f32_32x32x16_bf16 v[18:33], v[216:219], v[228:231], v[18:33]
	v_mfma_f32_32x32x16_bf16 v[2:17], v[224:227], v[228:231], v[2:17]
	s_waitcnt lgkmcnt(0)
	s_barrier
;     ...
;   for (int kt = 0; kt < nk; ++kt) {
;     __syncthreads();
;     if (kt + 1 < nk) {
;       u16* aw = As0 + ((kt + 1) & 1) * 256 * LD;
;       u16* bw = Bs0 + ((kt + 1) & 1) * 256 * LD;
; #pragma unroll
;       for (int i = 0; i < 4; ++i) { *(u32x4*)(aw + (srow + 64 * i) * LD + skc * 8) = ra[i]; *(u32x4*)(bw + (srow + 64 * i) * LD + skc * 8) = rb[i]; }
;     }
;     if (kt + 2 < nk) {
; #pragma unroll
;       for (int i = 0; i < 4; ++i) { ra[i] = *(const u32x4*)(Ag + (size_t)(64 * i) * K + (kt + 2) * 64); rb[i] = *(const u32x4*)(Bg[i] + (kt + 2) * 64); }
;     }
;     __builtin_amdgcn_sched_barrier(0);
;     const u16* as = As0 + (kt & 1) * 256 * LD + (wr * 128 + l31) * LD + h * 8;
;     const u16* bs = Bs0 + (kt & 1) * 256 * LD + (wc * 64 + l31) * LD + h * 8;
;     if (domma)
; #pragma unroll
;     for (int ks = 0; ks < 4; ++ks) {
;       bf16x8 wf[2], xf[4];
; #pragma unroll
;       for (int ct = 0; ct < 2; ++ct) wf[ct] = *(const bf16x8*)(bs + ct * 32 * LD + ks * 16);
; #pragma unroll
;       for (int tt = 0; tt < 4; ++tt) xf[tt] = *(const bf16x8*)(as + tt * 32 * LD + ks * 16);
; #pragma unroll
;       for (int ct = 0; ct < 2; ++ct)
; #pragma unroll
;         for (int tt = 0; tt < 4; ++tt) acc[ct][tt] = __builtin_amdgcn_mfma_f32_32x32x16_bf16(wf[ct], xf[tt], acc[ct][tt], 0, 0, 0);
;     }
	ds_read_b128 v[208:211], v148 offset:36864
	ds_read_b128 v[228:231], v147 offset:36864
	ds_read_b128 v[212:215], v148 offset:41472
	ds_read_b128 v[232:235], v147 offset:41472
	ds_read_b128 v[236:239], v147 offset:46080
	ds_read_b128 v[240:243], v147 offset:50688
	s_waitcnt lgkmcnt(4)
	v_mfma_f32_32x32x16_bf16 v[98:113], v[208:211], v[228:231], v[98:113]
	ds_read_b128 v[216:219], v148 offset:36896
	s_waitcnt lgkmcnt(4)
	v_mfma_f32_32x32x16_bf16 v[114:129], v[212:215], v[228:231], v[114:129]
	ds_read_b128 v[244:247], v147 offset:36896
	s_waitcnt lgkmcnt(4)
	v_mfma_f32_32x32x16_bf16 v[82:97], v[208:211], v[232:235], v[82:97]
	ds_read_b128 v[224:227], v148 offset:41504
	v_mfma_f32_32x32x16_bf16 v[66:81], v[212:215], v[232:235], v[66:81]
	ds_read_b128 v[228:231], v147 offset:41504
	s_waitcnt vmcnt(15)
	ds_write_b128 v149, v[130:133]
	s_waitcnt lgkmcnt(6)
	v_mfma_f32_32x32x16_bf16 v[50:65], v[208:211], v[236:239], v[50:65]
	ds_read_b128 v[232:235], v147 offset:46112
	v_mfma_f32_32x32x16_bf16 v[34:49], v[212:215], v[236:239], v[34:49]
	global_load_dwordx4 v[130:133], v153, s[74:75] offset:1536 sc0
	s_waitcnt lgkmcnt(6)
	v_mfma_f32_32x32x16_bf16 v[18:33], v[208:211], v[240:243], v[18:33]
	ds_read_b128 v[236:239], v147 offset:50720
	s_waitcnt vmcnt(15)
	ds_write_b128 v152, v[176:179]
	v_mfma_f32_32x32x16_bf16 v[2:17], v[212:215], v[240:243], v[2:17]
	s_waitcnt lgkmcnt(6)
	v_mfma_f32_32x32x16_bf16 v[98:113], v[216:219], v[244:247], v[98:113]
	ds_read_b128 v[208:211], v148 offset:36928
	global_load_dwordx4 v[176:179], v153, s[82:83] offset:1536 sc0
	s_waitcnt lgkmcnt(6)
	v_mfma_f32_32x32x16_bf16 v[114:129], v[224:227], v[244:247], v[114:129]
	ds_read_b128 v[240:243], v147 offset:36928
	s_waitcnt vmcnt(15)
	ds_write_b128 v149, v[134:137] offset:9216
	s_waitcnt lgkmcnt(7)
	v_mfma_f32_32x32x16_bf16 v[82:97], v[216:219], v[228:231], v[82:97]
	ds_read_b128 v[212:215], v148 offset:41536
	v_mfma_f32_32x32x16_bf16 v[66:81], v[224:227], v[228:231], v[66:81]
	ds_read_b128 v[244:247], v147 offset:41536
	global_load_dwordx4 v[134:137], v153, s[76:77] offset:1536 sc0
	s_waitcnt lgkmcnt(7)
	v_mfma_f32_32x32x16_bf16 v[50:65], v[216:219], v[232:235], v[50:65]
	ds_read_b128 v[228:231], v147 offset:46144
	s_waitcnt vmcnt(15)
	ds_write_b128 v152, v[180:183] offset:9216
	v_mfma_f32_32x32x16_bf16 v[34:49], v[224:227], v[232:235], v[34:49]
	s_waitcnt lgkmcnt(8)
	v_mfma_f32_32x32x16_bf16 v[18:33], v[216:219], v[236:239], v[18:33]
	ds_read_b128 v[232:235], v147 offset:50752
	global_load_dwordx4 v[180:183], v153, s[84:85] offset:1536 sc0
	v_mfma_f32_32x32x16_bf16 v[2:17], v[224:227], v[236:239], v[2:17]
	s_waitcnt vmcnt(15)
	ds_write_b128 v149, v[138:141] offset:18432
	s_waitcnt lgkmcnt(7)
	v_mfma_f32_32x32x16_bf16 v[98:113], v[208:211], v[240:243], v[98:113]
	ds_read_b128 v[216:219], v148 offset:36960
	s_waitcnt lgkmcnt(6)
	v_mfma_f32_32x32x16_bf16 v[114:129], v[212:215], v[240:243], v[114:129]
	ds_read_b128 v[236:239], v147 offset:36960
	global_load_dwordx4 v[138:141], v153, s[78:79] offset:1536 sc0
	s_waitcnt lgkmcnt(6)
	v_mfma_f32_32x32x16_bf16 v[82:97], v[208:211], v[244:247], v[82:97]
	ds_read_b128 v[224:227], v148 offset:41568
	s_waitcnt vmcnt(15)
	ds_write_b128 v152, v[184:187] offset:18432
	v_mfma_f32_32x32x16_bf16 v[66:81], v[212:215], v[244:247], v[66:81]
	ds_read_b128 v[240:243], v147 offset:41568
	s_waitcnt lgkmcnt(8)
	v_mfma_f32_32x32x16_bf16 v[50:65], v[208:211], v[228:231], v[50:65]
	ds_read_b128 v[244:247], v147 offset:46176
	global_load_dwordx4 v[184:187], v153, s[86:87] offset:1536 sc0
	v_mfma_f32_32x32x16_bf16 v[34:49], v[212:215], v[228:231], v[34:49]
	s_waitcnt vmcnt(15)
	ds_write_b128 v149, v[142:145] offset:27648
	s_waitcnt lgkmcnt(8)
	v_mfma_f32_32x32x16_bf16 v[18:33], v[208:211], v[232:235], v[18:33]
	ds_read_b128 v[228:231], v147 offset:50784
	v_mfma_f32_32x32x16_bf16 v[2:17], v[212:215], v[232:235], v[2:17]
	global_load_dwordx4 v[142:145], v153, s[80:81] offset:1536 sc0
	s_waitcnt lgkmcnt(6)
	v_mfma_f32_32x32x16_bf16 v[98:113], v[216:219], v[236:239], v[98:113]
	s_waitcnt vmcnt(15)
	ds_write_b128 v152, v[188:191] offset:27648
	s_waitcnt lgkmcnt(6)
	v_mfma_f32_32x32x16_bf16 v[114:129], v[224:227], v[236:239], v[114:129]
	s_waitcnt lgkmcnt(4)
	v_mfma_f32_32x32x16_bf16 v[82:97], v[216:219], v[240:243], v[82:97]
	global_load_dwordx4 v[188:191], v153, s[92:93] offset:1536 sc0
	v_mfma_f32_32x32x16_bf16 v[66:81], v[224:227], v[240:243], v[66:81]
	s_waitcnt lgkmcnt(3)
	v_mfma_f32_32x32x16_bf16 v[50:65], v[216:219], v[244:247], v[50:65]
	v_mfma_f32_32x32x16_bf16 v[34:49], v[224:227], v[244:247], v[34:49]
	s_waitcnt lgkmcnt(1)
	v_mfma_f32_32x32x16_bf16 v[18:33], v[216:219], v[228:231], v[18:33]
	v_mfma_f32_32x32x16_bf16 v[2:17], v[224:227], v[228:231], v[2:17]
	s_waitcnt lgkmcnt(0)
	s_barrier
;     ...
;   for (int kt = 0; kt < nk; ++kt) {
;     __syncthreads();
;     if (kt + 1 < nk) {
;       u16* aw = As0 + ((kt + 1) & 1) * 256 * LD;
;       u16* bw = Bs0 + ((kt + 1) & 1) * 256 * LD;
; #pragma unroll
;       for (int i = 0; i < 4; ++i) { *(u32x4*)(aw + (srow + 64 * i) * LD + skc * 8) = ra[i]; *(u32x4*)(bw + (srow + 64 * i) * LD + skc * 8) = rb[i]; }
;     }
;     if (kt + 2 < nk) {
; #pragma unroll
;       for (int i = 0; i < 4; ++i) { ra[i] = *(const u32x4*)(Ag + (size_t)(64 * i) * K + (kt + 2) * 64); rb[i] = *(const u32x4*)(Bg[i] + (kt + 2) * 64); }
;     }
;     __builtin_amdgcn_sched_barrier(0);
;     const u16* as = As0 + (kt & 1) * 256 * LD + (wr * 128 + l31) * LD + h * 8;
;     const u16* bs = Bs0 + (kt & 1) * 256 * LD + (wc * 64 + l31) * LD + h * 8;
;     if (domma)
; #pragma unroll
;     for (int ks = 0; ks < 4; ++ks) {
;       bf16x8 wf[2], xf[4];
; #pragma unroll
;       for (int ct = 0; ct < 2; ++ct) wf[ct] = *(const bf16x8*)(bs + ct * 32 * LD + ks * 16);
; #pragma unroll
;       for (int tt = 0; tt < 4; ++tt) xf[tt] = *(const bf16x8*)(as + tt * 32 * LD + ks * 16);
; #pragma unroll
;       for (int ct = 0; ct < 2; ++ct)
; #pragma unroll
;         for (int tt = 0; tt < 4; ++tt) acc[ct][tt] = __builtin_amdgcn_mfma_f32_32x32x16_bf16(wf[ct], xf[tt], acc[ct][tt], 0, 0, 0);
;     }
	ds_read_b128 v[208:211], v148
	ds_read_b128 v[228:231], v147
	ds_read_b128 v[212:215], v148 offset:4608
	ds_read_b128 v[232:235], v147 offset:4608
	ds_read_b128 v[236:239], v147 offset:9216
	ds_read_b128 v[240:243], v147 offset:13824
	s_waitcnt lgkmcnt(4)
	v_mfma_f32_32x32x16_bf16 v[98:113], v[208:211], v[228:231], v[98:113]
	ds_read_b128 v[216:219], v148 offset:32
	s_waitcnt lgkmcnt(4)
	v_mfma_f32_32x32x16_bf16 v[114:129], v[212:215], v[228:231], v[114:129]
	ds_read_b128 v[244:247], v147 offset:32
	s_waitcnt lgkmcnt(4)
	v_mfma_f32_32x32x16_bf16 v[82:97], v[208:211], v[232:235], v[82:97]
	ds_read_b128 v[224:227], v148 offset:4640
	v_mfma_f32_32x32x16_bf16 v[66:81], v[212:215], v[232:235], v[66:81]
	ds_read_b128 v[228:231], v147 offset:4640
	s_waitcnt vmcnt(15)
	ds_write_b128 v149, v[160:163] offset:36864
	s_waitcnt lgkmcnt(6)
	v_mfma_f32_32x32x16_bf16 v[50:65], v[208:211], v[236:239], v[50:65]
	ds_read_b128 v[232:235], v147 offset:9248
	v_mfma_f32_32x32x16_bf16 v[34:49], v[212:215], v[236:239], v[34:49]
	global_load_dwordx4 v[160:163], v153, s[74:75] offset:1664 sc0
	s_waitcnt lgkmcnt(6)
	v_mfma_f32_32x32x16_bf16 v[18:33], v[208:211], v[240:243], v[18:33]
	ds_read_b128 v[236:239], v147 offset:13856
	s_waitcnt vmcnt(15)
	ds_write_b128 v152, v[192:195] offset:36864
	v_mfma_f32_32x32x16_bf16 v[2:17], v[212:215], v[240:243], v[2:17]
	s_waitcnt lgkmcnt(6)
	v_mfma_f32_32x32x16_bf16 v[98:113], v[216:219], v[244:247], v[98:113]
	ds_read_b128 v[208:211], v148 offset:64
	global_load_dwordx4 v[192:195], v153, s[82:83] offset:1664 sc0
	s_waitcnt lgkmcnt(6)
	v_mfma_f32_32x32x16_bf16 v[114:129], v[224:227], v[244:247], v[114:129]
	ds_read_b128 v[240:243], v147 offset:64
	s_waitcnt vmcnt(15)
	ds_write_b128 v149, v[164:167] offset:46080
	s_waitcnt lgkmcnt(7)
	v_mfma_f32_32x32x16_bf16 v[82:97], v[216:219], v[228:231], v[82:97]
	ds_read_b128 v[212:215], v148 offset:4672
	v_mfma_f32_32x32x16_bf16 v[66:81], v[224:227], v[228:231], v[66:81]
	ds_read_b128 v[244:247], v147 offset:4672
	global_load_dwordx4 v[164:167], v153, s[76:77] offset:1664 sc0
	s_waitcnt lgkmcnt(7)
	v_mfma_f32_32x32x16_bf16 v[50:65], v[216:219], v[232:235], v[50:65]
	ds_read_b128 v[228:231], v147 offset:9280
	s_waitcnt vmcnt(15)
	ds_write_b128 v152, v[196:199] offset:46080
	v_mfma_f32_32x32x16_bf16 v[34:49], v[224:227], v[232:235], v[34:49]
	s_waitcnt lgkmcnt(8)
	v_mfma_f32_32x32x16_bf16 v[18:33], v[216:219], v[236:239], v[18:33]
	ds_read_b128 v[232:235], v147 offset:13888
	global_load_dwordx4 v[196:199], v153, s[84:85] offset:1664 sc0
	v_mfma_f32_32x32x16_bf16 v[2:17], v[224:227], v[236:239], v[2:17]
	s_waitcnt vmcnt(15)
	ds_write_b128 v149, v[168:171] offset:55296
	s_waitcnt lgkmcnt(7)
	v_mfma_f32_32x32x16_bf16 v[98:113], v[208:211], v[240:243], v[98:113]
	ds_read_b128 v[216:219], v148 offset:96
	s_waitcnt lgkmcnt(6)
	v_mfma_f32_32x32x16_bf16 v[114:129], v[212:215], v[240:243], v[114:129]
	ds_read_b128 v[236:239], v147 offset:96
	global_load_dwordx4 v[168:171], v153, s[78:79] offset:1664 sc0
	s_waitcnt lgkmcnt(6)
	v_mfma_f32_32x32x16_bf16 v[82:97], v[208:211], v[244:247], v[82:97]
	ds_read_b128 v[224:227], v148 offset:4704
	s_waitcnt vmcnt(15)
	ds_write_b128 v152, v[200:203] offset:55296
	v_mfma_f32_32x32x16_bf16 v[66:81], v[212:215], v[244:247], v[66:81]
	ds_read_b128 v[240:243], v147 offset:4704
	s_waitcnt lgkmcnt(8)
	v_mfma_f32_32x32x16_bf16 v[50:65], v[208:211], v[228:231], v[50:65]
	ds_read_b128 v[244:247], v147 offset:9312
	global_load_dwordx4 v[200:203], v153, s[86:87] offset:1664 sc0
	v_mfma_f32_32x32x16_bf16 v[34:49], v[212:215], v[228:231], v[34:49]
	s_waitcnt vmcnt(15)
	ds_write_b128 v149, v[172:175] offset:64512
	s_waitcnt lgkmcnt(8)
	v_mfma_f32_32x32x16_bf16 v[18:33], v[208:211], v[232:235], v[18:33]
	ds_read_b128 v[228:231], v147 offset:13920
	v_mfma_f32_32x32x16_bf16 v[2:17], v[212:215], v[232:235], v[2:17]
	global_load_dwordx4 v[172:175], v153, s[80:81] offset:1664 sc0
	s_waitcnt lgkmcnt(6)
	v_mfma_f32_32x32x16_bf16 v[98:113], v[216:219], v[236:239], v[98:113]
	s_waitcnt vmcnt(15)
	ds_write_b128 v152, v[204:207] offset:64512
	s_waitcnt lgkmcnt(6)
	v_mfma_f32_32x32x16_bf16 v[114:129], v[224:227], v[236:239], v[114:129]
	s_waitcnt lgkmcnt(4)
	v_mfma_f32_32x32x16_bf16 v[82:97], v[216:219], v[240:243], v[82:97]
	global_load_dwordx4 v[204:207], v153, s[92:93] offset:1664 sc0
	v_mfma_f32_32x32x16_bf16 v[66:81], v[224:227], v[240:243], v[66:81]
	s_waitcnt lgkmcnt(3)
	v_mfma_f32_32x32x16_bf16 v[50:65], v[216:219], v[244:247], v[50:65]
	v_mfma_f32_32x32x16_bf16 v[34:49], v[224:227], v[244:247], v[34:49]
	s_waitcnt lgkmcnt(1)
	v_mfma_f32_32x32x16_bf16 v[18:33], v[216:219], v[228:231], v[18:33]
	v_mfma_f32_32x32x16_bf16 v[2:17], v[224:227], v[228:231], v[2:17]
	s_waitcnt lgkmcnt(0)
	s_barrier
;     ...
;   for (int kt = 0; kt < nk; ++kt) {
;     __syncthreads();
;     if (kt + 1 < nk) {
;       u16* aw = As0 + ((kt + 1) & 1) * 256 * LD;
;       u16* bw = Bs0 + ((kt + 1) & 1) * 256 * LD;
; #pragma unroll
;       for (int i = 0; i < 4; ++i) { *(u32x4*)(aw + (srow + 64 * i) * LD + skc * 8) = ra[i]; *(u32x4*)(bw + (srow + 64 * i) * LD + skc * 8) = rb[i]; }
;     }
;     if (kt + 2 < nk) {
; #pragma unroll
;       for (int i = 0; i < 4; ++i) { ra[i] = *(const u32x4*)(Ag + (size_t)(64 * i) * K + (kt + 2) * 64); rb[i] = *(const u32x4*)(Bg[i] + (kt + 2) * 64); }
;     }
;     __builtin_amdgcn_sched_barrier(0);
;     const u16* as = As0 + (kt & 1) * 256 * LD + (wr * 128 + l31) * LD + h * 8;
;     const u16* bs = Bs0 + (kt & 1) * 256 * LD + (wc * 64 + l31) * LD + h * 8;
;     if (domma)
; #pragma unroll
;     for (int ks = 0; ks < 4; ++ks) {
;       bf16x8 wf[2], xf[4];
; #pragma unroll
;       for (int ct = 0; ct < 2; ++ct) wf[ct] = *(const bf16x8*)(bs + ct * 32 * LD + ks * 16);
; #pragma unroll
;       for (int tt = 0; tt < 4; ++tt) xf[tt] = *(const bf16x8*)(as + tt * 32 * LD + ks * 16);
; #pragma unroll
;       for (int ct = 0; ct < 2; ++ct)
; #pragma unroll
;         for (int tt = 0; tt < 4; ++tt) acc[ct][tt] = __builtin_amdgcn_mfma_f32_32x32x16_bf16(wf[ct], xf[tt], acc[ct][tt], 0, 0, 0);
;     }
	ds_read_b128 v[208:211], v148 offset:36864
	ds_read_b128 v[228:231], v147 offset:36864
	ds_read_b128 v[212:215], v148 offset:41472
	ds_read_b128 v[232:235], v147 offset:41472
	ds_read_b128 v[236:239], v147 offset:46080
	ds_read_b128 v[240:243], v147 offset:50688
	s_waitcnt lgkmcnt(4)
	v_mfma_f32_32x32x16_bf16 v[98:113], v[208:211], v[228:231], v[98:113]
	ds_read_b128 v[216:219], v148 offset:36896
	s_waitcnt lgkmcnt(4)
	v_mfma_f32_32x32x16_bf16 v[114:129], v[212:215], v[228:231], v[114:129]
	ds_read_b128 v[244:247], v147 offset:36896
	s_waitcnt lgkmcnt(4)
	v_mfma_f32_32x32x16_bf16 v[82:97], v[208:211], v[232:235], v[82:97]
	ds_read_b128 v[224:227], v148 offset:41504
	v_mfma_f32_32x32x16_bf16 v[66:81], v[212:215], v[232:235], v[66:81]
	ds_read_b128 v[228:231], v147 offset:41504
	s_waitcnt vmcnt(15)
	ds_write_b128 v149, v[130:133]
	s_waitcnt lgkmcnt(6)
	v_mfma_f32_32x32x16_bf16 v[50:65], v[208:211], v[236:239], v[50:65]
	ds_read_b128 v[232:235], v147 offset:46112
	v_mfma_f32_32x32x16_bf16 v[34:49], v[212:215], v[236:239], v[34:49]
	global_load_dwordx4 v[130:133], v153, s[74:75] offset:1792 sc0
	s_waitcnt lgkmcnt(6)
	v_mfma_f32_32x32x16_bf16 v[18:33], v[208:211], v[240:243], v[18:33]
	ds_read_b128 v[236:239], v147 offset:50720
	s_waitcnt vmcnt(15)
	ds_write_b128 v152, v[176:179]
	v_mfma_f32_32x32x16_bf16 v[2:17], v[212:215], v[240:243], v[2:17]
	s_waitcnt lgkmcnt(6)
	v_mfma_f32_32x32x16_bf16 v[98:113], v[216:219], v[244:247], v[98:113]
	ds_read_b128 v[208:211], v148 offset:36928
	global_load_dwordx4 v[176:179], v153, s[82:83] offset:1792 sc0
	s_waitcnt lgkmcnt(6)
	v_mfma_f32_32x32x16_bf16 v[114:129], v[224:227], v[244:247], v[114:129]
	ds_read_b128 v[240:243], v147 offset:36928
	s_waitcnt vmcnt(15)
	ds_write_b128 v149, v[134:137] offset:9216
	s_waitcnt lgkmcnt(7)
	v_mfma_f32_32x32x16_bf16 v[82:97], v[216:219], v[228:231], v[82:97]
	ds_read_b128 v[212:215], v148 offset:41536
	v_mfma_f32_32x32x16_bf16 v[66:81], v[224:227], v[228:231], v[66:81]
	ds_read_b128 v[244:247], v147 offset:41536
	global_load_dwordx4 v[134:137], v153, s[76:77] offset:1792 sc0
	s_waitcnt lgkmcnt(7)
	v_mfma_f32_32x32x16_bf16 v[50:65], v[216:219], v[232:235], v[50:65]
	ds_read_b128 v[228:231], v147 offset:46144
	s_waitcnt vmcnt(15)
	ds_write_b128 v152, v[180:183] offset:9216
	v_mfma_f32_32x32x16_bf16 v[34:49], v[224:227], v[232:235], v[34:49]
	s_waitcnt lgkmcnt(8)
	v_mfma_f32_32x32x16_bf16 v[18:33], v[216:219], v[236:239], v[18:33]
	ds_read_b128 v[232:235], v147 offset:50752
	global_load_dwordx4 v[180:183], v153, s[84:85] offset:1792 sc0
	v_mfma_f32_32x32x16_bf16 v[2:17], v[224:227], v[236:239], v[2:17]
	s_waitcnt vmcnt(15)
	ds_write_b128 v149, v[138:141] offset:18432
	s_waitcnt lgkmcnt(7)
	v_mfma_f32_32x32x16_bf16 v[98:113], v[208:211], v[240:243], v[98:113]
	ds_read_b128 v[216:219], v148 offset:36960
	s_waitcnt lgkmcnt(6)
	v_mfma_f32_32x32x16_bf16 v[114:129], v[212:215], v[240:243], v[114:129]
	ds_read_b128 v[236:239], v147 offset:36960
	global_load_dwordx4 v[138:141], v153, s[78:79] offset:1792 sc0
	s_waitcnt lgkmcnt(6)
	v_mfma_f32_32x32x16_bf16 v[82:97], v[208:211], v[244:247], v[82:97]
	ds_read_b128 v[224:227], v148 offset:41568
	s_waitcnt vmcnt(15)
	ds_write_b128 v152, v[184:187] offset:18432
	v_mfma_f32_32x32x16_bf16 v[66:81], v[212:215], v[244:247], v[66:81]
	ds_read_b128 v[240:243], v147 offset:41568
	s_waitcnt lgkmcnt(8)
	v_mfma_f32_32x32x16_bf16 v[50:65], v[208:211], v[228:231], v[50:65]
	ds_read_b128 v[244:247], v147 offset:46176
	global_load_dwordx4 v[184:187], v153, s[86:87] offset:1792 sc0
	v_mfma_f32_32x32x16_bf16 v[34:49], v[212:215], v[228:231], v[34:49]
	s_waitcnt vmcnt(15)
	ds_write_b128 v149, v[142:145] offset:27648
	s_waitcnt lgkmcnt(8)
	v_mfma_f32_32x32x16_bf16 v[18:33], v[208:211], v[232:235], v[18:33]
	ds_read_b128 v[228:231], v147 offset:50784
	v_mfma_f32_32x32x16_bf16 v[2:17], v[212:215], v[232:235], v[2:17]
	global_load_dwordx4 v[142:145], v153, s[80:81] offset:1792 sc0
	s_waitcnt lgkmcnt(6)
	v_mfma_f32_32x32x16_bf16 v[98:113], v[216:219], v[236:239], v[98:113]
	s_waitcnt vmcnt(15)
	ds_write_b128 v152, v[188:191] offset:27648
	s_waitcnt lgkmcnt(6)
	v_mfma_f32_32x32x16_bf16 v[114:129], v[224:227], v[236:239], v[114:129]
	s_waitcnt lgkmcnt(4)
	v_mfma_f32_32x32x16_bf16 v[82:97], v[216:219], v[240:243], v[82:97]
	global_load_dwordx4 v[188:191], v153, s[92:93] offset:1792 sc0
	v_mfma_f32_32x32x16_bf16 v[66:81], v[224:227], v[240:243], v[66:81]
	s_waitcnt lgkmcnt(3)
	v_mfma_f32_32x32x16_bf16 v[50:65], v[216:219], v[244:247], v[50:65]
	v_mfma_f32_32x32x16_bf16 v[34:49], v[224:227], v[244:247], v[34:49]
	s_waitcnt lgkmcnt(1)
	v_mfma_f32_32x32x16_bf16 v[18:33], v[216:219], v[228:231], v[18:33]
	v_mfma_f32_32x32x16_bf16 v[2:17], v[224:227], v[228:231], v[2:17]
	s_waitcnt lgkmcnt(0)
	s_barrier
;     ...
;   for (int kt = 0; kt < nk; ++kt) {
;     __syncthreads();
;     if (kt + 1 < nk) {
;       u16* aw = As0 + ((kt + 1) & 1) * 256 * LD;
;       u16* bw = Bs0 + ((kt + 1) & 1) * 256 * LD;
; #pragma unroll
;       for (int i = 0; i < 4; ++i) { *(u32x4*)(aw + (srow + 64 * i) * LD + skc * 8) = ra[i]; *(u32x4*)(bw + (srow + 64 * i) * LD + skc * 8) = rb[i]; }
;     }
;     if (kt + 2 < nk) {
; #pragma unroll
;       for (int i = 0; i < 4; ++i) { ra[i] = *(const u32x4*)(Ag + (size_t)(64 * i) * K + (kt + 2) * 64); rb[i] = *(const u32x4*)(Bg[i] + (kt + 2) * 64); }
;     }
;     __builtin_amdgcn_sched_barrier(0);
;     const u16* as = As0 + (kt & 1) * 256 * LD + (wr * 128 + l31) * LD + h * 8;
;     const u16* bs = Bs0 + (kt & 1) * 256 * LD + (wc * 64 + l31) * LD + h * 8;
;     if (domma)
; #pragma unroll
;     for (int ks = 0; ks < 4; ++ks) {
;       bf16x8 wf[2], xf[4];
; #pragma unroll
;       for (int ct = 0; ct < 2; ++ct) wf[ct] = *(const bf16x8*)(bs + ct * 32 * LD + ks * 16);
; #pragma unroll
;       for (int tt = 0; tt < 4; ++tt) xf[tt] = *(const bf16x8*)(as + tt * 32 * LD + ks * 16);
; #pragma unroll
;       for (int ct = 0; ct < 2; ++ct)
; #pragma unroll
;         for (int tt = 0; tt < 4; ++tt) acc[ct][tt] = __builtin_amdgcn_mfma_f32_32x32x16_bf16(wf[ct], xf[tt], acc[ct][tt], 0, 0, 0);
;     }
	ds_read_b128 v[208:211], v148
	ds_read_b128 v[228:231], v147
	ds_read_b128 v[212:215], v148 offset:4608
	ds_read_b128 v[232:235], v147 offset:4608
	ds_read_b128 v[236:239], v147 offset:9216
	ds_read_b128 v[240:243], v147 offset:13824
	s_waitcnt lgkmcnt(4)
	v_mfma_f32_32x32x16_bf16 v[98:113], v[208:211], v[228:231], v[98:113]
	ds_read_b128 v[216:219], v148 offset:32
	s_waitcnt lgkmcnt(4)
	v_mfma_f32_32x32x16_bf16 v[114:129], v[212:215], v[228:231], v[114:129]
	ds_read_b128 v[244:247], v147 offset:32
	s_waitcnt lgkmcnt(4)
	v_mfma_f32_32x32x16_bf16 v[82:97], v[208:211], v[232:235], v[82:97]
	ds_read_b128 v[224:227], v148 offset:4640
	v_mfma_f32_32x32x16_bf16 v[66:81], v[212:215], v[232:235], v[66:81]
	ds_read_b128 v[228:231], v147 offset:4640
	s_waitcnt vmcnt(15)
	ds_write_b128 v149, v[160:163] offset:36864
	s_waitcnt lgkmcnt(6)
	v_mfma_f32_32x32x16_bf16 v[50:65], v[208:211], v[236:239], v[50:65]
	ds_read_b128 v[232:235], v147 offset:9248
	v_mfma_f32_32x32x16_bf16 v[34:49], v[212:215], v[236:239], v[34:49]
	global_load_dwordx4 v[160:163], v153, s[74:75] offset:1920 sc0
	s_waitcnt lgkmcnt(6)
	v_mfma_f32_32x32x16_bf16 v[18:33], v[208:211], v[240:243], v[18:33]
	ds_read_b128 v[236:239], v147 offset:13856
	s_waitcnt vmcnt(15)
	ds_write_b128 v152, v[192:195] offset:36864
	v_mfma_f32_32x32x16_bf16 v[2:17], v[212:215], v[240:243], v[2:17]
	s_waitcnt lgkmcnt(6)
	v_mfma_f32_32x32x16_bf16 v[98:113], v[216:219], v[244:247], v[98:113]
	ds_read_b128 v[208:211], v148 offset:64
	global_load_dwordx4 v[192:195], v153, s[82:83] offset:1920 sc0
	s_waitcnt lgkmcnt(6)
	v_mfma_f32_32x32x16_bf16 v[114:129], v[224:227], v[244:247], v[114:129]
	ds_read_b128 v[240:243], v147 offset:64
	s_waitcnt vmcnt(15)
	ds_write_b128 v149, v[164:167] offset:46080
	s_waitcnt lgkmcnt(7)
	v_mfma_f32_32x32x16_bf16 v[82:97], v[216:219], v[228:231], v[82:97]
	ds_read_b128 v[212:215], v148 offset:4672
	v_mfma_f32_32x32x16_bf16 v[66:81], v[224:227], v[228:231], v[66:81]
	ds_read_b128 v[244:247], v147 offset:4672
	global_load_dwordx4 v[164:167], v153, s[76:77] offset:1920 sc0
	s_waitcnt lgkmcnt(7)
	v_mfma_f32_32x32x16_bf16 v[50:65], v[216:219], v[232:235], v[50:65]
	ds_read_b128 v[228:231], v147 offset:9280
	s_waitcnt vmcnt(15)
	ds_write_b128 v152, v[196:199] offset:46080
	v_mfma_f32_32x32x16_bf16 v[34:49], v[224:227], v[232:235], v[34:49]
	s_waitcnt lgkmcnt(8)
	v_mfma_f32_32x32x16_bf16 v[18:33], v[216:219], v[236:239], v[18:33]
	ds_read_b128 v[232:235], v147 offset:13888
	global_load_dwordx4 v[196:199], v153, s[84:85] offset:1920 sc0
	v_mfma_f32_32x32x16_bf16 v[2:17], v[224:227], v[236:239], v[2:17]
	s_waitcnt vmcnt(15)
	ds_write_b128 v149, v[168:171] offset:55296
	s_waitcnt lgkmcnt(7)
	v_mfma_f32_32x32x16_bf16 v[98:113], v[208:211], v[240:243], v[98:113]
	ds_read_b128 v[216:219], v148 offset:96
	s_waitcnt lgkmcnt(6)
	v_mfma_f32_32x32x16_bf16 v[114:129], v[212:215], v[240:243], v[114:129]
	ds_read_b128 v[236:239], v147 offset:96
	global_load_dwordx4 v[168:171], v153, s[78:79] offset:1920 sc0
	s_waitcnt lgkmcnt(6)
	v_mfma_f32_32x32x16_bf16 v[82:97], v[208:211], v[244:247], v[82:97]
	ds_read_b128 v[224:227], v148 offset:4704
	s_waitcnt vmcnt(15)
	ds_write_b128 v152, v[200:203] offset:55296
	v_mfma_f32_32x32x16_bf16 v[66:81], v[212:215], v[244:247], v[66:81]
	ds_read_b128 v[240:243], v147 offset:4704
	s_waitcnt lgkmcnt(8)
	v_mfma_f32_32x32x16_bf16 v[50:65], v[208:211], v[228:231], v[50:65]
	ds_read_b128 v[244:247], v147 offset:9312
	global_load_dwordx4 v[200:203], v153, s[86:87] offset:1920 sc0
	v_mfma_f32_32x32x16_bf16 v[34:49], v[212:215], v[228:231], v[34:49]
	s_waitcnt vmcnt(15)
	ds_write_b128 v149, v[172:175] offset:64512
	s_waitcnt lgkmcnt(8)
	v_mfma_f32_32x32x16_bf16 v[18:33], v[208:211], v[232:235], v[18:33]
	ds_read_b128 v[228:231], v147 offset:13920
	v_mfma_f32_32x32x16_bf16 v[2:17], v[212:215], v[232:235], v[2:17]
	global_load_dwordx4 v[172:175], v153, s[80:81] offset:1920 sc0
	s_waitcnt lgkmcnt(6)
	v_mfma_f32_32x32x16_bf16 v[98:113], v[216:219], v[236:239], v[98:113]
	s_waitcnt vmcnt(15)
	ds_write_b128 v152, v[204:207] offset:64512
	s_waitcnt lgkmcnt(6)
	v_mfma_f32_32x32x16_bf16 v[114:129], v[224:227], v[236:239], v[114:129]
	s_waitcnt lgkmcnt(4)
	v_mfma_f32_32x32x16_bf16 v[82:97], v[216:219], v[240:243], v[82:97]
	global_load_dwordx4 v[204:207], v153, s[92:93] offset:1920 sc0
	v_mfma_f32_32x32x16_bf16 v[66:81], v[224:227], v[240:243], v[66:81]
	s_waitcnt lgkmcnt(3)
	v_mfma_f32_32x32x16_bf16 v[50:65], v[216:219], v[244:247], v[50:65]
	v_mfma_f32_32x32x16_bf16 v[34:49], v[224:227], v[244:247], v[34:49]
	s_waitcnt lgkmcnt(1)
	v_mfma_f32_32x32x16_bf16 v[18:33], v[216:219], v[228:231], v[18:33]
	v_mfma_f32_32x32x16_bf16 v[2:17], v[224:227], v[228:231], v[2:17]
	s_waitcnt lgkmcnt(0)
	s_barrier
;     ...
;   for (int kt = 0; kt < nk; ++kt) {
;     __syncthreads();
;     if (kt + 1 < nk) {
;       u16* aw = As0 + ((kt + 1) & 1) * 256 * LD;
;       u16* bw = Bs0 + ((kt + 1) & 1) * 256 * LD;
; #pragma unroll
;       for (int i = 0; i < 4; ++i) { *(u32x4*)(aw + (srow + 64 * i) * LD + skc * 8) = ra[i]; *(u32x4*)(bw + (srow + 64 * i) * LD + skc * 8) = rb[i]; }
;     }
;     if (kt + 2 < nk) {
; #pragma unroll
;       for (int i = 0; i < 4; ++i) { ra[i] = *(const u32x4*)(Ag + (size_t)(64 * i) * K + (kt + 2) * 64); rb[i] = *(const u32x4*)(Bg[i] + (kt + 2) * 64); }
;     }
;     __builtin_amdgcn_sched_barrier(0);
;     const u16* as = As0 + (kt & 1) * 256 * LD + (wr * 128 + l31) * LD + h * 8;
;     const u16* bs = Bs0 + (kt & 1) * 256 * LD + (wc * 64 + l31) * LD + h * 8;
;     if (domma)
; #pragma unroll
;     for (int ks = 0; ks < 4; ++ks) {
;       bf16x8 wf[2], xf[4];
; #pragma unroll
;       for (int ct = 0; ct < 2; ++ct) wf[ct] = *(const bf16x8*)(bs + ct * 32 * LD + ks * 16);
; #pragma unroll
;       for (int tt = 0; tt < 4; ++tt) xf[tt] = *(const bf16x8*)(as + tt * 32 * LD + ks * 16);
; #pragma unroll
;       for (int ct = 0; ct < 2; ++ct)
; #pragma unroll
;         for (int tt = 0; tt < 4; ++tt) acc[ct][tt] = __builtin_amdgcn_mfma_f32_32x32x16_bf16(wf[ct], xf[tt], acc[ct][tt], 0, 0, 0);
;     }
	ds_read_b128 v[208:211], v148 offset:36864
	ds_read_b128 v[228:231], v147 offset:36864
	ds_read_b128 v[212:215], v148 offset:41472
	ds_read_b128 v[232:235], v147 offset:41472
	ds_read_b128 v[236:239], v147 offset:46080
	ds_read_b128 v[240:243], v147 offset:50688
	s_waitcnt lgkmcnt(4)
	v_mfma_f32_32x32x16_bf16 v[98:113], v[208:211], v[228:231], v[98:113]
	ds_read_b128 v[216:219], v148 offset:36896
	s_waitcnt lgkmcnt(4)
	v_mfma_f32_32x32x16_bf16 v[114:129], v[212:215], v[228:231], v[114:129]
	ds_read_b128 v[244:247], v147 offset:36896
	s_waitcnt lgkmcnt(4)
	v_mfma_f32_32x32x16_bf16 v[82:97], v[208:211], v[232:235], v[82:97]
	ds_read_b128 v[224:227], v148 offset:41504
	v_mfma_f32_32x32x16_bf16 v[66:81], v[212:215], v[232:235], v[66:81]
	ds_read_b128 v[228:231], v147 offset:41504
	s_waitcnt vmcnt(15)
	ds_write_b128 v149, v[130:133]
	s_waitcnt lgkmcnt(6)
	v_mfma_f32_32x32x16_bf16 v[50:65], v[208:211], v[236:239], v[50:65]
	ds_read_b128 v[232:235], v147 offset:46112
	v_mfma_f32_32x32x16_bf16 v[34:49], v[212:215], v[236:239], v[34:49]
	s_waitcnt lgkmcnt(6)
	v_mfma_f32_32x32x16_bf16 v[18:33], v[208:211], v[240:243], v[18:33]
	ds_read_b128 v[236:239], v147 offset:50720
	s_waitcnt vmcnt(14)
	ds_write_b128 v152, v[176:179]
	v_mfma_f32_32x32x16_bf16 v[2:17], v[212:215], v[240:243], v[2:17]
	s_waitcnt lgkmcnt(6)
	v_mfma_f32_32x32x16_bf16 v[98:113], v[216:219], v[244:247], v[98:113]
	ds_read_b128 v[208:211], v148 offset:36928
	s_waitcnt lgkmcnt(6)
	v_mfma_f32_32x32x16_bf16 v[114:129], v[224:227], v[244:247], v[114:129]
	ds_read_b128 v[240:243], v147 offset:36928
	s_waitcnt vmcnt(13)
	ds_write_b128 v149, v[134:137] offset:9216
	s_waitcnt lgkmcnt(7)
	v_mfma_f32_32x32x16_bf16 v[82:97], v[216:219], v[228:231], v[82:97]
	ds_read_b128 v[212:215], v148 offset:41536
	v_mfma_f32_32x32x16_bf16 v[66:81], v[224:227], v[228:231], v[66:81]
	ds_read_b128 v[244:247], v147 offset:41536
	s_waitcnt lgkmcnt(7)
	v_mfma_f32_32x32x16_bf16 v[50:65], v[216:219], v[232:235], v[50:65]
	ds_read_b128 v[228:231], v147 offset:46144
	s_waitcnt vmcnt(12)
	ds_write_b128 v152, v[180:183] offset:9216
	v_mfma_f32_32x32x16_bf16 v[34:49], v[224:227], v[232:235], v[34:49]
	s_waitcnt lgkmcnt(8)
	v_mfma_f32_32x32x16_bf16 v[18:33], v[216:219], v[236:239], v[18:33]
	ds_read_b128 v[232:235], v147 offset:50752
	v_mfma_f32_32x32x16_bf16 v[2:17], v[224:227], v[236:239], v[2:17]
	s_waitcnt vmcnt(11)
	ds_write_b128 v149, v[138:141] offset:18432
	s_waitcnt lgkmcnt(7)
	v_mfma_f32_32x32x16_bf16 v[98:113], v[208:211], v[240:243], v[98:113]
	ds_read_b128 v[216:219], v148 offset:36960
	s_waitcnt lgkmcnt(6)
	v_mfma_f32_32x32x16_bf16 v[114:129], v[212:215], v[240:243], v[114:129]
	ds_read_b128 v[236:239], v147 offset:36960
	s_waitcnt lgkmcnt(6)
	v_mfma_f32_32x32x16_bf16 v[82:97], v[208:211], v[244:247], v[82:97]
	ds_read_b128 v[224:227], v148 offset:41568
	s_waitcnt vmcnt(10)
	ds_write_b128 v152, v[184:187] offset:18432
	v_mfma_f32_32x32x16_bf16 v[66:81], v[212:215], v[244:247], v[66:81]
	ds_read_b128 v[240:243], v147 offset:41568
	s_waitcnt lgkmcnt(8)
	v_mfma_f32_32x32x16_bf16 v[50:65], v[208:211], v[228:231], v[50:65]
	ds_read_b128 v[244:247], v147 offset:46176
	v_mfma_f32_32x32x16_bf16 v[34:49], v[212:215], v[228:231], v[34:49]
	s_waitcnt vmcnt(9)
	ds_write_b128 v149, v[142:145] offset:27648
	s_waitcnt lgkmcnt(8)
	v_mfma_f32_32x32x16_bf16 v[18:33], v[208:211], v[232:235], v[18:33]
	ds_read_b128 v[228:231], v147 offset:50784
	v_mfma_f32_32x32x16_bf16 v[2:17], v[212:215], v[232:235], v[2:17]
	s_waitcnt lgkmcnt(6)
	v_mfma_f32_32x32x16_bf16 v[98:113], v[216:219], v[236:239], v[98:113]
	s_waitcnt vmcnt(8)
	ds_write_b128 v152, v[188:191] offset:27648
	s_waitcnt lgkmcnt(6)
	v_mfma_f32_32x32x16_bf16 v[114:129], v[224:227], v[236:239], v[114:129]
	s_waitcnt lgkmcnt(4)
	v_mfma_f32_32x32x16_bf16 v[82:97], v[216:219], v[240:243], v[82:97]
	v_mfma_f32_32x32x16_bf16 v[66:81], v[224:227], v[240:243], v[66:81]
	s_waitcnt lgkmcnt(3)
	v_mfma_f32_32x32x16_bf16 v[50:65], v[216:219], v[244:247], v[50:65]
	v_mfma_f32_32x32x16_bf16 v[34:49], v[224:227], v[244:247], v[34:49]
	s_waitcnt lgkmcnt(1)
	v_mfma_f32_32x32x16_bf16 v[18:33], v[216:219], v[228:231], v[18:33]
	v_mfma_f32_32x32x16_bf16 v[2:17], v[224:227], v[228:231], v[2:17]
	s_waitcnt lgkmcnt(0)
	s_barrier
;     ...
;   for (int kt = 0; kt < nk; ++kt) {
;     __syncthreads();
;     if (kt + 1 < nk) {
;       u16* aw = As0 + ((kt + 1) & 1) * 256 * LD;
;       u16* bw = Bs0 + ((kt + 1) & 1) * 256 * LD;
; #pragma unroll
;       for (int i = 0; i < 4; ++i) { *(u32x4*)(aw + (srow + 64 * i) * LD + skc * 8) = ra[i]; *(u32x4*)(bw + (srow + 64 * i) * LD + skc * 8) = rb[i]; }
;     }
;     if (kt + 2 < nk) {
; #pragma unroll
;       for (int i = 0; i < 4; ++i) { ra[i] = *(const u32x4*)(Ag + (size_t)(64 * i) * K + (kt + 2) * 64); rb[i] = *(const u32x4*)(Bg[i] + (kt + 2) * 64); }
;     }
;     __builtin_amdgcn_sched_barrier(0);
;     const u16* as = As0 + (kt & 1) * 256 * LD + (wr * 128 + l31) * LD + h * 8;
;     const u16* bs = Bs0 + (kt & 1) * 256 * LD + (wc * 64 + l31) * LD + h * 8;
;     if (domma)
; #pragma unroll
;     for (int ks = 0; ks < 4; ++ks) {
;       bf16x8 wf[2], xf[4];
; #pragma unroll
;       for (int ct = 0; ct < 2; ++ct) wf[ct] = *(const bf16x8*)(bs + ct * 32 * LD + ks * 16);
; #pragma unroll
;       for (int tt = 0; tt < 4; ++tt) xf[tt] = *(const bf16x8*)(as + tt * 32 * LD + ks * 16);
; #pragma unroll
;       for (int ct = 0; ct < 2; ++ct)
; #pragma unroll
;         for (int tt = 0; tt < 4; ++tt) acc[ct][tt] = __builtin_amdgcn_mfma_f32_32x32x16_bf16(wf[ct], xf[tt], acc[ct][tt], 0, 0, 0);
;     }
	ds_read_b128 v[208:211], v148
	ds_read_b128 v[228:231], v147
	ds_read_b128 v[212:215], v148 offset:4608
	ds_read_b128 v[232:235], v147 offset:4608
	ds_read_b128 v[236:239], v147 offset:9216
	ds_read_b128 v[240:243], v147 offset:13824
	s_waitcnt lgkmcnt(4)
	v_mfma_f32_32x32x16_bf16 v[98:113], v[208:211], v[228:231], v[98:113]
	ds_read_b128 v[216:219], v148 offset:32
	s_waitcnt lgkmcnt(4)
	v_mfma_f32_32x32x16_bf16 v[114:129], v[212:215], v[228:231], v[114:129]
	ds_read_b128 v[244:247], v147 offset:32
	s_waitcnt lgkmcnt(4)
	v_mfma_f32_32x32x16_bf16 v[82:97], v[208:211], v[232:235], v[82:97]
	ds_read_b128 v[224:227], v148 offset:4640
	v_mfma_f32_32x32x16_bf16 v[66:81], v[212:215], v[232:235], v[66:81]
	ds_read_b128 v[228:231], v147 offset:4640
	s_waitcnt vmcnt(7)
	ds_write_b128 v149, v[160:163] offset:36864
	s_waitcnt lgkmcnt(6)
	v_mfma_f32_32x32x16_bf16 v[50:65], v[208:211], v[236:239], v[50:65]
	ds_read_b128 v[232:235], v147 offset:9248
	v_mfma_f32_32x32x16_bf16 v[34:49], v[212:215], v[236:239], v[34:49]
	s_waitcnt lgkmcnt(6)
	v_mfma_f32_32x32x16_bf16 v[18:33], v[208:211], v[240:243], v[18:33]
	ds_read_b128 v[236:239], v147 offset:13856
	s_waitcnt vmcnt(6)
	ds_write_b128 v152, v[192:195] offset:36864
	v_mfma_f32_32x32x16_bf16 v[2:17], v[212:215], v[240:243], v[2:17]
	s_waitcnt lgkmcnt(6)
	v_mfma_f32_32x32x16_bf16 v[98:113], v[216:219], v[244:247], v[98:113]
	ds_read_b128 v[208:211], v148 offset:64
	s_waitcnt lgkmcnt(6)
	v_mfma_f32_32x32x16_bf16 v[114:129], v[224:227], v[244:247], v[114:129]
	ds_read_b128 v[240:243], v147 offset:64
	s_waitcnt vmcnt(5)
	ds_write_b128 v149, v[164:167] offset:46080
	s_waitcnt lgkmcnt(7)
	v_mfma_f32_32x32x16_bf16 v[82:97], v[216:219], v[228:231], v[82:97]
	ds_read_b128 v[212:215], v148 offset:4672
	v_mfma_f32_32x32x16_bf16 v[66:81], v[224:227], v[228:231], v[66:81]
	ds_read_b128 v[244:247], v147 offset:4672
	s_waitcnt lgkmcnt(7)
	v_mfma_f32_32x32x16_bf16 v[50:65], v[216:219], v[232:235], v[50:65]
	ds_read_b128 v[228:231], v147 offset:9280
	s_waitcnt vmcnt(4)
	ds_write_b128 v152, v[196:199] offset:46080
	v_mfma_f32_32x32x16_bf16 v[34:49], v[224:227], v[232:235], v[34:49]
	s_waitcnt lgkmcnt(8)
	v_mfma_f32_32x32x16_bf16 v[18:33], v[216:219], v[236:239], v[18:33]
	ds_read_b128 v[232:235], v147 offset:13888
	v_mfma_f32_32x32x16_bf16 v[2:17], v[224:227], v[236:239], v[2:17]
	s_waitcnt vmcnt(3)
	ds_write_b128 v149, v[168:171] offset:55296
	s_waitcnt lgkmcnt(7)
	v_mfma_f32_32x32x16_bf16 v[98:113], v[208:211], v[240:243], v[98:113]
	ds_read_b128 v[216:219], v148 offset:96
	s_waitcnt lgkmcnt(6)
	v_mfma_f32_32x32x16_bf16 v[114:129], v[212:215], v[240:243], v[114:129]
	ds_read_b128 v[236:239], v147 offset:96
	s_waitcnt lgkmcnt(6)
	v_mfma_f32_32x32x16_bf16 v[82:97], v[208:211], v[244:247], v[82:97]
	ds_read_b128 v[224:227], v148 offset:4704
	s_waitcnt vmcnt(2)
	ds_write_b128 v152, v[200:203] offset:55296
	v_mfma_f32_32x32x16_bf16 v[66:81], v[212:215], v[244:247], v[66:81]
	ds_read_b128 v[240:243], v147 offset:4704
	s_waitcnt lgkmcnt(8)
	v_mfma_f32_32x32x16_bf16 v[50:65], v[208:211], v[228:231], v[50:65]
	ds_read_b128 v[244:247], v147 offset:9312
	v_mfma_f32_32x32x16_bf16 v[34:49], v[212:215], v[228:231], v[34:49]
	s_waitcnt vmcnt(1)
	ds_write_b128 v149, v[172:175] offset:64512
	s_waitcnt lgkmcnt(8)
	v_mfma_f32_32x32x16_bf16 v[18:33], v[208:211], v[232:235], v[18:33]
	ds_read_b128 v[228:231], v147 offset:13920
	v_mfma_f32_32x32x16_bf16 v[2:17], v[212:215], v[232:235], v[2:17]
	s_waitcnt lgkmcnt(6)
	v_mfma_f32_32x32x16_bf16 v[98:113], v[216:219], v[236:239], v[98:113]
	s_waitcnt vmcnt(0)
	ds_write_b128 v152, v[204:207] offset:64512
	s_waitcnt lgkmcnt(6)
	v_mfma_f32_32x32x16_bf16 v[114:129], v[224:227], v[236:239], v[114:129]
	s_waitcnt lgkmcnt(4)
	v_mfma_f32_32x32x16_bf16 v[82:97], v[216:219], v[240:243], v[82:97]
	v_mfma_f32_32x32x16_bf16 v[66:81], v[224:227], v[240:243], v[66:81]
	s_waitcnt lgkmcnt(3)
	v_mfma_f32_32x32x16_bf16 v[50:65], v[216:219], v[244:247], v[50:65]
	v_mfma_f32_32x32x16_bf16 v[34:49], v[224:227], v[244:247], v[34:49]
	s_waitcnt lgkmcnt(1)
	v_mfma_f32_32x32x16_bf16 v[18:33], v[216:219], v[228:231], v[18:33]
	v_mfma_f32_32x32x16_bf16 v[2:17], v[224:227], v[228:231], v[2:17]
	s_waitcnt lgkmcnt(0)
	s_barrier
	ds_read_b128 v[208:211], v148 offset:36864
	ds_read_b128 v[228:231], v147 offset:36864
	ds_read_b128 v[212:215], v148 offset:41472
	ds_read_b128 v[232:235], v147 offset:41472
	ds_read_b128 v[236:239], v147 offset:46080
	ds_read_b128 v[240:243], v147 offset:50688
	s_waitcnt lgkmcnt(4)
	v_mfma_f32_32x32x16_bf16 v[98:113], v[208:211], v[228:231], v[98:113]
	ds_read_b128 v[216:219], v148 offset:36896
	s_waitcnt lgkmcnt(4)
	v_mfma_f32_32x32x16_bf16 v[114:129], v[212:215], v[228:231], v[114:129]
	ds_read_b128 v[244:247], v147 offset:36896
	s_waitcnt lgkmcnt(4)
	v_mfma_f32_32x32x16_bf16 v[82:97], v[208:211], v[232:235], v[82:97]
	ds_read_b128 v[224:227], v148 offset:41504
	v_mfma_f32_32x32x16_bf16 v[66:81], v[212:215], v[232:235], v[66:81]
	ds_read_b128 v[228:231], v147 offset:41504
	s_waitcnt lgkmcnt(5)
	v_mfma_f32_32x32x16_bf16 v[50:65], v[208:211], v[236:239], v[50:65]
	ds_read_b128 v[232:235], v147 offset:46112
	v_mfma_f32_32x32x16_bf16 v[34:49], v[212:215], v[236:239], v[34:49]
	s_waitcnt lgkmcnt(5)
	v_mfma_f32_32x32x16_bf16 v[18:33], v[208:211], v[240:243], v[18:33]
	ds_read_b128 v[236:239], v147 offset:50720
	v_mfma_f32_32x32x16_bf16 v[2:17], v[212:215], v[240:243], v[2:17]
	s_waitcnt lgkmcnt(4)
	v_mfma_f32_32x32x16_bf16 v[98:113], v[216:219], v[244:247], v[98:113]
	ds_read_b128 v[208:211], v148 offset:36928
	s_waitcnt lgkmcnt(4)
	v_mfma_f32_32x32x16_bf16 v[114:129], v[224:227], v[244:247], v[114:129]
	ds_read_b128 v[240:243], v147 offset:36928
	s_waitcnt lgkmcnt(4)
;     ...
;     for (int ks = 0; ks < 4; ++ks) {
;       bf16x8 wf[2], xf[4];
; #pragma unroll
;       for (int ct = 0; ct < 2; ++ct) wf[ct] = *(const bf16x8*)(bs + ct * 32 * LD + ks * 16);
; #pragma unroll
;       for (int tt = 0; tt < 4; ++tt) xf[tt] = *(const bf16x8*)(as + tt * 32 * LD + ks * 16);
; #pragma unroll
;       for (int ct = 0; ct < 2; ++ct)
; #pragma unroll
;         for (int tt = 0; tt < 4; ++tt) acc[ct][tt] = __builtin_amdgcn_mfma_f32_32x32x16_bf16(wf[ct], xf[tt], acc[ct][tt], 0, 0, 0);
;     }
; __device__ void phase_gemm2(const Params& p, char* lds, int bid, int nb, bool fused) {
;     ...
;       for (int tt = 0; tt < 4; ++tt) {
;         const int tok = m0 + wr * 128 + tt * 32 + l31;
;         const float* xr = p.x + (size_t)tok * DM + n0 + wc * 64;
;         float ss = 0.f;
; #pragma unroll
;         for (int ct = 0; ct < 2; ++ct)
; #pragma unroll
;           for (int rq = 0; rq < 4; ++rq) {
;             const f32x4 xv = *(const f32x4*)(xr + ct * 32 + 8 * rq + 4 * h);
; #pragma unroll
;             for (int e = 0; e < 4; ++e) { acc[ct][tt][rq * 4 + e] += xv[e]; ss += acc[ct][tt][rq * 4 + e] * acc[ct][tt][rq * 4 + e]; }
;           }
;         ss += __shfl_xor(ss, 32);
;         olds[tt] = 0.f;
;         if (h == 0) olds[tt] = atomicAdd(p.ssq + tok, ss);
;       }
	v_mfma_f32_32x32x16_bf16 v[82:97], v[216:219], v[228:231], v[82:97]
	ds_read_b128 v[212:215], v148 offset:41536
	v_mfma_f32_32x32x16_bf16 v[66:81], v[224:227], v[228:231], v[66:81]
	ds_read_b128 v[244:247], v147 offset:41536
	s_waitcnt lgkmcnt(5)
	v_mfma_f32_32x32x16_bf16 v[50:65], v[216:219], v[232:235], v[50:65]
	ds_read_b128 v[228:231], v147 offset:46144
	v_mfma_f32_32x32x16_bf16 v[34:49], v[224:227], v[232:235], v[34:49]
	s_waitcnt lgkmcnt(5)
	v_mfma_f32_32x32x16_bf16 v[18:33], v[216:219], v[236:239], v[18:33]
	ds_read_b128 v[232:235], v147 offset:50752
	v_mfma_f32_32x32x16_bf16 v[2:17], v[224:227], v[236:239], v[2:17]
	s_waitcnt lgkmcnt(4)
	v_mfma_f32_32x32x16_bf16 v[98:113], v[208:211], v[240:243], v[98:113]
	ds_read_b128 v[216:219], v148 offset:36960
	s_waitcnt lgkmcnt(4)
	v_mfma_f32_32x32x16_bf16 v[114:129], v[212:215], v[240:243], v[114:129]
	ds_read_b128 v[236:239], v147 offset:36960
	s_waitcnt lgkmcnt(4)
	v_mfma_f32_32x32x16_bf16 v[82:97], v[208:211], v[244:247], v[82:97]
	ds_read_b128 v[224:227], v148 offset:41568
	v_mfma_f32_32x32x16_bf16 v[66:81], v[212:215], v[244:247], v[66:81]
	ds_read_b128 v[240:243], v147 offset:41568
	s_waitcnt lgkmcnt(5)
	v_mfma_f32_32x32x16_bf16 v[50:65], v[208:211], v[228:231], v[50:65]
	ds_read_b128 v[244:247], v147 offset:46176
	v_mfma_f32_32x32x16_bf16 v[34:49], v[212:215], v[228:231], v[34:49]
	s_waitcnt lgkmcnt(5)
	v_mfma_f32_32x32x16_bf16 v[18:33], v[208:211], v[232:235], v[18:33]
	ds_read_b128 v[228:231], v147 offset:50784
	v_mfma_f32_32x32x16_bf16 v[2:17], v[212:215], v[232:235], v[2:17]
	s_waitcnt lgkmcnt(4)
	v_mfma_f32_32x32x16_bf16 v[98:113], v[216:219], v[236:239], v[98:113]
	s_waitcnt lgkmcnt(3)
	v_mfma_f32_32x32x16_bf16 v[114:129], v[224:227], v[236:239], v[114:129]
	s_waitcnt lgkmcnt(2)
	v_mfma_f32_32x32x16_bf16 v[82:97], v[216:219], v[240:243], v[82:97]
	v_mfma_f32_32x32x16_bf16 v[66:81], v[224:227], v[240:243], v[66:81]
	s_waitcnt lgkmcnt(1)
	v_mfma_f32_32x32x16_bf16 v[50:65], v[216:219], v[244:247], v[50:65]
	v_mfma_f32_32x32x16_bf16 v[34:49], v[224:227], v[244:247], v[34:49]
	s_waitcnt lgkmcnt(0)
	v_mfma_f32_32x32x16_bf16 v[18:33], v[216:219], v[228:231], v[18:33]
	v_mfma_f32_32x32x16_bf16 v[2:17], v[224:227], v[228:231], v[2:17]
	s_andn2_b64 vcc, exec, s[12:13]
	s_cbranch_vccnz .Lp5_slow
	v_or_b32_e32 v130, s38, v146
	v_add_u32_e32 v152, s5, v130
	s_lshl_b32 s14, s4, 2
	s_lshl_b32 s36, s34, 2
	s_add_i32 s36, s36, s14
	v_lshl_add_u32 v162, v152, 12, v150
	v_lshlrev_b32_e32 v163, 2, v152
	s_add_u32 s54, s24, s36
	s_addc_u32 s55, s25, 0
	s_add_u32 s56, s54, 0x20000
	s_addc_u32 s57, s55, 0
	s_add_u32 s58, s54, 0x40000
	s_addc_u32 s59, s55, 0
	s_add_u32 s60, s54, 0x60000
	s_addc_u32 s61, s55, 0
	global_load_dwordx4 v[164:167], v162, s[54:55]
	global_load_dwordx4 v[168:171], v162, s[54:55] offset:32
	global_load_dwordx4 v[172:175], v162, s[54:55] offset:64
	global_load_dwordx4 v[176:179], v162, s[54:55] offset:96
	global_load_dwordx4 v[180:183], v162, s[54:55] offset:128
	global_load_dwordx4 v[184:187], v162, s[54:55] offset:160
	global_load_dwordx4 v[188:191], v162, s[54:55] offset:192
	global_load_dwordx4 v[192:195], v162, s[54:55] offset:224
	global_load_dwordx4 v[224:227], v162, s[56:57]
	global_load_dwordx4 v[228:231], v162, s[56:57] offset:32
	global_load_dwordx4 v[232:235], v162, s[56:57] offset:64
	global_load_dwordx4 v[236:239], v162, s[56:57] offset:96
	global_load_dwordx4 v[240:243], v162, s[56:57] offset:128
	global_load_dwordx4 v[244:247], v162, s[56:57] offset:160
	global_load_dwordx4 v[248:251], v162, s[56:57] offset:192
	global_load_dwordx4 v[252:255], v162, s[56:57] offset:224
	global_load_dwordx4 v[196:199], v162, s[58:59]
	global_load_dwordx4 v[200:203], v162, s[58:59] offset:32
	global_load_dwordx4 v[204:207], v162, s[58:59] offset:64
	global_load_dwordx4 v[208:211], v162, s[58:59] offset:96
	global_load_dwordx4 v[212:215], v162, s[58:59] offset:128
	global_load_dwordx4 v[216:219], v162, s[58:59] offset:160
	global_load_dwordx4 v[130:133], v162, s[58:59] offset:192
	global_load_dwordx4 v[134:137], v162, s[58:59] offset:224
	v_mbcnt_lo_u32_b32 v160, -1, 0
	v_mbcnt_hi_u32_b32 v160, -1, v160
	v_xor_b32_e32 v160, 32, v160
	v_lshlrev_b32_e32 v160, 2, v160
	v_cmp_eq_u32_e64 s[62:63], 0, v159
	s_add_u32 s66, s8, s36
	s_addc_u32 s67, s9, 0
	s_waitcnt vmcnt(16)
	v_pk_add_f32 v[98:99], v[98:99], v[164:165]
	v_pk_add_f32 v[100:101], v[100:101], v[166:167]
	v_pk_add_f32 v[102:103], v[102:103], v[168:169]
	v_pk_add_f32 v[104:105], v[104:105], v[170:171]
	v_pk_add_f32 v[106:107], v[106:107], v[172:173]
	v_pk_add_f32 v[108:109], v[108:109], v[174:175]
	v_pk_add_f32 v[110:111], v[110:111], v[176:177]
	v_pk_add_f32 v[112:113], v[112:113], v[178:179]
	v_pk_add_f32 v[114:115], v[114:115], v[180:181]
	v_pk_add_f32 v[116:117], v[116:117], v[182:183]
	v_pk_add_f32 v[118:119], v[118:119], v[184:185]
	v_pk_add_f32 v[120:121], v[120:121], v[186:187]
	v_pk_add_f32 v[122:123], v[122:123], v[188:189]
	v_pk_add_f32 v[124:125], v[124:125], v[190:191]
	v_pk_add_f32 v[126:127], v[126:127], v[192:193]
	v_pk_add_f32 v[128:129], v[128:129], v[194:195]
	v_pk_mul_f32 v[146:147], v[98:99], v[98:99]
	v_add_f32_e32 v161, v146, v147
	v_pk_mul_f32 v[148:149], v[100:101], v[100:101]
	v_add_f32_e32 v161, v148, v161
	v_add_f32_e32 v161, v149, v161
	v_pk_mul_f32 v[146:147], v[102:103], v[102:103]
	v_add_f32_e32 v161, v146, v161
	v_add_f32_e32 v161, v147, v161
	v_pk_mul_f32 v[148:149], v[104:105], v[104:105]
	v_add_f32_e32 v161, v148, v161
	v_add_f32_e32 v161, v149, v161
	v_pk_mul_f32 v[146:147], v[106:107], v[106:107]
	v_add_f32_e32 v161, v146, v161
	v_add_f32_e32 v161, v147, v161
	v_pk_mul_f32 v[148:149], v[108:109], v[108:109]
	v_add_f32_e32 v161, v148, v161
	v_add_f32_e32 v161, v149, v161
	v_pk_mul_f32 v[146:147], v[110:111], v[110:111]
	v_add_f32_e32 v161, v146, v161
	v_add_f32_e32 v161, v147, v161
	v_pk_mul_f32 v[148:149], v[112:113], v[112:113]
	v_add_f32_e32 v161, v148, v161
	v_add_f32_e32 v161, v149, v161
	v_pk_mul_f32 v[146:147], v[114:115], v[114:115]
	v_add_f32_e32 v161, v146, v161
	v_add_f32_e32 v161, v147, v161
	v_pk_mul_f32 v[148:149], v[116:117], v[116:117]
	v_add_f32_e32 v161, v148, v161
	v_add_f32_e32 v161, v149, v161
	v_pk_mul_f32 v[146:147], v[118:119], v[118:119]
	v_add_f32_e32 v161, v146, v161
	v_add_f32_e32 v161, v147, v161
	v_pk_mul_f32 v[148:149], v[120:121], v[120:121]
	v_add_f32_e32 v161, v148, v161
	v_add_f32_e32 v161, v149, v161
	v_pk_mul_f32 v[146:147], v[122:123], v[122:123]
	v_add_f32_e32 v161, v146, v161
	v_add_f32_e32 v161, v147, v161
	v_pk_mul_f32 v[148:149], v[124:125], v[124:125]
	v_add_f32_e32 v161, v148, v161
	v_add_f32_e32 v161, v149, v161
	v_pk_mul_f32 v[146:147], v[126:127], v[126:127]
	v_add_f32_e32 v161, v146, v161
	v_add_f32_e32 v161, v147, v161
	v_pk_mul_f32 v[148:149], v[128:129], v[128:129]
	v_add_f32_e32 v161, v148, v161
	v_add_f32_e32 v161, v149, v161
	ds_bpermute_b32 v146, v160, v161
	s_waitcnt lgkmcnt(0)
; __device__ void phase_gemm2(const Params& p, char* lds, int bid, int nb, bool fused) {
;     ...
;       for (int tt = 0; tt < 4; ++tt) {
;         const int tok = m0 + wr * 128 + tt * 32 + l31;
;         const float* xr = p.x + (size_t)tok * DM + n0 + wc * 64;
;         float ss = 0.f;
; #pragma unroll
;         for (int ct = 0; ct < 2; ++ct)
; #pragma unroll
;           for (int rq = 0; rq < 4; ++rq) {
;             const f32x4 xv = *(const f32x4*)(xr + ct * 32 + 8 * rq + 4 * h);
; #pragma unroll
;             for (int e = 0; e < 4; ++e) { acc[ct][tt][rq * 4 + e] += xv[e]; ss += acc[ct][tt][rq * 4 + e] * acc[ct][tt][rq * 4 + e]; }
;           }
;         ss += __shfl_xor(ss, 32);
;         olds[tt] = 0.f;
;         if (h == 0) olds[tt] = atomicAdd(p.ssq + tok, ss);
;       }
;       asm volatile("" :: "v"(olds[0]), "v"(olds[1]), "v"(olds[2]), "v"(olds[3]));
;       if (fused) {
;         __syncthreads();
;         if (threadIdx.x == 0) {
;           __hip_atomic_fetch_add(p.pcnt + (m0 >> 8), 1, __ATOMIC_RELAXED, __HIP_MEMORY_SCOPE_AGENT);
;           while (__hip_atomic_load(p.pcnt + (m0 >> 8), __ATOMIC_RELAXED, __HIP_MEMORY_SCOPE_AGENT) < NNT) __builtin_amdgcn_s_sleep(2);
;         }
;         __syncthreads();
;       }
; #pragma unroll
;       for (int tt = 0; tt < 4; ++tt) {
;         const int tok = m0 + wr * 128 + tt * 32 + l31;
;         float sc = 1.f;
;         if (fused) sc = __builtin_amdgcn_rsqf(__hip_atomic_load(p.ssq + tok, __ATOMIC_RELAXED, __HIP_MEMORY_SCOPE_AGENT) * (1.f / DM) + 1e-6f);
;         float* orow = p.out + (size_t)tok * DM + n0 + wc * 64;
;         const float* gr = p.final_gain + n0 + wc * 64;
; #pragma unroll
;         for (int ct = 0; ct < 2; ++ct)
; #pragma unroll
;           for (int rq = 0; rq < 4; ++rq) {
;             const int c = ct * 32 + 8 * rq + 4 * h;
;             f32x4 o;
;             if (fused) {
;               const f32x4 gv = *(const f32x4*)(gr + c);
	v_add_f32_e32 v161, v161, v146
	s_and_saveexec_b64 s[64:65], s[62:63]
	global_atomic_add_f32 v139, v163, v161, s[18:19] sc0
	s_or_b64 exec, exec, s[64:65]
	global_load_dwordx4 v[164:167], v162, s[60:61]
	global_load_dwordx4 v[168:171], v162, s[60:61] offset:32
	global_load_dwordx4 v[172:175], v162, s[60:61] offset:64
	global_load_dwordx4 v[176:179], v162, s[60:61] offset:96
	global_load_dwordx4 v[180:183], v162, s[60:61] offset:128
	global_load_dwordx4 v[184:187], v162, s[60:61] offset:160
	global_load_dwordx4 v[188:191], v162, s[60:61] offset:192
	global_load_dwordx4 v[192:195], v162, s[60:61] offset:224
	s_waitcnt vmcnt(17)
	v_pk_add_f32 v[82:83], v[82:83], v[224:225]
	v_pk_add_f32 v[84:85], v[84:85], v[226:227]
	v_pk_add_f32 v[86:87], v[86:87], v[228:229]
	v_pk_add_f32 v[88:89], v[88:89], v[230:231]
	v_pk_add_f32 v[90:91], v[90:91], v[232:233]
	v_pk_add_f32 v[92:93], v[92:93], v[234:235]
	v_pk_add_f32 v[94:95], v[94:95], v[236:237]
	v_pk_add_f32 v[96:97], v[96:97], v[238:239]
	v_pk_add_f32 v[66:67], v[66:67], v[240:241]
	v_pk_add_f32 v[68:69], v[68:69], v[242:243]
	v_pk_add_f32 v[70:71], v[70:71], v[244:245]
	v_pk_add_f32 v[72:73], v[72:73], v[246:247]
	v_pk_add_f32 v[74:75], v[74:75], v[248:249]
	v_pk_add_f32 v[76:77], v[76:77], v[250:251]
	v_pk_add_f32 v[78:79], v[78:79], v[252:253]
	v_pk_add_f32 v[80:81], v[80:81], v[254:255]
	v_pk_mul_f32 v[146:147], v[82:83], v[82:83]
	v_add_f32_e32 v220, v146, v147
	v_pk_mul_f32 v[148:149], v[84:85], v[84:85]
	v_add_f32_e32 v220, v148, v220
	v_add_f32_e32 v220, v149, v220
	v_pk_mul_f32 v[146:147], v[86:87], v[86:87]
	v_add_f32_e32 v220, v146, v220
	v_add_f32_e32 v220, v147, v220
	v_pk_mul_f32 v[148:149], v[88:89], v[88:89]
	v_add_f32_e32 v220, v148, v220
	v_add_f32_e32 v220, v149, v220
	v_pk_mul_f32 v[146:147], v[90:91], v[90:91]
	v_add_f32_e32 v220, v146, v220
	v_add_f32_e32 v220, v147, v220
	v_pk_mul_f32 v[148:149], v[92:93], v[92:93]
	v_add_f32_e32 v220, v148, v220
	v_add_f32_e32 v220, v149, v220
	v_pk_mul_f32 v[146:147], v[94:95], v[94:95]
	v_add_f32_e32 v220, v146, v220
	v_add_f32_e32 v220, v147, v220
	v_pk_mul_f32 v[148:149], v[96:97], v[96:97]
	v_add_f32_e32 v220, v148, v220
	v_add_f32_e32 v220, v149, v220
	v_pk_mul_f32 v[146:147], v[66:67], v[66:67]
	v_add_f32_e32 v220, v146, v220
	v_add_f32_e32 v220, v147, v220
	v_pk_mul_f32 v[148:149], v[68:69], v[68:69]
	v_add_f32_e32 v220, v148, v220
	v_add_f32_e32 v220, v149, v220
	v_pk_mul_f32 v[146:147], v[70:71], v[70:71]
	v_add_f32_e32 v220, v146, v220
	v_add_f32_e32 v220, v147, v220
	v_pk_mul_f32 v[148:149], v[72:73], v[72:73]
	v_add_f32_e32 v220, v148, v220
	v_add_f32_e32 v220, v149, v220
	v_pk_mul_f32 v[146:147], v[74:75], v[74:75]
	v_add_f32_e32 v220, v146, v220
	v_add_f32_e32 v220, v147, v220
	v_pk_mul_f32 v[148:149], v[76:77], v[76:77]
	v_add_f32_e32 v220, v148, v220
	v_add_f32_e32 v220, v149, v220
	v_pk_mul_f32 v[146:147], v[78:79], v[78:79]
	v_add_f32_e32 v220, v146, v220
	v_add_f32_e32 v220, v147, v220
	v_pk_mul_f32 v[148:149], v[80:81], v[80:81]
	v_add_f32_e32 v220, v148, v220
	v_add_f32_e32 v220, v149, v220
	ds_bpermute_b32 v146, v160, v220
	s_waitcnt lgkmcnt(0)
	v_add_f32_e32 v220, v220, v146
	s_and_saveexec_b64 s[64:65], s[62:63]
	global_atomic_add_f32 v141, v163, v220, s[18:19] offset:128 sc0
	s_or_b64 exec, exec, s[64:65]
	global_load_dwordx4 v[224:227], v150, s[66:67]
	global_load_dwordx4 v[228:231], v150, s[66:67] offset:32
	global_load_dwordx4 v[232:235], v150, s[66:67] offset:64
	global_load_dwordx4 v[236:239], v150, s[66:67] offset:96
	global_load_dwordx4 v[240:243], v150, s[66:67] offset:128
	global_load_dwordx4 v[244:247], v150, s[66:67] offset:160
	global_load_dwordx4 v[248:251], v150, s[66:67] offset:192
	global_load_dwordx4 v[252:255], v150, s[66:67] offset:224
	s_waitcnt vmcnt(18)
; __device__ void phase_gemm2(const Params& p, char* lds, int bid, int nb, bool fused) {
;     ...
;       for (int tt = 0; tt < 4; ++tt) {
;         const int tok = m0 + wr * 128 + tt * 32 + l31;
;         const float* xr = p.x + (size_t)tok * DM + n0 + wc * 64;
;         float ss = 0.f;
; #pragma unroll
;         for (int ct = 0; ct < 2; ++ct)
; #pragma unroll
;           for (int rq = 0; rq < 4; ++rq) {
;             const f32x4 xv = *(const f32x4*)(xr + ct * 32 + 8 * rq + 4 * h);
; #pragma unroll
;             for (int e = 0; e < 4; ++e) { acc[ct][tt][rq * 4 + e] += xv[e]; ss += acc[ct][tt][rq * 4 + e] * acc[ct][tt][rq * 4 + e]; }
;           }
;         ss += __shfl_xor(ss, 32);
;         olds[tt] = 0.f;
;         if (h == 0) olds[tt] = atomicAdd(p.ssq + tok, ss);
;       }
;       asm volatile("" :: "v"(olds[0]), "v"(olds[1]), "v"(olds[2]), "v"(olds[3]));
;       if (fused) {
;         __syncthreads();
;         if (threadIdx.x == 0) {
;           __hip_atomic_fetch_add(p.pcnt + (m0 >> 8), 1, __ATOMIC_RELAXED, __HIP_MEMORY_SCOPE_AGENT);
;           while (__hip_atomic_load(p.pcnt + (m0 >> 8), __ATOMIC_RELAXED, __HIP_MEMORY_SCOPE_AGENT) < NNT) __builtin_amdgcn_s_sleep(2);
;         }
	v_pk_add_f32 v[50:51], v[50:51], v[196:197]
	v_pk_add_f32 v[52:53], v[52:53], v[198:199]
	v_pk_add_f32 v[54:55], v[54:55], v[200:201]
	v_pk_add_f32 v[56:57], v[56:57], v[202:203]
	v_pk_add_f32 v[58:59], v[58:59], v[204:205]
	v_pk_add_f32 v[60:61], v[60:61], v[206:207]
	v_pk_add_f32 v[62:63], v[62:63], v[208:209]
	v_pk_add_f32 v[64:65], v[64:65], v[210:211]
	v_pk_add_f32 v[34:35], v[34:35], v[212:213]
	v_pk_add_f32 v[36:37], v[36:37], v[214:215]
	v_pk_add_f32 v[38:39], v[38:39], v[216:217]
	v_pk_add_f32 v[40:41], v[40:41], v[218:219]
	v_pk_add_f32 v[42:43], v[42:43], v[130:131]
	v_pk_add_f32 v[44:45], v[44:45], v[132:133]
	v_pk_add_f32 v[46:47], v[46:47], v[134:135]
	v_pk_add_f32 v[48:49], v[48:49], v[136:137]
	v_pk_mul_f32 v[146:147], v[50:51], v[50:51]
	v_add_f32_e32 v221, v146, v147
	v_pk_mul_f32 v[148:149], v[52:53], v[52:53]
	v_add_f32_e32 v221, v148, v221
	v_add_f32_e32 v221, v149, v221
	v_pk_mul_f32 v[146:147], v[54:55], v[54:55]
	v_add_f32_e32 v221, v146, v221
	v_add_f32_e32 v221, v147, v221
	v_pk_mul_f32 v[148:149], v[56:57], v[56:57]
	v_add_f32_e32 v221, v148, v221
	v_add_f32_e32 v221, v149, v221
	v_pk_mul_f32 v[146:147], v[58:59], v[58:59]
	v_add_f32_e32 v221, v146, v221
	v_add_f32_e32 v221, v147, v221
	v_pk_mul_f32 v[148:149], v[60:61], v[60:61]
	v_add_f32_e32 v221, v148, v221
	v_add_f32_e32 v221, v149, v221
	v_pk_mul_f32 v[146:147], v[62:63], v[62:63]
	v_add_f32_e32 v221, v146, v221
	v_add_f32_e32 v221, v147, v221
	v_pk_mul_f32 v[148:149], v[64:65], v[64:65]
	v_add_f32_e32 v221, v148, v221
	v_add_f32_e32 v221, v149, v221
	v_pk_mul_f32 v[146:147], v[34:35], v[34:35]
	v_add_f32_e32 v221, v146, v221
	v_add_f32_e32 v221, v147, v221
	v_pk_mul_f32 v[148:149], v[36:37], v[36:37]
	v_add_f32_e32 v221, v148, v221
	v_add_f32_e32 v221, v149, v221
	v_pk_mul_f32 v[146:147], v[38:39], v[38:39]
	v_add_f32_e32 v221, v146, v221
	v_add_f32_e32 v221, v147, v221
	v_pk_mul_f32 v[148:149], v[40:41], v[40:41]
	v_add_f32_e32 v221, v148, v221
	v_add_f32_e32 v221, v149, v221
	v_pk_mul_f32 v[146:147], v[42:43], v[42:43]
	v_add_f32_e32 v221, v146, v221
	v_add_f32_e32 v221, v147, v221
	v_pk_mul_f32 v[148:149], v[44:45], v[44:45]
	v_add_f32_e32 v221, v148, v221
	v_add_f32_e32 v221, v149, v221
	v_pk_mul_f32 v[146:147], v[46:47], v[46:47]
	v_add_f32_e32 v221, v146, v221
	v_add_f32_e32 v221, v147, v221
	v_pk_mul_f32 v[148:149], v[48:49], v[48:49]
	v_add_f32_e32 v221, v148, v221
	v_add_f32_e32 v221, v149, v221
	ds_bpermute_b32 v146, v160, v221
	s_waitcnt lgkmcnt(0)
	v_add_f32_e32 v221, v221, v146
	s_and_saveexec_b64 s[64:65], s[62:63]
	global_atomic_add_f32 v143, v163, v221, s[18:19] offset:256 sc0
	s_or_b64 exec, exec, s[64:65]
	s_waitcnt vmcnt(10)
	v_pk_add_f32 v[18:19], v[18:19], v[164:165]
	v_pk_add_f32 v[20:21], v[20:21], v[166:167]
	v_pk_add_f32 v[22:23], v[22:23], v[168:169]
	v_pk_add_f32 v[24:25], v[24:25], v[170:171]
	v_pk_add_f32 v[26:27], v[26:27], v[172:173]
	v_pk_add_f32 v[28:29], v[28:29], v[174:175]
	v_pk_add_f32 v[30:31], v[30:31], v[176:177]
	v_pk_add_f32 v[32:33], v[32:33], v[178:179]
	v_pk_add_f32 v[2:3], v[2:3], v[180:181]
	v_pk_add_f32 v[4:5], v[4:5], v[182:183]
	v_pk_add_f32 v[6:7], v[6:7], v[184:185]
	v_pk_add_f32 v[8:9], v[8:9], v[186:187]
	v_pk_add_f32 v[10:11], v[10:11], v[188:189]
	v_pk_add_f32 v[12:13], v[12:13], v[190:191]
	v_pk_add_f32 v[14:15], v[14:15], v[192:193]
	v_pk_add_f32 v[16:17], v[16:17], v[194:195]
	v_pk_mul_f32 v[146:147], v[18:19], v[18:19]
	v_add_f32_e32 v222, v146, v147
	v_pk_mul_f32 v[148:149], v[20:21], v[20:21]
	v_add_f32_e32 v222, v148, v222
	v_add_f32_e32 v222, v149, v222
	v_pk_mul_f32 v[146:147], v[22:23], v[22:23]
	v_add_f32_e32 v222, v146, v222
	v_add_f32_e32 v222, v147, v222
	v_pk_mul_f32 v[148:149], v[24:25], v[24:25]
	v_add_f32_e32 v222, v148, v222
	v_add_f32_e32 v222, v149, v222
	v_pk_mul_f32 v[146:147], v[26:27], v[26:27]
	v_add_f32_e32 v222, v146, v222
	v_add_f32_e32 v222, v147, v222
	v_pk_mul_f32 v[148:149], v[28:29], v[28:29]
	v_add_f32_e32 v222, v148, v222
	v_add_f32_e32 v222, v149, v222
	v_pk_mul_f32 v[146:147], v[30:31], v[30:31]
	v_add_f32_e32 v222, v146, v222
	v_add_f32_e32 v222, v147, v222
	v_pk_mul_f32 v[148:149], v[32:33], v[32:33]
	v_add_f32_e32 v222, v148, v222
	v_add_f32_e32 v222, v149, v222
	v_pk_mul_f32 v[146:147], v[2:3], v[2:3]
	v_add_f32_e32 v222, v146, v222
	v_add_f32_e32 v222, v147, v222
	v_pk_mul_f32 v[148:149], v[4:5], v[4:5]
	v_add_f32_e32 v222, v148, v222
	v_add_f32_e32 v222, v149, v222
	v_pk_mul_f32 v[146:147], v[6:7], v[6:7]
	v_add_f32_e32 v222, v146, v222
	v_add_f32_e32 v222, v147, v222
	v_pk_mul_f32 v[148:149], v[8:9], v[8:9]
	v_add_f32_e32 v222, v148, v222
	v_add_f32_e32 v222, v149, v222
	v_pk_mul_f32 v[146:147], v[10:11], v[10:11]
	v_add_f32_e32 v222, v146, v222
	v_add_f32_e32 v222, v147, v222
	v_pk_mul_f32 v[148:149], v[12:13], v[12:13]
	v_add_f32_e32 v222, v148, v222
	v_add_f32_e32 v222, v149, v222
	v_pk_mul_f32 v[146:147], v[14:15], v[14:15]
	v_add_f32_e32 v222, v146, v222
	v_add_f32_e32 v222, v147, v222
	v_pk_mul_f32 v[148:149], v[16:17], v[16:17]
	v_add_f32_e32 v222, v148, v222
	v_add_f32_e32 v222, v149, v222
	ds_bpermute_b32 v146, v160, v222
	s_waitcnt lgkmcnt(0)
	v_add_f32_e32 v222, v222, v146
	s_and_saveexec_b64 s[64:65], s[62:63]
	global_atomic_add_f32 v145, v163, v222, s[18:19] offset:384 sc0
	s_or_b64 exec, exec, s[64:65]
	s_waitcnt vmcnt(0)
	s_barrier
	s_and_saveexec_b64 s[64:65], s[48:49]
	s_cbranch_execz .Lp5_pollend
	s_ashr_i32 s38, s38, 8
	s_mov_b64 s[40:41], exec
	s_ashr_i32 s39, s38, 31
	s_lshl_b64 s[38:39], s[38:39], 2
	v_mbcnt_lo_u32_b32 v146, s40, 0
	s_add_u32 s38, s20, s38
	v_mbcnt_hi_u32_b32 v146, s41, v146
	s_addc_u32 s39, s21, s39
	v_cmp_eq_u32_e32 vcc, 0, v146
	s_and_saveexec_b64 s[42:43], vcc
	s_cbranch_execz .Lp5_noinc
	s_bcnt1_i32_b64 s40, s[40:41]
	v_mov_b32_e32 v146, s40
	global_atomic_add v151, v146, s[38:39]
